# u5 variant: scan scheduling regions extended back to the chunk barrier with top-block temporaries renamed so the first LDS read burst overlaps address math and prefetch issue
# speedup vs baseline: 1.0025x; 1.0025x over previous
; DI float row16_sum(float v) { v += dppf(v, 0); v += dppf(v, 1); v += dppf(v, 2); v += dppf(v, 3); return v; }
; DI void mamba_scan(CP p, const Ptrs& w, int l, int item, float* sm) {
;     ...
;   auto load = [&](int c, MPre& P) {
; #pragma unroll
;     for (int i = 0; i < 2; ++i) {
;       int idx = tid + 256 * i, j = idx >> 5, q = idx & 31;
;       int ii = pos2i(c * 16 + j, dir);
;       P.pbq[i] = *(const uint4*)(mbc + ((size_t)b * TPB + ii) * 512 + (q < 16 ? 0 : 256) + gp * 128 + (q & 15) * 8);
;     }
;     {
;       int pos = c * 16 + xj, ii = pos2i(pos, dir);
;       size_t tok = (size_t)b * TPB + ii;
;       const bf16_t* prw = w.pC + tok * SPC;
;       bool hp = (ii != 0) && (ii != CTXL), hn = (ii != CTXL - 1) && (ii != TPB - 1);
;       P.px[0] = prw[chX + (hp ? -SPC : 0)]; P.px[1] = prw[chX]; P.px[2] = prw[chX + (hn ? SPC : 0)];
;       P.pxm[0] = hp ? 1.f : 0.f; P.pxm[1] = hn ? 1.f : 0.f;
;       float2 dd = *(const float2*)(w.mdt + (tok * 16 + dir * 8 + hd) * 2);
;       P.pdt[0] = dd.x; P.pdt[1] = dd.y; P.pdt[2] = w.mcb[tok * 2 + gp];
;     }
;   };
;     ...
;   auto flush = [&](int c) {
;     {
;       int j = tid >> 4, rr = tid & 15;
;       int ii = pos2i(c * 16 + j, dir);
;       yout[((size_t)b * TPB + ii) * 512 + hd * 64 + pq * 16 + rr] = f2bf(sY[(c & 1) * 256 + j * 16 + rr]);
;     }
;   };
;   __syncthreads();
;   load(0, PA);
;   stage(PA, sm);
;   load(1, PB);
;   __syncthreads();
;   const int NCH = TPB / 16;
;   auto run_chunk = [&](int c, const float* bf, float* sy) {
;     flush(max(c - 1, 0));
;     MStep cur = lds_step(bf, 0);
; #pragma unroll
;     for (int j = 0; j < 16; ++j) {
;       MStep nxt = cur;
;       if (j + 1 < 16) nxt = lds_step(bf, j + 1);
;       f2v ya = M0 * cur.C0.xy + M1 * cur.C0.zw, yb = M2 * cur.C1.xy + M3 * cur.C1.zw;
;       ya += yb;
;       float yp = row16_sum(ya.x + ya.y);
;       float y = cur.sc.x * yp + cur.xq * cur.sc.y + cur.ds;
;       const float dA = cur.sc.x, xq = cur.xq;
;       M0 = M0 * dA + xq * cur.B0.xy; M1 = M1 * dA + xq * cur.B0.zw;
;       M2 = M2 * dA + xq * cur.B1.xy; M3 = M3 * dA + xq * cur.B1.zw;
;       sy[(ng == 0 ? j * 16 : 0) + ysel] = y;
;       cur = nxt;
;     }
.LBB0_544:
	s_waitcnt lgkmcnt(0)
	s_min_u32 s4, s52, 1
	s_lshl_b32 s5, s4, 8
	s_lshl_b32 s54, s4, 4
	s_add_i32 s4, s7, 4
	s_min_u32 s4, s4, 0x20f
	s_lshl_b32 s42, s4, 4
	v_add_u32_e32 v8, s42, v55
	s_sub_i32 s53, s57, s5
	v_mov_b64_e32 v[104:105], s[48:49]
	v_cmp_lt_i32_e64 s[4:5], s37, v8
	v_mov_b32_e32 v107, v157
	ds_read_b128 v[38:41], v59
	v_cndmask_b32_e64 v12, v231, v232, s[4:5]
	ds_read_b128 v[42:45], v59 offset:16
	v_sub_u32_e32 v12, v12, v8
	ds_read_b128 v[88:91], v59 offset:8192
	v_cndmask_b32_e64 v12, v12, v8, s[40:41]
	v_add_u32_e32 v8, s42, v56
	ds_read_b128 v[92:95], v59 offset:8208
	v_ashrrev_i32_e32 v13, 31, v12
	v_cmp_lt_i32_e64 s[4:5], s37, v8
	v_add_u32_e32 v112, 0x4000, v60
	v_lshl_add_u64 v[12:13], v[12:13], 0, s[90:91]
	v_cndmask_b32_e64 v14, v231, v232, s[4:5]
	v_add_u32_e32 v113, 0x4400, v60
	v_lshlrev_b64 v[12:13], 10, v[12:13]
	v_sub_u32_e32 v14, v14, v8
	ds_read2_b32 v[46:47], v112 offset1:16
	v_lshl_add_u64 v[12:13], v[30:31], 0, v[12:13]
	v_cndmask_b32_e64 v14, v14, v8, s[40:41]
	v_add_u32_e32 v8, s42, v54
	global_load_dwordx4 v[18:21], v[12:13], off
	v_ashrrev_i32_e32 v15, 31, v14
	v_cmp_lt_i32_e64 s[4:5], s37, v8
	ds_read2_b32 v[116:117], v113 offset1:16
	v_lshl_add_u64 v[14:15], v[14:15], 0, s[90:91]
	v_cndmask_b32_e64 v16, v231, v232, s[4:5]
	v_lshlrev_b64 v[14:15], 10, v[14:15]
	v_sub_u32_e32 v16, v16, v8
	v_lshl_add_u64 v[14:15], v[30:31], 0, v[14:15]
	v_cndmask_b32_e64 v16, v16, v8, s[40:41]
	global_load_dwordx4 v[12:15], v[14:15], off
	v_and_b32_e32 v8, 0xfffffeff, v16
	v_ashrrev_i32_e32 v17, 31, v16
	v_and_b32_e32 v106, 0xffffdfff, v16
	v_cmp_eq_u32_e64 s[42:43], 0, v8
	v_lshl_add_u64 v[36:37], v[16:17], 0, s[90:91]
	v_cmp_eq_u32_e64 s[44:45], s37, v106
	v_cndmask_b32_e64 v8, v233, 0, s[42:43]
	v_mad_u64_u32 v[104:105], s[4:5], v36, s92, v[104:105]
	v_cndmask_b32_e64 v106, v234, 0, s[44:45]
	v_add_u32_e32 v16, v8, v48
	v_mad_i32_i24 v105, v37, s92, v105
	v_lshlrev_b64 v[108:109], 7, v[36:37]
	v_ashrrev_i32_e32 v17, 31, v16
	v_lshl_add_u64 v[110:111], v[36:37], 3, s[50:51]
	v_lshl_or_b32 v108, s6, 3, v108
	v_lshl_add_u64 v[16:17], v[16:17], 1, v[104:105]
	v_lshl_add_u64 v[104:105], v[104:105], 0, v[156:157]
	v_lshl_add_u64 v[108:109], s[46:47], 0, v[108:109]
	global_load_ushort v84, v[16:17], off
	global_load_ushort v85, v[104:105], off
	v_lshl_add_u64 v[106:107], v[104:105], 0, v[106:107]
	s_and_b32 s4, s53, 0x100
	v_lshl_add_u32 v16, s4, 2, v57
	global_load_ushort v83, v[106:107], off
	global_load_dwordx2 v[36:37], v[108:109], off
	global_load_dword v17, v[110:111], off
	ds_read_b32 v16, v16 offset:37376
	v_subrev_u32_e32 v8, s54, v82
	s_movk_i32 s101, 0x4800
	v_add_u32_e64 v114, s101, 0
	v_cmp_lt_i32_e64 s[4:5], s37, v8
	s_waitcnt lgkmcnt(1)
	v_pk_mul_f32 v[90:91], v[28:29], v[90:91]
	ds_read2_b64 v[96:99], v114 offset1:2
	v_cndmask_b32_e64 v104, v231, v232, s[4:5]
	ds_read_b128 v[100:103], v59 offset:512
	v_add3_u32 v104, v104, v81, s54
	v_pk_fma_f32 v[88:89], v[26:27], v[88:89], v[90:91]
	v_pk_mul_f32 v[90:91], v[24:25], v[94:95]
	v_cndmask_b32_e64 v104, v104, v8, s[40:41]
	v_pk_fma_f32 v[90:91], v[22:23], v[92:93], v[90:91]
	v_ashrrev_i32_e32 v105, 31, v104
	v_pk_add_f32 v[88:89], v[88:89], v[90:91]
	v_lshl_add_u64 v[104:105], v[104:105], 0, s[90:91]
	v_lshlrev_b64 v[104:105], 10, v[104:105]
	v_lshl_add_u64 v[104:105], v[34:35], 0, v[104:105]
	s_waitcnt lgkmcnt(2)
	v_cvt_pk_bf16_f32 v8, v16, s0
	global_store_short v[104:105], v8, off
	ds_read_b128 v[104:107], v59 offset:528
	ds_read_b128 v[108:111], v59 offset:8704
	ds_read_b128 v[112:115], v59 offset:8720
	v_add_f32_e32 v8, v88, v89
	s_waitcnt lgkmcnt(4)
	v_pk_mul_f32 v[22:23], v[22:23], v[96:97] op_sel_hi:[1,0]
	v_pk_fma_f32 v[92:93], v[42:43], v[46:47], v[22:23] op_sel_hi:[1,0,1]
	v_add_f32_dpp v8, v8, v8 quad_perm:[1,0,3,2] row_mask:0xf bank_mask:0xf bound_ctrl:1
	v_pk_mul_f32 v[26:27], v[26:27], v[96:97] op_sel_hi:[1,0]
	v_pk_fma_f32 v[88:89], v[38:39], v[46:47], v[26:27] op_sel_hi:[1,0,1]
	v_add_f32_dpp v8, v8, v8 quad_perm:[2,3,0,1] row_mask:0xf bank_mask:0xf bound_ctrl:1
	v_pk_mul_f32 v[22:23], v[24:25], v[96:97] op_sel_hi:[1,0]
	v_pk_mul_f32 v[26:27], v[28:29], v[96:97] op_sel_hi:[1,0]
	v_add_f32_dpp v8, v8, v8 row_half_mirror row_mask:0xf bank_mask:0xf bound_ctrl:1
	v_pk_fma_f32 v[94:95], v[44:45], v[46:47], v[22:23] op_sel_hi:[1,0,1]
	v_pk_fma_f32 v[90:91], v[40:41], v[46:47], v[26:27] op_sel_hi:[1,0,1]
	v_add_f32_dpp v8, v8, v8 row_mirror row_mask:0xf bank_mask:0xf bound_ctrl:1
	v_mul_f32_e32 v8, v96, v8
	v_fmac_f32_e32 v8, v46, v97
	v_add_f32_e32 v8, v116, v8
	ds_write_b32 v61, v8 offset:37376
	ds_read_b128 v[22:25], v59 offset:1024
	ds_read_b128 v[26:29], v59 offset:1040
	ds_read_b128 v[38:41], v59 offset:9216
	ds_read_b128 v[42:45], v59 offset:9232
	ds_read_b32 v8, v60 offset:16512
	ds_read_b32 v116, v60 offset:17536
	ds_read_b64 v[118:119], v157 offset:18464
	s_waitcnt lgkmcnt(9)
	v_pk_mul_f32 v[96:97], v[90:91], v[110:111]
	v_pk_fma_f32 v[96:97], v[88:89], v[108:109], v[96:97]
	s_waitcnt lgkmcnt(8)
	v_pk_mul_f32 v[108:109], v[94:95], v[114:115]
	v_pk_mul_f32 v[88:89], v[88:89], v[98:99] op_sel_hi:[1,0]
	v_pk_fma_f32 v[108:109], v[92:93], v[112:113], v[108:109]
	v_pk_add_f32 v[96:97], v[96:97], v[108:109]
	v_add_f32_e32 v16, v96, v97
	s_nop 1
	v_add_f32_dpp v16, v16, v16 quad_perm:[1,0,3,2] row_mask:0xf bank_mask:0xf bound_ctrl:1
	s_nop 1
	v_add_f32_dpp v16, v16, v16 quad_perm:[2,3,0,1] row_mask:0xf bank_mask:0xf bound_ctrl:1
	s_nop 1
	v_add_f32_dpp v16, v16, v16 row_half_mirror row_mask:0xf bank_mask:0xf bound_ctrl:1
	s_nop 1
	v_add_f32_dpp v16, v16, v16 row_mirror row_mask:0xf bank_mask:0xf bound_ctrl:1
	v_mul_f32_e32 v16, v98, v16
	v_fmac_f32_e32 v16, v47, v99
	v_add_f32_e32 v96, v117, v16
	v_mov_b32_e32 v16, v47
	ds_write_b32 v62, v96 offset:37376
	v_pk_fma_f32 v[46:47], v[100:101], v[16:17], v[88:89] op_sel_hi:[1,0,1]
	v_pk_mul_f32 v[88:89], v[90:91], v[98:99] op_sel_hi:[1,0]
	v_pk_fma_f32 v[108:109], v[102:103], v[16:17], v[88:89] op_sel_hi:[1,0,1]
	v_pk_mul_f32 v[88:89], v[92:93], v[98:99] op_sel_hi:[1,0]
	s_waitcnt lgkmcnt(5)
; DI float row16_sum(float v) { v += dppf(v, 0); v += dppf(v, 1); v += dppf(v, 2); v += dppf(v, 3); return v; }
; DI void mamba_scan(CP p, const Ptrs& w, int l, int item, float* sm) {
;     ...
;   auto run_chunk = [&](int c, const float* bf, float* sy) {
;     flush(max(c - 1, 0));
;     MStep cur = lds_step(bf, 0);
; #pragma unroll
;     for (int j = 0; j < 16; ++j) {
;       MStep nxt = cur;
;       if (j + 1 < 16) nxt = lds_step(bf, j + 1);
;       f2v ya = M0 * cur.C0.xy + M1 * cur.C0.zw, yb = M2 * cur.C1.xy + M3 * cur.C1.zw;
;       ya += yb;
;       float yp = row16_sum(ya.x + ya.y);
;       float y = cur.sc.x * yp + cur.xq * cur.sc.y + cur.ds;
;       const float dA = cur.sc.x, xq = cur.xq;
;       M0 = M0 * dA + xq * cur.B0.xy; M1 = M1 * dA + xq * cur.B0.zw;
;       M2 = M2 * dA + xq * cur.B1.xy; M3 = M3 * dA + xq * cur.B1.zw;
;       sy[(ng == 0 ? j * 16 : 0) + ysel] = y;
;       cur = nxt;
;     }
	v_pk_mul_f32 v[40:41], v[108:109], v[40:41]
	v_pk_fma_f32 v[104:105], v[104:105], v[16:17], v[88:89] op_sel_hi:[1,0,1]
	v_pk_mul_f32 v[88:89], v[94:95], v[98:99] op_sel_hi:[1,0]
	v_pk_fma_f32 v[38:39], v[46:47], v[38:39], v[40:41]
	v_pk_fma_f32 v[106:107], v[106:107], v[16:17], v[88:89] op_sel_hi:[1,0,1]
	ds_read_b128 v[88:91], v59 offset:1536
	s_waitcnt lgkmcnt(3)
	v_pk_mul_f32 v[40:41], v[106:107], v[44:45]
	ds_read_b128 v[92:95], v59 offset:1552
	v_pk_fma_f32 v[40:41], v[104:105], v[42:43], v[40:41]
	ds_read_b128 v[96:99], v59 offset:9728
	v_pk_add_f32 v[38:39], v[38:39], v[40:41]
	ds_read_b128 v[100:103], v59 offset:9744
	v_add_f32_e32 v38, v38, v39
	ds_read_b32 v16, v60 offset:16576
	ds_read_b32 v114, v60 offset:17600
	v_add_f32_dpp v38, v38, v38 quad_perm:[1,0,3,2] row_mask:0xf bank_mask:0xf bound_ctrl:1
	ds_read_b64 v[110:111], v157 offset:18480
	s_nop 0
	v_add_f32_dpp v38, v38, v38 quad_perm:[2,3,0,1] row_mask:0xf bank_mask:0xf bound_ctrl:1
	s_nop 1
	v_add_f32_dpp v38, v38, v38 row_half_mirror row_mask:0xf bank_mask:0xf bound_ctrl:1
	s_nop 1
	v_add_f32_dpp v38, v38, v38 row_mirror row_mask:0xf bank_mask:0xf bound_ctrl:1
	s_waitcnt lgkmcnt(8)
	v_mul_f32_e32 v38, v118, v38
	v_fmac_f32_e32 v38, v8, v119
	v_add_f32_e32 v40, v116, v38
	v_pk_mul_f32 v[38:39], v[46:47], v[118:119] op_sel_hi:[1,0]
	ds_write_b32 v63, v40 offset:37376
	v_pk_fma_f32 v[46:47], v[22:23], v[8:9], v[38:39] op_sel_hi:[1,0,1]
	v_pk_mul_f32 v[22:23], v[108:109], v[118:119] op_sel_hi:[1,0]
	v_pk_fma_f32 v[108:109], v[24:25], v[8:9], v[22:23] op_sel_hi:[1,0,1]
	v_pk_mul_f32 v[22:23], v[104:105], v[118:119] op_sel_hi:[1,0]
	v_pk_fma_f32 v[104:105], v[26:27], v[8:9], v[22:23] op_sel_hi:[1,0,1]
	v_pk_mul_f32 v[22:23], v[106:107], v[118:119] op_sel_hi:[1,0]
	v_pk_fma_f32 v[106:107], v[28:29], v[8:9], v[22:23] op_sel_hi:[1,0,1]
	ds_read_b128 v[22:25], v59 offset:2048
	ds_read_b128 v[26:29], v59 offset:2064
	ds_read_b128 v[38:41], v59 offset:10240
	ds_read_b128 v[42:45], v59 offset:10256
	ds_read_b32 v8, v60 offset:16640
	ds_read_b32 v115, v60 offset:17664
	s_waitcnt lgkmcnt(14)
	ds_read_b64 v[112:113], v157 offset:18496
	s_waitcnt lgkmcnt(11)
	v_pk_mul_f32 v[98:99], v[108:109], v[98:99]
	v_pk_fma_f32 v[96:97], v[46:47], v[96:97], v[98:99]
	v_pk_mul_f32 v[98:99], v[106:107], v[102:103]
	v_pk_fma_f32 v[98:99], v[104:105], v[100:101], v[98:99]
	v_pk_add_f32 v[96:97], v[96:97], v[98:99]
	s_waitcnt lgkmcnt(8)
	v_pk_mul_f32 v[46:47], v[46:47], v[110:111] op_sel_hi:[1,0]
	v_add_f32_e32 v96, v96, v97
	v_pk_fma_f32 v[46:47], v[88:89], v[16:17], v[46:47] op_sel_hi:[1,0,1]
	v_pk_mul_f32 v[88:89], v[108:109], v[110:111] op_sel_hi:[1,0]
	v_add_f32_dpp v96, v96, v96 quad_perm:[1,0,3,2] row_mask:0xf bank_mask:0xf bound_ctrl:1
	v_pk_fma_f32 v[108:109], v[90:91], v[16:17], v[88:89] op_sel_hi:[1,0,1]
	v_pk_mul_f32 v[88:89], v[104:105], v[110:111] op_sel_hi:[1,0]
	v_add_f32_dpp v96, v96, v96 quad_perm:[2,3,0,1] row_mask:0xf bank_mask:0xf bound_ctrl:1
	v_pk_fma_f32 v[104:105], v[92:93], v[16:17], v[88:89] op_sel_hi:[1,0,1]
	v_pk_mul_f32 v[88:89], v[106:107], v[110:111] op_sel_hi:[1,0]
	v_add_f32_dpp v96, v96, v96 row_half_mirror row_mask:0xf bank_mask:0xf bound_ctrl:1
	v_pk_fma_f32 v[106:107], v[94:95], v[16:17], v[88:89] op_sel_hi:[1,0,1]
	s_waitcnt lgkmcnt(4)
	v_pk_mul_f32 v[40:41], v[108:109], v[40:41]
	v_add_f32_dpp v96, v96, v96 row_mirror row_mask:0xf bank_mask:0xf bound_ctrl:1
	v_pk_fma_f32 v[38:39], v[46:47], v[38:39], v[40:41]
	s_waitcnt lgkmcnt(3)
	v_pk_mul_f32 v[40:41], v[106:107], v[44:45]
	v_mul_f32_e32 v96, v110, v96
	v_pk_fma_f32 v[40:41], v[104:105], v[42:43], v[40:41]
	v_fmac_f32_e32 v96, v16, v111
	v_pk_add_f32 v[38:39], v[38:39], v[40:41]
	v_add_f32_e32 v96, v114, v96
	v_add_f32_e32 v38, v38, v39
	ds_write_b32 v65, v96 offset:37376
	ds_read_b128 v[88:91], v59 offset:2560
	v_add_f32_dpp v38, v38, v38 quad_perm:[1,0,3,2] row_mask:0xf bank_mask:0xf bound_ctrl:1
	ds_read_b128 v[92:95], v59 offset:2576
	ds_read_b128 v[96:99], v59 offset:10752
	v_add_f32_dpp v38, v38, v38 quad_perm:[2,3,0,1] row_mask:0xf bank_mask:0xf bound_ctrl:1
	ds_read_b128 v[100:103], v59 offset:10768
	ds_read_b32 v16, v60 offset:16704
	v_add_f32_dpp v38, v38, v38 row_half_mirror row_mask:0xf bank_mask:0xf bound_ctrl:1
	ds_read_b32 v114, v60 offset:17728
	ds_read_b64 v[110:111], v157 offset:18512
	v_add_f32_dpp v38, v38, v38 row_mirror row_mask:0xf bank_mask:0xf bound_ctrl:1
	s_waitcnt lgkmcnt(8)
	v_mul_f32_e32 v38, v112, v38
	v_fmac_f32_e32 v38, v8, v113
	v_add_f32_e32 v40, v115, v38
	v_pk_mul_f32 v[38:39], v[46:47], v[112:113] op_sel_hi:[1,0]
	ds_write_b32 v66, v40 offset:37376
	v_pk_fma_f32 v[46:47], v[22:23], v[8:9], v[38:39] op_sel_hi:[1,0,1]
	v_pk_mul_f32 v[22:23], v[108:109], v[112:113] op_sel_hi:[1,0]
	v_pk_fma_f32 v[108:109], v[24:25], v[8:9], v[22:23] op_sel_hi:[1,0,1]
	v_pk_mul_f32 v[22:23], v[104:105], v[112:113] op_sel_hi:[1,0]
	v_pk_fma_f32 v[104:105], v[26:27], v[8:9], v[22:23] op_sel_hi:[1,0,1]
	v_pk_mul_f32 v[22:23], v[106:107], v[112:113] op_sel_hi:[1,0]
	v_pk_fma_f32 v[106:107], v[28:29], v[8:9], v[22:23] op_sel_hi:[1,0,1]
	ds_read_b128 v[22:25], v59 offset:3072
	ds_read_b128 v[26:29], v59 offset:3088
	ds_read_b128 v[38:41], v59 offset:11264
	ds_read_b128 v[42:45], v59 offset:11280
	ds_read_b32 v8, v60 offset:16768
	ds_read_b32 v115, v60 offset:17792
	s_waitcnt lgkmcnt(14)
	ds_read_b64 v[112:113], v157 offset:18528
	s_waitcnt lgkmcnt(12)
	v_pk_mul_f32 v[98:99], v[108:109], v[98:99]
	v_pk_fma_f32 v[96:97], v[46:47], v[96:97], v[98:99]
	s_waitcnt lgkmcnt(11)
	v_pk_mul_f32 v[98:99], v[106:107], v[102:103]
	v_pk_fma_f32 v[98:99], v[104:105], v[100:101], v[98:99]
	v_pk_add_f32 v[96:97], v[96:97], v[98:99]
	s_waitcnt lgkmcnt(8)
; DI float row16_sum(float v) { v += dppf(v, 0); v += dppf(v, 1); v += dppf(v, 2); v += dppf(v, 3); return v; }
; DI void mamba_scan(CP p, const Ptrs& w, int l, int item, float* sm) {
;     ...
;   auto run_chunk = [&](int c, const float* bf, float* sy) {
;     flush(max(c - 1, 0));
;     MStep cur = lds_step(bf, 0);
; #pragma unroll
;     for (int j = 0; j < 16; ++j) {
;       MStep nxt = cur;
;       if (j + 1 < 16) nxt = lds_step(bf, j + 1);
;       f2v ya = M0 * cur.C0.xy + M1 * cur.C0.zw, yb = M2 * cur.C1.xy + M3 * cur.C1.zw;
;       ya += yb;
;       float yp = row16_sum(ya.x + ya.y);
;       float y = cur.sc.x * yp + cur.xq * cur.sc.y + cur.ds;
;       const float dA = cur.sc.x, xq = cur.xq;
;       M0 = M0 * dA + xq * cur.B0.xy; M1 = M1 * dA + xq * cur.B0.zw;
;       M2 = M2 * dA + xq * cur.B1.xy; M3 = M3 * dA + xq * cur.B1.zw;
;       sy[(ng == 0 ? j * 16 : 0) + ysel] = y;
;       cur = nxt;
;     }
	v_pk_mul_f32 v[46:47], v[46:47], v[110:111] op_sel_hi:[1,0]
	v_add_f32_e32 v96, v96, v97
	v_pk_fma_f32 v[46:47], v[88:89], v[16:17], v[46:47] op_sel_hi:[1,0,1]
	v_pk_mul_f32 v[88:89], v[108:109], v[110:111] op_sel_hi:[1,0]
	v_add_f32_dpp v96, v96, v96 quad_perm:[1,0,3,2] row_mask:0xf bank_mask:0xf bound_ctrl:1
	v_pk_fma_f32 v[108:109], v[90:91], v[16:17], v[88:89] op_sel_hi:[1,0,1]
	v_pk_mul_f32 v[88:89], v[104:105], v[110:111] op_sel_hi:[1,0]
	v_add_f32_dpp v96, v96, v96 quad_perm:[2,3,0,1] row_mask:0xf bank_mask:0xf bound_ctrl:1
	v_pk_fma_f32 v[104:105], v[92:93], v[16:17], v[88:89] op_sel_hi:[1,0,1]
	v_pk_mul_f32 v[88:89], v[106:107], v[110:111] op_sel_hi:[1,0]
	v_add_f32_dpp v96, v96, v96 row_half_mirror row_mask:0xf bank_mask:0xf bound_ctrl:1
	v_pk_fma_f32 v[106:107], v[94:95], v[16:17], v[88:89] op_sel_hi:[1,0,1]
	s_waitcnt lgkmcnt(4)
	v_pk_mul_f32 v[40:41], v[108:109], v[40:41]
	v_add_f32_dpp v96, v96, v96 row_mirror row_mask:0xf bank_mask:0xf bound_ctrl:1
	v_pk_fma_f32 v[38:39], v[46:47], v[38:39], v[40:41]
	s_waitcnt lgkmcnt(3)
	v_pk_mul_f32 v[40:41], v[106:107], v[44:45]
	v_mul_f32_e32 v96, v110, v96
	v_pk_fma_f32 v[40:41], v[104:105], v[42:43], v[40:41]
	v_fmac_f32_e32 v96, v16, v111
	v_pk_add_f32 v[38:39], v[38:39], v[40:41]
	v_add_f32_e32 v96, v114, v96
	v_add_f32_e32 v38, v38, v39
	ds_write_b32 v67, v96 offset:37376
	ds_read_b128 v[88:91], v59 offset:3584
	v_add_f32_dpp v38, v38, v38 quad_perm:[1,0,3,2] row_mask:0xf bank_mask:0xf bound_ctrl:1
	ds_read_b128 v[92:95], v59 offset:3600
	ds_read_b128 v[96:99], v59 offset:11776
	v_add_f32_dpp v38, v38, v38 quad_perm:[2,3,0,1] row_mask:0xf bank_mask:0xf bound_ctrl:1
	ds_read_b128 v[100:103], v59 offset:11792
	ds_read_b32 v16, v60 offset:16832
	v_add_f32_dpp v38, v38, v38 row_half_mirror row_mask:0xf bank_mask:0xf bound_ctrl:1
	ds_read_b32 v114, v60 offset:17856
	ds_read_b64 v[110:111], v157 offset:18544
	v_add_f32_dpp v38, v38, v38 row_mirror row_mask:0xf bank_mask:0xf bound_ctrl:1
	s_waitcnt lgkmcnt(8)
	v_mul_f32_e32 v38, v112, v38
	v_fmac_f32_e32 v38, v8, v113
	v_add_f32_e32 v40, v115, v38
	v_pk_mul_f32 v[38:39], v[46:47], v[112:113] op_sel_hi:[1,0]
	ds_write_b32 v68, v40 offset:37376
	v_pk_fma_f32 v[46:47], v[22:23], v[8:9], v[38:39] op_sel_hi:[1,0,1]
	v_pk_mul_f32 v[22:23], v[108:109], v[112:113] op_sel_hi:[1,0]
	v_pk_fma_f32 v[108:109], v[24:25], v[8:9], v[22:23] op_sel_hi:[1,0,1]
	v_pk_mul_f32 v[22:23], v[104:105], v[112:113] op_sel_hi:[1,0]
	v_pk_fma_f32 v[104:105], v[26:27], v[8:9], v[22:23] op_sel_hi:[1,0,1]
	v_pk_mul_f32 v[22:23], v[106:107], v[112:113] op_sel_hi:[1,0]
	v_pk_fma_f32 v[106:107], v[28:29], v[8:9], v[22:23] op_sel_hi:[1,0,1]
	ds_read_b128 v[22:25], v59 offset:4096
	ds_read_b128 v[26:29], v59 offset:4112
	ds_read_b128 v[38:41], v59 offset:12288
	ds_read_b128 v[42:45], v59 offset:12304
	ds_read_b32 v8, v60 offset:16896
	ds_read_b32 v115, v60 offset:17920
	s_waitcnt lgkmcnt(14)
	ds_read_b64 v[112:113], v157 offset:18560
	s_waitcnt lgkmcnt(12)
	v_pk_mul_f32 v[98:99], v[108:109], v[98:99]
	v_pk_fma_f32 v[96:97], v[46:47], v[96:97], v[98:99]
	s_waitcnt lgkmcnt(11)
	v_pk_mul_f32 v[98:99], v[106:107], v[102:103]
	v_pk_fma_f32 v[98:99], v[104:105], v[100:101], v[98:99]
	v_pk_add_f32 v[96:97], v[96:97], v[98:99]
	s_waitcnt lgkmcnt(8)
	v_pk_mul_f32 v[46:47], v[46:47], v[110:111] op_sel_hi:[1,0]
	v_add_f32_e32 v96, v96, v97
	v_pk_fma_f32 v[46:47], v[88:89], v[16:17], v[46:47] op_sel_hi:[1,0,1]
	v_pk_mul_f32 v[88:89], v[108:109], v[110:111] op_sel_hi:[1,0]
	v_add_f32_dpp v96, v96, v96 quad_perm:[1,0,3,2] row_mask:0xf bank_mask:0xf bound_ctrl:1
	v_pk_fma_f32 v[108:109], v[90:91], v[16:17], v[88:89] op_sel_hi:[1,0,1]
	v_pk_mul_f32 v[88:89], v[104:105], v[110:111] op_sel_hi:[1,0]
	v_add_f32_dpp v96, v96, v96 quad_perm:[2,3,0,1] row_mask:0xf bank_mask:0xf bound_ctrl:1
	v_pk_fma_f32 v[104:105], v[92:93], v[16:17], v[88:89] op_sel_hi:[1,0,1]
	v_pk_mul_f32 v[88:89], v[106:107], v[110:111] op_sel_hi:[1,0]
	v_add_f32_dpp v96, v96, v96 row_half_mirror row_mask:0xf bank_mask:0xf bound_ctrl:1
	v_pk_fma_f32 v[106:107], v[94:95], v[16:17], v[88:89] op_sel_hi:[1,0,1]
	s_waitcnt lgkmcnt(4)
	v_pk_mul_f32 v[40:41], v[108:109], v[40:41]
	v_add_f32_dpp v96, v96, v96 row_mirror row_mask:0xf bank_mask:0xf bound_ctrl:1
	v_pk_fma_f32 v[38:39], v[46:47], v[38:39], v[40:41]
	s_waitcnt lgkmcnt(3)
	v_pk_mul_f32 v[40:41], v[106:107], v[44:45]
	v_mul_f32_e32 v96, v110, v96
	v_pk_fma_f32 v[40:41], v[104:105], v[42:43], v[40:41]
	v_fmac_f32_e32 v96, v16, v111
	v_pk_add_f32 v[38:39], v[38:39], v[40:41]
	v_add_f32_e32 v96, v114, v96
	v_add_f32_e32 v38, v38, v39
	ds_write_b32 v70, v96 offset:37376
	ds_read_b128 v[88:91], v59 offset:4608
	v_add_f32_dpp v38, v38, v38 quad_perm:[1,0,3,2] row_mask:0xf bank_mask:0xf bound_ctrl:1
	ds_read_b128 v[92:95], v59 offset:4624
	ds_read_b128 v[96:99], v59 offset:12800
	v_add_f32_dpp v38, v38, v38 quad_perm:[2,3,0,1] row_mask:0xf bank_mask:0xf bound_ctrl:1
	ds_read_b128 v[100:103], v59 offset:12816
	ds_read_b32 v16, v60 offset:16960
	v_add_f32_dpp v38, v38, v38 row_half_mirror row_mask:0xf bank_mask:0xf bound_ctrl:1
	ds_read_b32 v114, v60 offset:17984
	ds_read_b64 v[110:111], v157 offset:18576
	v_add_f32_dpp v38, v38, v38 row_mirror row_mask:0xf bank_mask:0xf bound_ctrl:1
	s_waitcnt lgkmcnt(8)
; DI float row16_sum(float v) { v += dppf(v, 0); v += dppf(v, 1); v += dppf(v, 2); v += dppf(v, 3); return v; }
; DI void mamba_scan(CP p, const Ptrs& w, int l, int item, float* sm) {
;     ...
;   auto run_chunk = [&](int c, const float* bf, float* sy) {
;     flush(max(c - 1, 0));
;     MStep cur = lds_step(bf, 0);
; #pragma unroll
;     for (int j = 0; j < 16; ++j) {
;       MStep nxt = cur;
;       if (j + 1 < 16) nxt = lds_step(bf, j + 1);
;       f2v ya = M0 * cur.C0.xy + M1 * cur.C0.zw, yb = M2 * cur.C1.xy + M3 * cur.C1.zw;
;       ya += yb;
;       float yp = row16_sum(ya.x + ya.y);
;       float y = cur.sc.x * yp + cur.xq * cur.sc.y + cur.ds;
;       const float dA = cur.sc.x, xq = cur.xq;
;       M0 = M0 * dA + xq * cur.B0.xy; M1 = M1 * dA + xq * cur.B0.zw;
;       M2 = M2 * dA + xq * cur.B1.xy; M3 = M3 * dA + xq * cur.B1.zw;
;       sy[(ng == 0 ? j * 16 : 0) + ysel] = y;
;       cur = nxt;
;     }
	v_mul_f32_e32 v38, v112, v38
	v_fmac_f32_e32 v38, v8, v113
	v_add_f32_e32 v40, v115, v38
	v_pk_mul_f32 v[38:39], v[46:47], v[112:113] op_sel_hi:[1,0]
	ds_write_b32 v71, v40 offset:37376
	v_pk_fma_f32 v[46:47], v[22:23], v[8:9], v[38:39] op_sel_hi:[1,0,1]
	v_pk_mul_f32 v[22:23], v[108:109], v[112:113] op_sel_hi:[1,0]
	v_pk_fma_f32 v[108:109], v[24:25], v[8:9], v[22:23] op_sel_hi:[1,0,1]
	v_pk_mul_f32 v[22:23], v[104:105], v[112:113] op_sel_hi:[1,0]
	v_pk_fma_f32 v[104:105], v[26:27], v[8:9], v[22:23] op_sel_hi:[1,0,1]
	v_pk_mul_f32 v[22:23], v[106:107], v[112:113] op_sel_hi:[1,0]
	v_pk_fma_f32 v[106:107], v[28:29], v[8:9], v[22:23] op_sel_hi:[1,0,1]
	ds_read_b128 v[22:25], v59 offset:5120
	ds_read_b128 v[26:29], v59 offset:5136
	ds_read_b128 v[38:41], v59 offset:13312
	ds_read_b128 v[42:45], v59 offset:13328
	ds_read_b32 v8, v60 offset:17024
	ds_read_b32 v115, v60 offset:18048
	s_waitcnt lgkmcnt(14)
	ds_read_b64 v[112:113], v157 offset:18592
	s_waitcnt lgkmcnt(12)
	v_pk_mul_f32 v[98:99], v[108:109], v[98:99]
	v_pk_fma_f32 v[96:97], v[46:47], v[96:97], v[98:99]
	s_waitcnt lgkmcnt(11)
	v_pk_mul_f32 v[98:99], v[106:107], v[102:103]
	v_pk_fma_f32 v[98:99], v[104:105], v[100:101], v[98:99]
	v_pk_add_f32 v[96:97], v[96:97], v[98:99]
	s_waitcnt lgkmcnt(8)
	v_pk_mul_f32 v[46:47], v[46:47], v[110:111] op_sel_hi:[1,0]
	v_add_f32_e32 v96, v96, v97
	v_pk_fma_f32 v[46:47], v[88:89], v[16:17], v[46:47] op_sel_hi:[1,0,1]
	v_pk_mul_f32 v[88:89], v[108:109], v[110:111] op_sel_hi:[1,0]
	v_add_f32_dpp v96, v96, v96 quad_perm:[1,0,3,2] row_mask:0xf bank_mask:0xf bound_ctrl:1
	v_pk_fma_f32 v[108:109], v[90:91], v[16:17], v[88:89] op_sel_hi:[1,0,1]
	v_pk_mul_f32 v[88:89], v[104:105], v[110:111] op_sel_hi:[1,0]
	v_add_f32_dpp v96, v96, v96 quad_perm:[2,3,0,1] row_mask:0xf bank_mask:0xf bound_ctrl:1
	v_pk_fma_f32 v[104:105], v[92:93], v[16:17], v[88:89] op_sel_hi:[1,0,1]
	v_pk_mul_f32 v[88:89], v[106:107], v[110:111] op_sel_hi:[1,0]
	v_add_f32_dpp v96, v96, v96 row_half_mirror row_mask:0xf bank_mask:0xf bound_ctrl:1
	v_pk_fma_f32 v[106:107], v[94:95], v[16:17], v[88:89] op_sel_hi:[1,0,1]
	s_waitcnt lgkmcnt(4)
	v_pk_mul_f32 v[40:41], v[108:109], v[40:41]
	v_add_f32_dpp v96, v96, v96 row_mirror row_mask:0xf bank_mask:0xf bound_ctrl:1
	v_pk_fma_f32 v[38:39], v[46:47], v[38:39], v[40:41]
	v_mul_f32_e32 v96, v110, v96
	s_waitcnt lgkmcnt(3)
	v_pk_mul_f32 v[40:41], v[106:107], v[44:45]
	v_fmac_f32_e32 v96, v16, v111
	v_pk_fma_f32 v[40:41], v[104:105], v[42:43], v[40:41]
	v_add_f32_e32 v96, v114, v96
	v_pk_add_f32 v[38:39], v[38:39], v[40:41]
	ds_write_b32 v73, v96 offset:37376
	ds_read_b128 v[88:91], v59 offset:5632
	ds_read_b128 v[92:95], v59 offset:5648
	v_add_f32_e32 v38, v38, v39
	ds_read_b128 v[96:99], v59 offset:13824
	ds_read_b128 v[100:103], v59 offset:13840
	v_add_f32_dpp v38, v38, v38 quad_perm:[1,0,3,2] row_mask:0xf bank_mask:0xf bound_ctrl:1
	ds_read_b32 v16, v60 offset:17088
	ds_read_b32 v114, v60 offset:18112
	v_add_f32_dpp v38, v38, v38 quad_perm:[2,3,0,1] row_mask:0xf bank_mask:0xf bound_ctrl:1
	ds_read_b64 v[110:111], v157 offset:18608
	s_nop 0
	v_add_f32_dpp v38, v38, v38 row_half_mirror row_mask:0xf bank_mask:0xf bound_ctrl:1
	s_nop 1
	v_add_f32_dpp v38, v38, v38 row_mirror row_mask:0xf bank_mask:0xf bound_ctrl:1
	s_waitcnt lgkmcnt(8)
	v_mul_f32_e32 v38, v112, v38
	v_fmac_f32_e32 v38, v8, v113
	v_add_f32_e32 v40, v115, v38
	v_pk_mul_f32 v[38:39], v[46:47], v[112:113] op_sel_hi:[1,0]
	ds_write_b32 v74, v40 offset:37376
	v_pk_fma_f32 v[46:47], v[22:23], v[8:9], v[38:39] op_sel_hi:[1,0,1]
	v_pk_mul_f32 v[22:23], v[108:109], v[112:113] op_sel_hi:[1,0]
	v_pk_fma_f32 v[108:109], v[24:25], v[8:9], v[22:23] op_sel_hi:[1,0,1]
	v_pk_mul_f32 v[22:23], v[104:105], v[112:113] op_sel_hi:[1,0]
	v_pk_fma_f32 v[104:105], v[26:27], v[8:9], v[22:23] op_sel_hi:[1,0,1]
	v_pk_mul_f32 v[22:23], v[106:107], v[112:113] op_sel_hi:[1,0]
	v_pk_fma_f32 v[106:107], v[28:29], v[8:9], v[22:23] op_sel_hi:[1,0,1]
	ds_read_b128 v[22:25], v59 offset:6144
	ds_read_b128 v[26:29], v59 offset:6160
	ds_read_b128 v[38:41], v59 offset:14336
	ds_read_b128 v[42:45], v59 offset:14352
	ds_read_b32 v8, v60 offset:17152
	ds_read_b32 v115, v60 offset:18176
	s_waitcnt lgkmcnt(14)
	ds_read_b64 v[112:113], v157 offset:18624
	s_waitcnt lgkmcnt(12)
	v_pk_mul_f32 v[98:99], v[108:109], v[98:99]
	v_pk_fma_f32 v[96:97], v[46:47], v[96:97], v[98:99]
	s_waitcnt lgkmcnt(11)
	v_pk_mul_f32 v[98:99], v[106:107], v[102:103]
	v_pk_fma_f32 v[98:99], v[104:105], v[100:101], v[98:99]
	v_pk_add_f32 v[96:97], v[96:97], v[98:99]
	s_waitcnt lgkmcnt(8)
	v_pk_mul_f32 v[46:47], v[46:47], v[110:111] op_sel_hi:[1,0]
	v_add_f32_e32 v96, v96, v97
	v_pk_fma_f32 v[46:47], v[88:89], v[16:17], v[46:47] op_sel_hi:[1,0,1]
	v_pk_mul_f32 v[88:89], v[108:109], v[110:111] op_sel_hi:[1,0]
	v_add_f32_dpp v96, v96, v96 quad_perm:[1,0,3,2] row_mask:0xf bank_mask:0xf bound_ctrl:1
	v_pk_fma_f32 v[108:109], v[90:91], v[16:17], v[88:89] op_sel_hi:[1,0,1]
	v_pk_mul_f32 v[88:89], v[104:105], v[110:111] op_sel_hi:[1,0]
	v_add_f32_dpp v96, v96, v96 quad_perm:[2,3,0,1] row_mask:0xf bank_mask:0xf bound_ctrl:1
	v_pk_fma_f32 v[104:105], v[92:93], v[16:17], v[88:89] op_sel_hi:[1,0,1]
	v_pk_mul_f32 v[88:89], v[106:107], v[110:111] op_sel_hi:[1,0]
	v_add_f32_dpp v96, v96, v96 row_half_mirror row_mask:0xf bank_mask:0xf bound_ctrl:1
	v_pk_fma_f32 v[106:107], v[94:95], v[16:17], v[88:89] op_sel_hi:[1,0,1]
	s_waitcnt lgkmcnt(4)
	v_pk_mul_f32 v[40:41], v[108:109], v[40:41]
	v_add_f32_dpp v96, v96, v96 row_mirror row_mask:0xf bank_mask:0xf bound_ctrl:1
	v_pk_fma_f32 v[38:39], v[46:47], v[38:39], v[40:41]
	v_mul_f32_e32 v96, v110, v96
	s_waitcnt lgkmcnt(3)
; DI float row16_sum(float v) { v += dppf(v, 0); v += dppf(v, 1); v += dppf(v, 2); v += dppf(v, 3); return v; }
; DI void mamba_scan(CP p, const Ptrs& w, int l, int item, float* sm) {
;     ...
;   auto run_chunk = [&](int c, const float* bf, float* sy) {
;     flush(max(c - 1, 0));
;     MStep cur = lds_step(bf, 0);
; #pragma unroll
;     for (int j = 0; j < 16; ++j) {
;       MStep nxt = cur;
;       if (j + 1 < 16) nxt = lds_step(bf, j + 1);
;       f2v ya = M0 * cur.C0.xy + M1 * cur.C0.zw, yb = M2 * cur.C1.xy + M3 * cur.C1.zw;
;       ya += yb;
;       float yp = row16_sum(ya.x + ya.y);
;       float y = cur.sc.x * yp + cur.xq * cur.sc.y + cur.ds;
;       const float dA = cur.sc.x, xq = cur.xq;
;       M0 = M0 * dA + xq * cur.B0.xy; M1 = M1 * dA + xq * cur.B0.zw;
;       M2 = M2 * dA + xq * cur.B1.xy; M3 = M3 * dA + xq * cur.B1.zw;
;       sy[(ng == 0 ? j * 16 : 0) + ysel] = y;
;       cur = nxt;
;     }
	v_pk_mul_f32 v[40:41], v[106:107], v[44:45]
	v_fmac_f32_e32 v96, v16, v111
	v_pk_fma_f32 v[40:41], v[104:105], v[42:43], v[40:41]
	v_add_f32_e32 v96, v114, v96
	v_pk_add_f32 v[38:39], v[38:39], v[40:41]
	ds_write_b32 v75, v96 offset:37376
	ds_read_b128 v[88:91], v59 offset:6656
	ds_read_b128 v[92:95], v59 offset:6672
	ds_read_b128 v[96:99], v59 offset:14848
	ds_read_b128 v[100:103], v59 offset:14864
	v_add_f32_e32 v38, v38, v39
	ds_read_b32 v16, v60 offset:17216
	ds_read_b32 v118, v60 offset:18240
	v_add_f32_dpp v38, v38, v38 quad_perm:[1,0,3,2] row_mask:0xf bank_mask:0xf bound_ctrl:1
	ds_read_b64 v[116:117], v157 offset:18640
	s_nop 0
	v_add_f32_dpp v38, v38, v38 quad_perm:[2,3,0,1] row_mask:0xf bank_mask:0xf bound_ctrl:1
	s_nop 1
	v_add_f32_dpp v38, v38, v38 row_half_mirror row_mask:0xf bank_mask:0xf bound_ctrl:1
	s_nop 1
	v_add_f32_dpp v38, v38, v38 row_mirror row_mask:0xf bank_mask:0xf bound_ctrl:1
	s_waitcnt lgkmcnt(8)
	v_mul_f32_e32 v38, v112, v38
	v_fmac_f32_e32 v38, v8, v113
	v_add_f32_e32 v40, v115, v38
	v_pk_mul_f32 v[38:39], v[46:47], v[112:113] op_sel_hi:[1,0]
	ds_write_b32 v76, v40 offset:37376
	v_pk_fma_f32 v[22:23], v[22:23], v[8:9], v[38:39] op_sel_hi:[1,0,1]
	v_pk_mul_f32 v[38:39], v[108:109], v[112:113] op_sel_hi:[1,0]
	ds_read_b128 v[42:45], v59 offset:7168
	v_pk_fma_f32 v[24:25], v[24:25], v[8:9], v[38:39] op_sel_hi:[1,0,1]
	v_pk_mul_f32 v[38:39], v[104:105], v[112:113] op_sel_hi:[1,0]
	v_pk_fma_f32 v[26:27], v[26:27], v[8:9], v[38:39] op_sel_hi:[1,0,1]
	v_pk_mul_f32 v[38:39], v[106:107], v[112:113] op_sel_hi:[1,0]
	ds_read_b128 v[104:107], v59 offset:7184
	v_pk_fma_f32 v[28:29], v[28:29], v[8:9], v[38:39] op_sel_hi:[1,0,1]
	ds_read_b128 v[108:111], v59 offset:15360
	ds_read_b128 v[112:115], v59 offset:15376
	ds_read_b32 v8, v60 offset:17280
	ds_read_b32 v119, v60 offset:18304
	s_waitcnt lgkmcnt(14)
	ds_read_b64 v[46:47], v157 offset:18656
	s_waitcnt lgkmcnt(11)
	v_pk_mul_f32 v[38:39], v[24:25], v[98:99]
	v_pk_mul_f32 v[40:41], v[28:29], v[102:103]
	v_pk_fma_f32 v[38:39], v[22:23], v[96:97], v[38:39]
	v_pk_fma_f32 v[40:41], v[26:27], v[100:101], v[40:41]
	v_pk_add_f32 v[38:39], v[38:39], v[40:41]
	v_add_f32_e32 v38, v38, v39
	s_waitcnt lgkmcnt(8)
	v_pk_mul_f32 v[22:23], v[22:23], v[116:117] op_sel_hi:[1,0]
	v_pk_fma_f32 v[40:41], v[88:89], v[16:17], v[22:23] op_sel_hi:[1,0,1]
	v_add_f32_dpp v38, v38, v38 quad_perm:[1,0,3,2] row_mask:0xf bank_mask:0xf bound_ctrl:1
	v_pk_mul_f32 v[22:23], v[24:25], v[116:117] op_sel_hi:[1,0]
	v_pk_fma_f32 v[96:97], v[90:91], v[16:17], v[22:23] op_sel_hi:[1,0,1]
	v_add_f32_dpp v38, v38, v38 quad_perm:[2,3,0,1] row_mask:0xf bank_mask:0xf bound_ctrl:1
	v_pk_mul_f32 v[22:23], v[26:27], v[116:117] op_sel_hi:[1,0]
	v_pk_fma_f32 v[98:99], v[92:93], v[16:17], v[22:23] op_sel_hi:[1,0,1]
	v_add_f32_dpp v38, v38, v38 row_half_mirror row_mask:0xf bank_mask:0xf bound_ctrl:1
	v_pk_mul_f32 v[22:23], v[28:29], v[116:117] op_sel_hi:[1,0]
	v_pk_fma_f32 v[100:101], v[94:95], v[16:17], v[22:23] op_sel_hi:[1,0,1]
	v_add_f32_dpp v38, v38, v38 row_mirror row_mask:0xf bank_mask:0xf bound_ctrl:1
	v_mul_f32_e32 v38, v116, v38
	v_fmac_f32_e32 v38, v16, v117
	v_add_f32_e32 v38, v118, v38
	ds_write_b32 v77, v38 offset:37376
	ds_read_b128 v[26:29], v59 offset:7680
	ds_read_b128 v[22:25], v59 offset:7696
	ds_read_b128 v[88:91], v59 offset:15872
	ds_read_b128 v[92:95], v59 offset:15888
	s_waitcnt lgkmcnt(6)
	v_pk_mul_f32 v[102:103], v[96:97], v[110:111]
	ds_read_b32 v16, v60 offset:17344
	v_pk_fma_f32 v[102:103], v[40:41], v[108:109], v[102:103]
	v_pk_mul_f32 v[108:109], v[100:101], v[114:115]
	s_waitcnt lgkmcnt(6)
	v_pk_mul_f32 v[40:41], v[40:41], v[46:47] op_sel_hi:[1,0]
	ds_read_b32 v116, v60 offset:18368
	v_pk_fma_f32 v[108:109], v[98:99], v[112:113], v[108:109]
	v_pk_fma_f32 v[42:43], v[42:43], v[8:9], v[40:41] op_sel_hi:[1,0,1]
	v_pk_mul_f32 v[40:41], v[96:97], v[46:47] op_sel_hi:[1,0]
	v_pk_add_f32 v[102:103], v[102:103], v[108:109]
	ds_read_b64 v[38:39], v157 offset:18672
	v_add_f32_e32 v102, v102, v103
	v_pk_fma_f32 v[44:45], v[44:45], v[8:9], v[40:41] op_sel_hi:[1,0,1]
	v_pk_mul_f32 v[40:41], v[98:99], v[46:47] op_sel_hi:[1,0]
	v_add_f32_dpp v102, v102, v102 quad_perm:[1,0,3,2] row_mask:0xf bank_mask:0xf bound_ctrl:1
	v_pk_fma_f32 v[40:41], v[104:105], v[8:9], v[40:41] op_sel_hi:[1,0,1]
	s_waitcnt lgkmcnt(4)
	v_pk_mul_f32 v[90:91], v[44:45], v[90:91]
	v_add_f32_dpp v102, v102, v102 quad_perm:[2,3,0,1] row_mask:0xf bank_mask:0xf bound_ctrl:1
	v_pk_fma_f32 v[88:89], v[42:43], v[88:89], v[90:91]
	s_nop 0
	v_add_f32_dpp v102, v102, v102 row_half_mirror row_mask:0xf bank_mask:0xf bound_ctrl:1
	s_nop 1
	v_add_f32_dpp v102, v102, v102 row_mirror row_mask:0xf bank_mask:0xf bound_ctrl:1
	v_mul_f32_e32 v102, v46, v102
	v_fmac_f32_e32 v102, v8, v47
	v_pk_mul_f32 v[46:47], v[100:101], v[46:47] op_sel_hi:[1,0]
	v_add_f32_e32 v102, v119, v102
	v_pk_fma_f32 v[46:47], v[106:107], v[8:9], v[46:47] op_sel_hi:[1,0,1]
	ds_write_b32 v78, v102 offset:37376
	s_waitcnt lgkmcnt(4)
	v_pk_mul_f32 v[90:91], v[46:47], v[94:95]
	v_pk_fma_f32 v[90:91], v[40:41], v[92:93], v[90:91]
	v_pk_add_f32 v[88:89], v[88:89], v[90:91]
	s_waitcnt vmcnt(8)
	v_lshlrev_b32_e32 v90, 16, v5
	v_add_f32_e32 v8, v88, v89
	v_lshlrev_b32_e32 v88, 16, v4
	v_and_b32_e32 v89, 0xffff0000, v4
	v_add_f32_dpp v8, v8, v8 quad_perm:[1,0,3,2] row_mask:0xf bank_mask:0xf bound_ctrl:1
	v_and_b32_e32 v91, 0xffff0000, v5
	v_lshlrev_b32_e32 v4, 16, v6
	v_add_f32_dpp v8, v8, v8 quad_perm:[2,3,0,1] row_mask:0xf bank_mask:0xf bound_ctrl:1
	v_and_b32_e32 v5, 0xffff0000, v6
	v_lshlrev_b32_e32 v6, 16, v7
	v_add_f32_dpp v8, v8, v8 row_half_mirror row_mask:0xf bank_mask:0xf bound_ctrl:1
	v_and_b32_e32 v7, 0xffff0000, v7
	s_nop 0
	v_add_f32_dpp v8, v8, v8 row_mirror row_mask:0xf bank_mask:0xf bound_ctrl:1
	s_waitcnt lgkmcnt(1)
; DI float bf2f(bf16_t h) { return __uint_as_float(((unsigned)h) << 16); }
; DI float siluf(float x) { return x * sigmf(x); }
; DI void mamba_scan(CP p, const Ptrs& w, int l, int item, float* sm) {
;     ...
;   auto load = [&](int c, MPre& P) {
; #pragma unroll
;     for (int i = 0; i < 2; ++i) {
;       int idx = tid + 256 * i, j = idx >> 5, q = idx & 31;
;       int ii = pos2i(c * 16 + j, dir);
;       P.pbq[i] = *(const uint4*)(mbc + ((size_t)b * TPB + ii) * 512 + (q < 16 ? 0 : 256) + gp * 128 + (q & 15) * 8);
;     }
;     {
;       int pos = c * 16 + xj, ii = pos2i(pos, dir);
;       size_t tok = (size_t)b * TPB + ii;
;       const bf16_t* prw = w.pC + tok * SPC;
;       bool hp = (ii != 0) && (ii != CTXL), hn = (ii != CTXL - 1) && (ii != TPB - 1);
;       P.px[0] = prw[chX + (hp ? -SPC : 0)]; P.px[1] = prw[chX]; P.px[2] = prw[chX + (hn ? SPC : 0)];
;       P.pxm[0] = hp ? 1.f : 0.f; P.pxm[1] = hn ? 1.f : 0.f;
;       float2 dd = *(const float2*)(w.mdt + (tok * 16 + dir * 8 + hd) * 2);
;       P.pdt[0] = dd.x; P.pdt[1] = dd.y; P.pdt[2] = w.mcb[tok * 2 + gp];
;     }
;   };
;   auto stage = [&](const MPre& P, float* bufp) {
; #pragma unroll
;     for (int i = 0; i < 2; ++i) {
;       int idx = tid + 256 * i, j = idx >> 5, q = idx & 31;
;       float f[8];
;       unpack8(P.pbq[i], f);
;       float* d = bufp + (q < 16 ? 0 : 2048) + j * 128 + (q & 15) * 8;
;       *(float4*)d = make_float4(f[0], f[1], f[2], f[3]);
;       *(float4*)(d + 4) = make_float4(f[4], f[5], f[6], f[7]);
;     }
;     {
;       float xs = siluf(wX0 * P.pxm[0] * bf2f(P.px[0]) + wX1 * bf2f(P.px[1]) + wX2 * P.pxm[1] * bf2f(P.px[2]) + bX);
;       bufp[4096 + xj * 16 + xp] = xs * P.pdt[0];
;       bufp[4096 + 256 + xj * 16 + xp] = Dsk * xs;
;       if (xp == 0) *(float4*)(bufp + 4096 + 512 + xj * 4) = make_float4(P.pdt[1], P.pdt[2], 0.f, 0.f);
;     }
;   };
	v_mul_f32_e32 v8, v38, v8
	v_fmac_f32_e32 v8, v16, v39
	v_add_f32_e32 v8, v116, v8
	ds_write_b32 v80, v8 offset:37376
	ds_write_b128 v58, v[88:91] offset:18688
	ds_write_b128 v58, v[4:7] offset:18704
	v_lshlrev_b32_e32 v4, 16, v0
	v_and_b32_e32 v5, 0xffff0000, v0
	v_lshlrev_b32_e32 v6, 16, v1
	v_and_b32_e32 v7, 0xffff0000, v1
	v_mul_f32_e32 v0, v49, v87
	v_lshlrev_b32_e32 v1, 16, v64
	v_mul_f32_e32 v0, v0, v1
	v_lshlrev_b32_e32 v1, 16, v69
	v_fmac_f32_e32 v0, v50, v1
	v_mul_f32_e32 v1, v51, v86
	v_lshlrev_b32_e32 v8, 16, v79
	v_fmac_f32_e32 v0, v1, v8
	v_add_f32_e32 v8, v52, v0
	v_mul_f32_e32 v0, 0xbfb8aa3b, v8
	v_exp_f32_e32 v39, v0
	v_lshlrev_b32_e32 v0, 16, v2
	v_and_b32_e32 v1, 0xffff0000, v2
	v_lshlrev_b32_e32 v2, 16, v3
	v_add_f32_e32 v39, 1.0, v39
	v_rcp_f32_e32 v39, v39
	v_and_b32_e32 v3, 0xffff0000, v3
	ds_write_b128 v58, v[4:7] offset:22784
	ds_write_b128 v58, v[0:3] offset:22800
	v_mul_f32_e32 v0, v8, v39
	v_mul_f32_e32 v1, v10, v0
	v_mul_f32_e32 v0, v53, v0
	ds_write2st64_b32 v57, v1, v0 offset0:137 offset1:141
	s_and_saveexec_b64 s[4:5], vcc
	v_mov_b32_e32 v8, v11
	v_mov_b32_e32 v10, v157
	v_mov_b32_e32 v11, v157
	ds_write_b128 v72, v[8:11] offset:37120
	s_or_b64 exec, exec, s[4:5]
	s_add_i32 s7, s7, 2
	v_pk_mul_f32 v[0:1], v[42:43], v[38:39] op_sel_hi:[1,0]
	s_min_u32 s4, s7, 0x20c
	v_pk_fma_f32 v[108:109], v[26:27], v[16:17], v[0:1] op_sel_hi:[1,0,1]
	v_pk_mul_f32 v[0:1], v[44:45], v[38:39] op_sel_hi:[1,0]
	s_lshl_b32 s4, s4, 4
	v_pk_fma_f32 v[110:111], v[28:29], v[16:17], v[0:1] op_sel_hi:[1,0,1]
	v_pk_mul_f32 v[0:1], v[40:41], v[38:39] op_sel_hi:[1,0]
	v_cndmask_b32_e64 v87, 1.0, 0, s[42:43]
	v_pk_fma_f32 v[112:113], v[22:23], v[16:17], v[0:1] op_sel_hi:[1,0,1]
	v_pk_mul_f32 v[0:1], v[46:47], v[38:39] op_sel_hi:[1,0]
	s_add_i32 s42, s4, 48
	v_pk_fma_f32 v[46:47], v[24:25], v[16:17], v[0:1] op_sel_hi:[1,0,1]
	v_add_u32_e32 v0, s42, v55
	v_cmp_lt_i32_e64 s[4:5], s37, v0
	v_add_u32_e32 v2, s42, v56
	v_add_u32_e32 v8, s42, v54
	v_cndmask_b32_e64 v1, v231, v232, s[4:5]
	v_cmp_lt_i32_e64 s[4:5], s37, v2
	v_sub_u32_e32 v1, v1, v0
	v_cndmask_b32_e64 v0, v1, v0, s[40:41]
	v_cndmask_b32_e64 v3, v231, v232, s[4:5]
	v_cmp_lt_i32_e64 s[4:5], s37, v8
	v_sub_u32_e32 v3, v3, v2
	v_cndmask_b32_e64 v2, v3, v2, s[40:41]
	v_cndmask_b32_e64 v9, v231, v232, s[4:5]
	v_sub_u32_e32 v9, v9, v8
	v_cndmask_b32_e64 v8, v9, v8, s[40:41]
	v_ashrrev_i32_e32 v9, 31, v8
	v_lshl_add_u64 v[10:11], v[8:9], 0, s[90:91]
	v_and_b32_e32 v9, 0xfffffeff, v8
	v_cmp_eq_u32_e64 s[42:43], 0, v9
	v_ashrrev_i32_e32 v1, 31, v0
	v_ashrrev_i32_e32 v3, 31, v2
	v_mov_b64_e32 v[22:23], s[48:49]
	v_and_b32_e32 v16, 0xffffdfff, v8
	v_cndmask_b32_e64 v8, v233, 0, s[42:43]
	v_lshl_add_u64 v[0:1], v[0:1], 0, s[90:91]
	v_lshl_add_u64 v[2:3], v[2:3], 0, s[90:91]
	v_mad_u64_u32 v[22:23], s[4:5], v10, s92, v[22:23]
	v_add_u32_e32 v8, v8, v48
	v_cndmask_b32_e64 v86, 1.0, 0, s[44:45]
	v_lshlrev_b64 v[0:1], 10, v[0:1]
	v_lshlrev_b64 v[2:3], 10, v[2:3]
	v_mad_i32_i24 v23, v11, s92, v23
	v_ashrrev_i32_e32 v9, 31, v8
	v_cmp_eq_u32_e64 s[44:45], s37, v16
	v_lshlrev_b64 v[26:27], 7, v[10:11]
	v_lshl_add_u64 v[0:1], v[30:31], 0, v[0:1]
	v_lshl_add_u64 v[2:3], v[30:31], 0, v[2:3]
	v_lshl_add_u64 v[8:9], v[8:9], 1, v[22:23]
	v_lshl_add_u64 v[22:23], v[22:23], 0, v[156:157]
	v_cndmask_b32_e64 v24, v234, 0, s[44:45]
	v_mov_b32_e32 v25, v157
	v_lshl_or_b32 v26, s6, 3, v26
	s_waitcnt lgkmcnt(0)
	s_barrier
	s_waitcnt lgkmcnt(0)
	global_load_dwordx4 v[4:7], v[0:1], off
	global_load_dwordx4 v[0:3], v[2:3], off
	global_load_ushort v64, v[8:9], off
	global_load_ushort v69, v[22:23], off
	v_lshl_add_u64 v[24:25], v[22:23], 0, v[24:25]
	v_lshl_add_u64 v[26:27], s[46:47], 0, v[26:27]
	v_lshl_add_u64 v[28:29], v[10:11], 3, s[50:51]
	global_load_ushort v79, v[24:25], off
	global_load_dwordx2 v[10:11], v[26:27], off
	global_load_dword v9, v[28:29], off
	ds_read_b32 v8, v57 offset:37376
	v_cmp_lt_i32_e64 s[4:5], s37, v82
	ds_read_b128 v[22:25], v59 offset:18688
	s_waitcnt lgkmcnt(1)
	v_cvt_pk_bf16_f32 v8, v8, s0
	v_cndmask_b32_e64 v16, v231, v232, s[4:5]
	s_mov_b32 s4, 0x9000
	v_add_u32_e32 v16, v16, v81
	v_cndmask_b32_e64 v26, v16, v82, s[40:41]
	v_ashrrev_i32_e32 v27, 31, v26
	v_lshl_add_u64 v[26:27], v[26:27], 0, s[90:91]
	v_lshlrev_b64 v[26:27], 10, v[26:27]
	v_lshl_add_u64 v[26:27], v[34:35], 0, v[26:27]
	global_store_short v[26:27], v8, off
	v_add_u32_e32 v8, 0x8800, v60
	ds_read2_b32 v[114:115], v8 offset0:64 offset1:80
	v_add_u32_e32 v8, 0x8c00, v60
	ds_read2_b32 v[116:117], v8 offset0:64 offset1:80
	v_add_u32_e64 v8, s4, 0
	ds_read2_b64 v[26:29], v8 offset0:32 offset1:34
	ds_read_b128 v[38:41], v59 offset:18704
	ds_read_b128 v[42:45], v59 offset:19200
	ds_read_b128 v[88:91], v59 offset:26880
	ds_read_b128 v[92:95], v59 offset:19216
	ds_read_b128 v[96:99], v59 offset:26896
	ds_read_b128 v[100:103], v59 offset:27392
	ds_read_b128 v[104:107], v59 offset:27408
	s_waitcnt lgkmcnt(4)
	v_pk_mul_f32 v[90:91], v[110:111], v[90:91]
	v_pk_fma_f32 v[88:89], v[108:109], v[88:89], v[90:91]
	s_waitcnt lgkmcnt(2)
	v_pk_mul_f32 v[90:91], v[46:47], v[98:99]
	v_pk_fma_f32 v[90:91], v[112:113], v[96:97], v[90:91]
	v_pk_add_f32 v[88:89], v[88:89], v[90:91]
	v_add_f32_e32 v8, v88, v89
	v_pk_mul_f32 v[88:89], v[108:109], v[26:27] op_sel_hi:[1,0]
	v_pk_fma_f32 v[108:109], v[22:23], v[114:115], v[88:89] op_sel_hi:[1,0,1]
	v_add_f32_dpp v8, v8, v8 quad_perm:[1,0,3,2] row_mask:0xf bank_mask:0xf bound_ctrl:1
	v_pk_mul_f32 v[22:23], v[110:111], v[26:27] op_sel_hi:[1,0]
	v_pk_fma_f32 v[110:111], v[24:25], v[114:115], v[22:23] op_sel_hi:[1,0,1]
	v_add_f32_dpp v8, v8, v8 quad_perm:[2,3,0,1] row_mask:0xf bank_mask:0xf bound_ctrl:1
	v_pk_mul_f32 v[22:23], v[112:113], v[26:27] op_sel_hi:[1,0]
	s_waitcnt lgkmcnt(1)
; DI float row16_sum(float v) { v += dppf(v, 0); v += dppf(v, 1); v += dppf(v, 2); v += dppf(v, 3); return v; }
; DI void mamba_scan(CP p, const Ptrs& w, int l, int item, float* sm) {
;     ...
;   auto run_chunk = [&](int c, const float* bf, float* sy) {
;     flush(max(c - 1, 0));
;     MStep cur = lds_step(bf, 0);
; #pragma unroll
;     for (int j = 0; j < 16; ++j) {
;       MStep nxt = cur;
;       if (j + 1 < 16) nxt = lds_step(bf, j + 1);
;       f2v ya = M0 * cur.C0.xy + M1 * cur.C0.zw, yb = M2 * cur.C1.xy + M3 * cur.C1.zw;
;       ya += yb;
;       float yp = row16_sum(ya.x + ya.y);
;       float y = cur.sc.x * yp + cur.xq * cur.sc.y + cur.ds;
;       const float dA = cur.sc.x, xq = cur.xq;
;       M0 = M0 * dA + xq * cur.B0.xy; M1 = M1 * dA + xq * cur.B0.zw;
;       M2 = M2 * dA + xq * cur.B1.xy; M3 = M3 * dA + xq * cur.B1.zw;
;       sy[(ng == 0 ? j * 16 : 0) + ysel] = y;
;       cur = nxt;
;     }
	v_pk_mul_f32 v[102:103], v[110:111], v[102:103]
	v_add_f32_dpp v8, v8, v8 row_half_mirror row_mask:0xf bank_mask:0xf bound_ctrl:1
	v_pk_fma_f32 v[112:113], v[38:39], v[114:115], v[22:23] op_sel_hi:[1,0,1]
	v_pk_mul_f32 v[22:23], v[46:47], v[26:27] op_sel_hi:[1,0]
	v_add_f32_dpp v8, v8, v8 row_mirror row_mask:0xf bank_mask:0xf bound_ctrl:1
	v_mul_f32_e32 v8, v26, v8
	v_fmac_f32_e32 v8, v114, v27
	v_pk_fma_f32 v[26:27], v[40:41], v[114:115], v[22:23] op_sel_hi:[1,0,1]
	v_add_f32_e32 v8, v116, v8
	v_pk_fma_f32 v[100:101], v[108:109], v[100:101], v[102:103]
	s_waitcnt lgkmcnt(0)
	v_pk_mul_f32 v[102:103], v[26:27], v[106:107]
	ds_write_b32 v61, v8 offset:38400
	ds_read_b128 v[22:25], v59 offset:19712
	ds_read_b128 v[38:41], v59 offset:19728
	ds_read_b128 v[88:91], v59 offset:27904
	ds_read_b128 v[96:99], v59 offset:27920
	v_pk_fma_f32 v[102:103], v[112:113], v[104:105], v[102:103]
	ds_read_b32 v8, v60 offset:35200
	v_pk_add_f32 v[100:101], v[100:101], v[102:103]
	ds_read_b32 v114, v60 offset:36224
	v_add_f32_e32 v16, v100, v101
	ds_read_b64 v[46:47], v157 offset:37152
	v_pk_mul_f32 v[100:101], v[108:109], v[28:29] op_sel_hi:[1,0]
	v_add_f32_dpp v16, v16, v16 quad_perm:[1,0,3,2] row_mask:0xf bank_mask:0xf bound_ctrl:1
	v_pk_mul_f32 v[26:27], v[26:27], v[28:29] op_sel_hi:[1,0]
	s_nop 0
	v_add_f32_dpp v16, v16, v16 quad_perm:[2,3,0,1] row_mask:0xf bank_mask:0xf bound_ctrl:1
	s_nop 1
	v_add_f32_dpp v16, v16, v16 row_half_mirror row_mask:0xf bank_mask:0xf bound_ctrl:1
	s_nop 1
	v_add_f32_dpp v16, v16, v16 row_mirror row_mask:0xf bank_mask:0xf bound_ctrl:1
	v_mul_f32_e32 v16, v28, v16
	v_fmac_f32_e32 v16, v115, v29
	v_add_f32_e32 v102, v117, v16
	v_mov_b32_e32 v16, v115
	ds_write_b32 v62, v102 offset:38400
	v_pk_fma_f32 v[104:105], v[42:43], v[16:17], v[100:101] op_sel_hi:[1,0,1]
	v_pk_mul_f32 v[42:43], v[110:111], v[28:29] op_sel_hi:[1,0]
	v_pk_fma_f32 v[110:111], v[94:95], v[16:17], v[26:27] op_sel_hi:[1,0,1]
	v_pk_fma_f32 v[106:107], v[44:45], v[16:17], v[42:43] op_sel_hi:[1,0,1]
	v_pk_mul_f32 v[42:43], v[112:113], v[28:29] op_sel_hi:[1,0]
	ds_read_b128 v[26:29], v59 offset:20224
	v_pk_fma_f32 v[108:109], v[92:93], v[16:17], v[42:43] op_sel_hi:[1,0,1]
	ds_read_b128 v[42:45], v59 offset:20240
	ds_read_b128 v[92:95], v59 offset:28416
	ds_read_b128 v[100:103], v59 offset:28432
	ds_read_b32 v16, v60 offset:35264
	ds_read_b32 v115, v60 offset:36288
	s_waitcnt lgkmcnt(14)
	ds_read_b64 v[112:113], v157 offset:37168
	s_waitcnt lgkmcnt(10)
	v_pk_mul_f32 v[90:91], v[106:107], v[90:91]
	v_pk_fma_f32 v[88:89], v[104:105], v[88:89], v[90:91]
	v_pk_mul_f32 v[90:91], v[110:111], v[98:99]
	v_pk_fma_f32 v[90:91], v[108:109], v[96:97], v[90:91]
	v_pk_add_f32 v[88:89], v[88:89], v[90:91]
	v_add_f32_e32 v88, v88, v89
	s_nop 1
	v_add_f32_dpp v88, v88, v88 quad_perm:[1,0,3,2] row_mask:0xf bank_mask:0xf bound_ctrl:1
	s_nop 1
	v_add_f32_dpp v88, v88, v88 quad_perm:[2,3,0,1] row_mask:0xf bank_mask:0xf bound_ctrl:1
	s_nop 1
	v_add_f32_dpp v88, v88, v88 row_half_mirror row_mask:0xf bank_mask:0xf bound_ctrl:1
	s_nop 1
	v_add_f32_dpp v88, v88, v88 row_mirror row_mask:0xf bank_mask:0xf bound_ctrl:1
	s_waitcnt lgkmcnt(8)
	v_mul_f32_e32 v88, v46, v88
	v_fmac_f32_e32 v88, v8, v47
	v_add_f32_e32 v90, v114, v88
	v_pk_mul_f32 v[88:89], v[104:105], v[46:47] op_sel_hi:[1,0]
	ds_write_b32 v63, v90 offset:38400
	v_pk_fma_f32 v[104:105], v[22:23], v[8:9], v[88:89] op_sel_hi:[1,0,1]
	v_pk_mul_f32 v[22:23], v[106:107], v[46:47] op_sel_hi:[1,0]
	v_pk_fma_f32 v[106:107], v[24:25], v[8:9], v[22:23] op_sel_hi:[1,0,1]
	v_pk_mul_f32 v[22:23], v[108:109], v[46:47] op_sel_hi:[1,0]
	v_pk_fma_f32 v[108:109], v[38:39], v[8:9], v[22:23] op_sel_hi:[1,0,1]
	v_pk_mul_f32 v[22:23], v[110:111], v[46:47] op_sel_hi:[1,0]
	s_waitcnt lgkmcnt(5)
	v_pk_mul_f32 v[94:95], v[106:107], v[94:95]
	v_pk_fma_f32 v[46:47], v[40:41], v[8:9], v[22:23] op_sel_hi:[1,0,1]
	ds_read_b128 v[22:25], v59 offset:20736
	v_pk_fma_f32 v[92:93], v[104:105], v[92:93], v[94:95]
	s_waitcnt lgkmcnt(4)
	v_pk_mul_f32 v[94:95], v[46:47], v[102:103]
	ds_read_b128 v[38:41], v59 offset:20752
	v_pk_fma_f32 v[94:95], v[108:109], v[100:101], v[94:95]
	ds_read_b128 v[88:91], v59 offset:28928
	v_pk_add_f32 v[92:93], v[92:93], v[94:95]
	ds_read_b128 v[96:99], v59 offset:28944
	v_add_f32_e32 v92, v92, v93
	ds_read_b32 v8, v60 offset:35328
	ds_read_b32 v114, v60 offset:36352
	v_add_f32_dpp v92, v92, v92 quad_perm:[1,0,3,2] row_mask:0xf bank_mask:0xf bound_ctrl:1
	ds_read_b64 v[110:111], v157 offset:37184
	s_nop 0
	v_add_f32_dpp v92, v92, v92 quad_perm:[2,3,0,1] row_mask:0xf bank_mask:0xf bound_ctrl:1
	s_nop 1
	v_add_f32_dpp v92, v92, v92 row_half_mirror row_mask:0xf bank_mask:0xf bound_ctrl:1
	s_nop 1
	v_add_f32_dpp v92, v92, v92 row_mirror row_mask:0xf bank_mask:0xf bound_ctrl:1
	s_waitcnt lgkmcnt(8)
	v_mul_f32_e32 v92, v112, v92
	v_fmac_f32_e32 v92, v16, v113
	v_add_f32_e32 v94, v115, v92
	v_pk_mul_f32 v[92:93], v[104:105], v[112:113] op_sel_hi:[1,0]
	ds_write_b32 v65, v94 offset:38400
	v_pk_fma_f32 v[104:105], v[26:27], v[16:17], v[92:93] op_sel_hi:[1,0,1]
	v_pk_mul_f32 v[26:27], v[106:107], v[112:113] op_sel_hi:[1,0]
	v_pk_fma_f32 v[106:107], v[28:29], v[16:17], v[26:27] op_sel_hi:[1,0,1]
	v_pk_mul_f32 v[26:27], v[108:109], v[112:113] op_sel_hi:[1,0]
	v_pk_fma_f32 v[108:109], v[42:43], v[16:17], v[26:27] op_sel_hi:[1,0,1]
	v_pk_mul_f32 v[26:27], v[46:47], v[112:113] op_sel_hi:[1,0]
	v_pk_fma_f32 v[46:47], v[44:45], v[16:17], v[26:27] op_sel_hi:[1,0,1]
	ds_read_b128 v[26:29], v59 offset:21248
	ds_read_b128 v[42:45], v59 offset:21264
	ds_read_b128 v[92:95], v59 offset:29440
	ds_read_b128 v[100:103], v59 offset:29456
	ds_read_b32 v16, v60 offset:35392
	ds_read_b32 v115, v60 offset:36416
	s_waitcnt lgkmcnt(14)
; DI float row16_sum(float v) { v += dppf(v, 0); v += dppf(v, 1); v += dppf(v, 2); v += dppf(v, 3); return v; }
; DI void mamba_scan(CP p, const Ptrs& w, int l, int item, float* sm) {
;     ...
;   auto run_chunk = [&](int c, const float* bf, float* sy) {
;     flush(max(c - 1, 0));
;     MStep cur = lds_step(bf, 0);
; #pragma unroll
;     for (int j = 0; j < 16; ++j) {
;       MStep nxt = cur;
;       if (j + 1 < 16) nxt = lds_step(bf, j + 1);
;       f2v ya = M0 * cur.C0.xy + M1 * cur.C0.zw, yb = M2 * cur.C1.xy + M3 * cur.C1.zw;
;       ya += yb;
;       float yp = row16_sum(ya.x + ya.y);
;       float y = cur.sc.x * yp + cur.xq * cur.sc.y + cur.ds;
;       const float dA = cur.sc.x, xq = cur.xq;
;       M0 = M0 * dA + xq * cur.B0.xy; M1 = M1 * dA + xq * cur.B0.zw;
;       M2 = M2 * dA + xq * cur.B1.xy; M3 = M3 * dA + xq * cur.B1.zw;
;       sy[(ng == 0 ? j * 16 : 0) + ysel] = y;
;       cur = nxt;
;     }
	ds_read_b64 v[112:113], v157 offset:37200
	s_waitcnt lgkmcnt(11)
	v_pk_mul_f32 v[90:91], v[106:107], v[90:91]
	v_pk_fma_f32 v[88:89], v[104:105], v[88:89], v[90:91]
	v_pk_mul_f32 v[90:91], v[46:47], v[98:99]
	v_pk_fma_f32 v[90:91], v[108:109], v[96:97], v[90:91]
	v_pk_add_f32 v[88:89], v[88:89], v[90:91]
	v_add_f32_e32 v88, v88, v89
	s_nop 1
	v_add_f32_dpp v88, v88, v88 quad_perm:[1,0,3,2] row_mask:0xf bank_mask:0xf bound_ctrl:1
	s_nop 1
	v_add_f32_dpp v88, v88, v88 quad_perm:[2,3,0,1] row_mask:0xf bank_mask:0xf bound_ctrl:1
	s_nop 1
	v_add_f32_dpp v88, v88, v88 row_half_mirror row_mask:0xf bank_mask:0xf bound_ctrl:1
	s_nop 1
	v_add_f32_dpp v88, v88, v88 row_mirror row_mask:0xf bank_mask:0xf bound_ctrl:1
	s_waitcnt lgkmcnt(8)
	v_mul_f32_e32 v88, v110, v88
	v_fmac_f32_e32 v88, v8, v111
	v_add_f32_e32 v90, v114, v88
	v_pk_mul_f32 v[88:89], v[104:105], v[110:111] op_sel_hi:[1,0]
	ds_write_b32 v66, v90 offset:38400
	v_pk_fma_f32 v[104:105], v[22:23], v[8:9], v[88:89] op_sel_hi:[1,0,1]
	v_pk_mul_f32 v[22:23], v[106:107], v[110:111] op_sel_hi:[1,0]
	v_pk_fma_f32 v[106:107], v[24:25], v[8:9], v[22:23] op_sel_hi:[1,0,1]
	v_pk_mul_f32 v[22:23], v[108:109], v[110:111] op_sel_hi:[1,0]
	v_pk_fma_f32 v[108:109], v[38:39], v[8:9], v[22:23] op_sel_hi:[1,0,1]
	v_pk_mul_f32 v[22:23], v[46:47], v[110:111] op_sel_hi:[1,0]
	v_pk_fma_f32 v[46:47], v[40:41], v[8:9], v[22:23] op_sel_hi:[1,0,1]
	ds_read_b128 v[22:25], v59 offset:21760
	s_waitcnt lgkmcnt(6)
	v_pk_mul_f32 v[94:95], v[106:107], v[94:95]
	ds_read_b128 v[38:41], v59 offset:21776
	v_pk_fma_f32 v[92:93], v[104:105], v[92:93], v[94:95]
	s_waitcnt lgkmcnt(4)
	v_pk_mul_f32 v[94:95], v[46:47], v[102:103]
	ds_read_b128 v[88:91], v59 offset:29952
	v_pk_fma_f32 v[94:95], v[108:109], v[100:101], v[94:95]
	ds_read_b128 v[96:99], v59 offset:29968
	v_pk_add_f32 v[92:93], v[92:93], v[94:95]
	ds_read_b32 v8, v60 offset:35456
	v_add_f32_e32 v92, v92, v93
	ds_read_b32 v114, v60 offset:36480
	ds_read_b64 v[110:111], v157 offset:37216
	v_add_f32_dpp v92, v92, v92 quad_perm:[1,0,3,2] row_mask:0xf bank_mask:0xf bound_ctrl:1
	s_nop 1
	v_add_f32_dpp v92, v92, v92 quad_perm:[2,3,0,1] row_mask:0xf bank_mask:0xf bound_ctrl:1
	s_nop 1
	v_add_f32_dpp v92, v92, v92 row_half_mirror row_mask:0xf bank_mask:0xf bound_ctrl:1
	s_nop 1
	v_add_f32_dpp v92, v92, v92 row_mirror row_mask:0xf bank_mask:0xf bound_ctrl:1
	s_waitcnt lgkmcnt(8)
	v_mul_f32_e32 v92, v112, v92
	v_fmac_f32_e32 v92, v16, v113
	v_add_f32_e32 v94, v115, v92
	v_pk_mul_f32 v[92:93], v[104:105], v[112:113] op_sel_hi:[1,0]
	ds_write_b32 v67, v94 offset:38400
	v_pk_fma_f32 v[104:105], v[26:27], v[16:17], v[92:93] op_sel_hi:[1,0,1]
	v_pk_mul_f32 v[26:27], v[106:107], v[112:113] op_sel_hi:[1,0]
	v_pk_fma_f32 v[106:107], v[28:29], v[16:17], v[26:27] op_sel_hi:[1,0,1]
	v_pk_mul_f32 v[26:27], v[108:109], v[112:113] op_sel_hi:[1,0]
	v_pk_fma_f32 v[108:109], v[42:43], v[16:17], v[26:27] op_sel_hi:[1,0,1]
	v_pk_mul_f32 v[26:27], v[46:47], v[112:113] op_sel_hi:[1,0]
	v_pk_fma_f32 v[46:47], v[44:45], v[16:17], v[26:27] op_sel_hi:[1,0,1]
	ds_read_b128 v[26:29], v59 offset:22272
	ds_read_b128 v[42:45], v59 offset:22288
	ds_read_b128 v[92:95], v59 offset:30464
	ds_read_b128 v[100:103], v59 offset:30480
	ds_read_b32 v16, v60 offset:35520
	ds_read_b32 v115, v60 offset:36544
	s_waitcnt lgkmcnt(14)
	ds_read_b64 v[112:113], v157 offset:37232
	s_waitcnt lgkmcnt(11)
	v_pk_mul_f32 v[90:91], v[106:107], v[90:91]
	v_pk_fma_f32 v[88:89], v[104:105], v[88:89], v[90:91]
	v_pk_mul_f32 v[90:91], v[46:47], v[98:99]
	v_pk_fma_f32 v[90:91], v[108:109], v[96:97], v[90:91]
	v_pk_add_f32 v[88:89], v[88:89], v[90:91]
	v_add_f32_e32 v88, v88, v89
	s_nop 1
	v_add_f32_dpp v88, v88, v88 quad_perm:[1,0,3,2] row_mask:0xf bank_mask:0xf bound_ctrl:1
	s_nop 1
	v_add_f32_dpp v88, v88, v88 quad_perm:[2,3,0,1] row_mask:0xf bank_mask:0xf bound_ctrl:1
	s_nop 1
	v_add_f32_dpp v88, v88, v88 row_half_mirror row_mask:0xf bank_mask:0xf bound_ctrl:1
	s_nop 1
	v_add_f32_dpp v88, v88, v88 row_mirror row_mask:0xf bank_mask:0xf bound_ctrl:1
	s_waitcnt lgkmcnt(8)
	v_mul_f32_e32 v88, v110, v88
	v_fmac_f32_e32 v88, v8, v111
	v_add_f32_e32 v90, v114, v88
	v_pk_mul_f32 v[88:89], v[104:105], v[110:111] op_sel_hi:[1,0]
	ds_write_b32 v68, v90 offset:38400
	v_pk_fma_f32 v[104:105], v[22:23], v[8:9], v[88:89] op_sel_hi:[1,0,1]
	v_pk_mul_f32 v[22:23], v[106:107], v[110:111] op_sel_hi:[1,0]
	v_pk_fma_f32 v[106:107], v[24:25], v[8:9], v[22:23] op_sel_hi:[1,0,1]
	v_pk_mul_f32 v[22:23], v[108:109], v[110:111] op_sel_hi:[1,0]
	v_pk_fma_f32 v[108:109], v[38:39], v[8:9], v[22:23] op_sel_hi:[1,0,1]
	v_pk_mul_f32 v[22:23], v[46:47], v[110:111] op_sel_hi:[1,0]
	v_pk_fma_f32 v[46:47], v[40:41], v[8:9], v[22:23] op_sel_hi:[1,0,1]
	ds_read_b128 v[22:25], v59 offset:22784
	ds_read_b128 v[38:41], v59 offset:22800
	s_waitcnt lgkmcnt(6)
	v_pk_mul_f32 v[94:95], v[106:107], v[94:95]
	ds_read_b128 v[88:91], v59 offset:30976
	v_pk_fma_f32 v[92:93], v[104:105], v[92:93], v[94:95]
	v_pk_mul_f32 v[94:95], v[46:47], v[102:103]
	ds_read_b128 v[96:99], v59 offset:30992
	v_pk_fma_f32 v[94:95], v[108:109], v[100:101], v[94:95]
	ds_read_b32 v8, v60 offset:35584
	v_pk_add_f32 v[92:93], v[92:93], v[94:95]
	ds_read_b32 v114, v60 offset:36608
	v_add_f32_e32 v92, v92, v93
	ds_read_b64 v[110:111], v157 offset:37248
	s_nop 0
	v_add_f32_dpp v92, v92, v92 quad_perm:[1,0,3,2] row_mask:0xf bank_mask:0xf bound_ctrl:1
	s_nop 1
	v_add_f32_dpp v92, v92, v92 quad_perm:[2,3,0,1] row_mask:0xf bank_mask:0xf bound_ctrl:1
	s_nop 1
	v_add_f32_dpp v92, v92, v92 row_half_mirror row_mask:0xf bank_mask:0xf bound_ctrl:1
	s_nop 1
	v_add_f32_dpp v92, v92, v92 row_mirror row_mask:0xf bank_mask:0xf bound_ctrl:1
	s_waitcnt lgkmcnt(8)
; DI float row16_sum(float v) { v += dppf(v, 0); v += dppf(v, 1); v += dppf(v, 2); v += dppf(v, 3); return v; }
; DI void mamba_scan(CP p, const Ptrs& w, int l, int item, float* sm) {
;     ...
;   auto run_chunk = [&](int c, const float* bf, float* sy) {
;     flush(max(c - 1, 0));
;     MStep cur = lds_step(bf, 0);
; #pragma unroll
;     for (int j = 0; j < 16; ++j) {
;       MStep nxt = cur;
;       if (j + 1 < 16) nxt = lds_step(bf, j + 1);
;       f2v ya = M0 * cur.C0.xy + M1 * cur.C0.zw, yb = M2 * cur.C1.xy + M3 * cur.C1.zw;
;       ya += yb;
;       float yp = row16_sum(ya.x + ya.y);
;       float y = cur.sc.x * yp + cur.xq * cur.sc.y + cur.ds;
;       const float dA = cur.sc.x, xq = cur.xq;
;       M0 = M0 * dA + xq * cur.B0.xy; M1 = M1 * dA + xq * cur.B0.zw;
;       M2 = M2 * dA + xq * cur.B1.xy; M3 = M3 * dA + xq * cur.B1.zw;
;       sy[(ng == 0 ? j * 16 : 0) + ysel] = y;
;       cur = nxt;
;     }
	v_mul_f32_e32 v92, v112, v92
	v_fmac_f32_e32 v92, v16, v113
	v_add_f32_e32 v94, v115, v92
	v_pk_mul_f32 v[92:93], v[104:105], v[112:113] op_sel_hi:[1,0]
	ds_write_b32 v70, v94 offset:38400
	v_pk_fma_f32 v[104:105], v[26:27], v[16:17], v[92:93] op_sel_hi:[1,0,1]
	v_pk_mul_f32 v[26:27], v[106:107], v[112:113] op_sel_hi:[1,0]
	v_pk_fma_f32 v[106:107], v[28:29], v[16:17], v[26:27] op_sel_hi:[1,0,1]
	v_pk_mul_f32 v[26:27], v[108:109], v[112:113] op_sel_hi:[1,0]
	v_pk_fma_f32 v[108:109], v[42:43], v[16:17], v[26:27] op_sel_hi:[1,0,1]
	v_pk_mul_f32 v[26:27], v[46:47], v[112:113] op_sel_hi:[1,0]
	v_pk_fma_f32 v[46:47], v[44:45], v[16:17], v[26:27] op_sel_hi:[1,0,1]
	ds_read_b128 v[26:29], v59 offset:23296
	ds_read_b128 v[42:45], v59 offset:23312
	ds_read_b128 v[92:95], v59 offset:31488
	ds_read_b128 v[100:103], v59 offset:31504
	ds_read_b32 v16, v60 offset:35648
	ds_read_b32 v115, v60 offset:36672
	s_waitcnt lgkmcnt(14)
	ds_read_b64 v[112:113], v157 offset:37264
	s_waitcnt lgkmcnt(10)
	v_pk_mul_f32 v[90:91], v[106:107], v[90:91]
	v_pk_fma_f32 v[88:89], v[104:105], v[88:89], v[90:91]
	v_pk_mul_f32 v[90:91], v[46:47], v[98:99]
	v_pk_fma_f32 v[90:91], v[108:109], v[96:97], v[90:91]
	v_pk_add_f32 v[88:89], v[88:89], v[90:91]
	v_add_f32_e32 v88, v88, v89
	s_nop 1
	v_add_f32_dpp v88, v88, v88 quad_perm:[1,0,3,2] row_mask:0xf bank_mask:0xf bound_ctrl:1
	s_nop 1
	v_add_f32_dpp v88, v88, v88 quad_perm:[2,3,0,1] row_mask:0xf bank_mask:0xf bound_ctrl:1
	s_nop 1
	v_add_f32_dpp v88, v88, v88 row_half_mirror row_mask:0xf bank_mask:0xf bound_ctrl:1
	s_nop 1
	v_add_f32_dpp v88, v88, v88 row_mirror row_mask:0xf bank_mask:0xf bound_ctrl:1
	s_waitcnt lgkmcnt(8)
	v_mul_f32_e32 v88, v110, v88
	v_fmac_f32_e32 v88, v8, v111
	v_add_f32_e32 v90, v114, v88
	v_pk_mul_f32 v[88:89], v[104:105], v[110:111] op_sel_hi:[1,0]
	ds_write_b32 v71, v90 offset:38400
	v_pk_fma_f32 v[104:105], v[22:23], v[8:9], v[88:89] op_sel_hi:[1,0,1]
	v_pk_mul_f32 v[22:23], v[106:107], v[110:111] op_sel_hi:[1,0]
	v_pk_fma_f32 v[106:107], v[24:25], v[8:9], v[22:23] op_sel_hi:[1,0,1]
	v_pk_mul_f32 v[22:23], v[108:109], v[110:111] op_sel_hi:[1,0]
	v_pk_fma_f32 v[108:109], v[38:39], v[8:9], v[22:23] op_sel_hi:[1,0,1]
	v_pk_mul_f32 v[22:23], v[46:47], v[110:111] op_sel_hi:[1,0]
	v_pk_fma_f32 v[46:47], v[40:41], v[8:9], v[22:23] op_sel_hi:[1,0,1]
	ds_read_b128 v[22:25], v59 offset:23808
	ds_read_b128 v[38:41], v59 offset:23824
	ds_read_b128 v[88:91], v59 offset:32000
	s_waitcnt lgkmcnt(6)
	v_pk_mul_f32 v[94:95], v[106:107], v[94:95]
	ds_read_b128 v[96:99], v59 offset:32016
	v_pk_fma_f32 v[92:93], v[104:105], v[92:93], v[94:95]
	v_pk_mul_f32 v[94:95], v[46:47], v[102:103]
	ds_read_b32 v8, v60 offset:35712
	v_pk_fma_f32 v[94:95], v[108:109], v[100:101], v[94:95]
	ds_read_b32 v114, v60 offset:36736
	v_pk_add_f32 v[92:93], v[92:93], v[94:95]
	ds_read_b64 v[110:111], v157 offset:37280
	v_add_f32_e32 v92, v92, v93
	s_nop 1
	v_add_f32_dpp v92, v92, v92 quad_perm:[1,0,3,2] row_mask:0xf bank_mask:0xf bound_ctrl:1
	s_nop 1
	v_add_f32_dpp v92, v92, v92 quad_perm:[2,3,0,1] row_mask:0xf bank_mask:0xf bound_ctrl:1
	s_nop 1
	v_add_f32_dpp v92, v92, v92 row_half_mirror row_mask:0xf bank_mask:0xf bound_ctrl:1
	s_nop 1
	v_add_f32_dpp v92, v92, v92 row_mirror row_mask:0xf bank_mask:0xf bound_ctrl:1
	s_waitcnt lgkmcnt(8)
	v_mul_f32_e32 v92, v112, v92
	v_fmac_f32_e32 v92, v16, v113
	v_add_f32_e32 v94, v115, v92
	v_pk_mul_f32 v[92:93], v[104:105], v[112:113] op_sel_hi:[1,0]
	ds_write_b32 v73, v94 offset:38400
	v_pk_fma_f32 v[104:105], v[26:27], v[16:17], v[92:93] op_sel_hi:[1,0,1]
	v_pk_mul_f32 v[26:27], v[106:107], v[112:113] op_sel_hi:[1,0]
	v_pk_fma_f32 v[106:107], v[28:29], v[16:17], v[26:27] op_sel_hi:[1,0,1]
	v_pk_mul_f32 v[26:27], v[108:109], v[112:113] op_sel_hi:[1,0]
	v_pk_fma_f32 v[108:109], v[42:43], v[16:17], v[26:27] op_sel_hi:[1,0,1]
	v_pk_mul_f32 v[26:27], v[46:47], v[112:113] op_sel_hi:[1,0]
	v_pk_fma_f32 v[46:47], v[44:45], v[16:17], v[26:27] op_sel_hi:[1,0,1]
	ds_read_b128 v[26:29], v59 offset:24320
	ds_read_b128 v[42:45], v59 offset:24336
	ds_read_b128 v[92:95], v59 offset:32512
	ds_read_b128 v[100:103], v59 offset:32528
	ds_read_b32 v16, v60 offset:35776
	ds_read_b32 v115, v60 offset:36800
	s_waitcnt lgkmcnt(9)
	v_pk_mul_f32 v[90:91], v[106:107], v[90:91]
	ds_read_b64 v[112:113], v157 offset:37296
	v_pk_fma_f32 v[88:89], v[104:105], v[88:89], v[90:91]
	v_pk_mul_f32 v[90:91], v[46:47], v[98:99]
	v_pk_fma_f32 v[90:91], v[108:109], v[96:97], v[90:91]
	v_pk_add_f32 v[88:89], v[88:89], v[90:91]
	v_add_f32_e32 v88, v88, v89
	s_nop 1
	v_add_f32_dpp v88, v88, v88 quad_perm:[1,0,3,2] row_mask:0xf bank_mask:0xf bound_ctrl:1
	s_nop 1
	v_add_f32_dpp v88, v88, v88 quad_perm:[2,3,0,1] row_mask:0xf bank_mask:0xf bound_ctrl:1
	s_nop 1
	v_add_f32_dpp v88, v88, v88 row_half_mirror row_mask:0xf bank_mask:0xf bound_ctrl:1
	s_nop 1
	v_add_f32_dpp v88, v88, v88 row_mirror row_mask:0xf bank_mask:0xf bound_ctrl:1
	s_waitcnt lgkmcnt(8)
	v_mul_f32_e32 v88, v110, v88
	v_fmac_f32_e32 v88, v8, v111
	v_add_f32_e32 v90, v114, v88
	v_pk_mul_f32 v[88:89], v[104:105], v[110:111] op_sel_hi:[1,0]
	ds_write_b32 v74, v90 offset:38400
	v_pk_fma_f32 v[104:105], v[22:23], v[8:9], v[88:89] op_sel_hi:[1,0,1]
	v_pk_mul_f32 v[22:23], v[106:107], v[110:111] op_sel_hi:[1,0]
	v_pk_fma_f32 v[106:107], v[24:25], v[8:9], v[22:23] op_sel_hi:[1,0,1]
	v_pk_mul_f32 v[22:23], v[108:109], v[110:111] op_sel_hi:[1,0]
	v_pk_fma_f32 v[108:109], v[38:39], v[8:9], v[22:23] op_sel_hi:[1,0,1]
	v_pk_mul_f32 v[22:23], v[46:47], v[110:111] op_sel_hi:[1,0]
	v_pk_fma_f32 v[46:47], v[40:41], v[8:9], v[22:23] op_sel_hi:[1,0,1]
	ds_read_b128 v[22:25], v59 offset:24832
	ds_read_b128 v[38:41], v59 offset:24848
	ds_read_b128 v[88:91], v59 offset:33024
	ds_read_b128 v[96:99], v59 offset:33040
	s_waitcnt lgkmcnt(6)
; DI float row16_sum(float v) { v += dppf(v, 0); v += dppf(v, 1); v += dppf(v, 2); v += dppf(v, 3); return v; }
; DI void mamba_scan(CP p, const Ptrs& w, int l, int item, float* sm) {
;     ...
;   auto run_chunk = [&](int c, const float* bf, float* sy) {
;     flush(max(c - 1, 0));
;     MStep cur = lds_step(bf, 0);
; #pragma unroll
;     for (int j = 0; j < 16; ++j) {
;       MStep nxt = cur;
;       if (j + 1 < 16) nxt = lds_step(bf, j + 1);
;       f2v ya = M0 * cur.C0.xy + M1 * cur.C0.zw, yb = M2 * cur.C1.xy + M3 * cur.C1.zw;
;       ya += yb;
;       float yp = row16_sum(ya.x + ya.y);
;       float y = cur.sc.x * yp + cur.xq * cur.sc.y + cur.ds;
;       const float dA = cur.sc.x, xq = cur.xq;
;       M0 = M0 * dA + xq * cur.B0.xy; M1 = M1 * dA + xq * cur.B0.zw;
;       M2 = M2 * dA + xq * cur.B1.xy; M3 = M3 * dA + xq * cur.B1.zw;
;       sy[(ng == 0 ? j * 16 : 0) + ysel] = y;
;       cur = nxt;
;     }
	v_pk_mul_f32 v[94:95], v[106:107], v[94:95]
	ds_read_b32 v8, v60 offset:35840
	v_pk_fma_f32 v[92:93], v[104:105], v[92:93], v[94:95]
	v_pk_mul_f32 v[94:95], v[46:47], v[102:103]
	ds_read_b32 v114, v60 offset:36864
	v_pk_fma_f32 v[94:95], v[108:109], v[100:101], v[94:95]
	ds_read_b64 v[110:111], v157 offset:37312
	v_pk_add_f32 v[92:93], v[92:93], v[94:95]
	v_add_f32_e32 v92, v92, v93
	s_nop 1
	v_add_f32_dpp v92, v92, v92 quad_perm:[1,0,3,2] row_mask:0xf bank_mask:0xf bound_ctrl:1
	s_nop 1
	v_add_f32_dpp v92, v92, v92 quad_perm:[2,3,0,1] row_mask:0xf bank_mask:0xf bound_ctrl:1
	s_nop 1
	v_add_f32_dpp v92, v92, v92 row_half_mirror row_mask:0xf bank_mask:0xf bound_ctrl:1
	s_nop 1
	v_add_f32_dpp v92, v92, v92 row_mirror row_mask:0xf bank_mask:0xf bound_ctrl:1
	s_waitcnt lgkmcnt(8)
	v_mul_f32_e32 v92, v112, v92
	v_fmac_f32_e32 v92, v16, v113
	v_add_f32_e32 v94, v115, v92
	v_pk_mul_f32 v[92:93], v[104:105], v[112:113] op_sel_hi:[1,0]
	ds_write_b32 v75, v94 offset:38400
	v_pk_fma_f32 v[104:105], v[26:27], v[16:17], v[92:93] op_sel_hi:[1,0,1]
	v_pk_mul_f32 v[26:27], v[106:107], v[112:113] op_sel_hi:[1,0]
	v_pk_fma_f32 v[106:107], v[28:29], v[16:17], v[26:27] op_sel_hi:[1,0,1]
	v_pk_mul_f32 v[26:27], v[108:109], v[112:113] op_sel_hi:[1,0]
	v_pk_fma_f32 v[108:109], v[42:43], v[16:17], v[26:27] op_sel_hi:[1,0,1]
	v_pk_mul_f32 v[26:27], v[46:47], v[112:113] op_sel_hi:[1,0]
	v_pk_fma_f32 v[46:47], v[44:45], v[16:17], v[26:27] op_sel_hi:[1,0,1]
	ds_read_b128 v[26:29], v59 offset:25344
	ds_read_b128 v[42:45], v59 offset:25360
	ds_read_b128 v[92:95], v59 offset:33536
	ds_read_b128 v[100:103], v59 offset:33552
	ds_read_b32 v16, v60 offset:35904
	ds_read_b32 v116, v60 offset:36928
	s_waitcnt lgkmcnt(9)
	v_pk_mul_f32 v[90:91], v[106:107], v[90:91]
	ds_read_b64 v[112:113], v157 offset:37328
	v_pk_fma_f32 v[88:89], v[104:105], v[88:89], v[90:91]
	v_pk_mul_f32 v[90:91], v[46:47], v[98:99]
	v_pk_fma_f32 v[90:91], v[108:109], v[96:97], v[90:91]
	v_pk_add_f32 v[88:89], v[88:89], v[90:91]
	s_waitcnt lgkmcnt(8)
	v_pk_mul_f32 v[46:47], v[46:47], v[110:111] op_sel_hi:[1,0]
	v_add_f32_e32 v88, v88, v89
	v_pk_fma_f32 v[40:41], v[40:41], v[8:9], v[46:47] op_sel_hi:[1,0,1]
	s_nop 0
	v_add_f32_dpp v88, v88, v88 quad_perm:[1,0,3,2] row_mask:0xf bank_mask:0xf bound_ctrl:1
	s_nop 1
	v_add_f32_dpp v88, v88, v88 quad_perm:[2,3,0,1] row_mask:0xf bank_mask:0xf bound_ctrl:1
	s_nop 1
	v_add_f32_dpp v88, v88, v88 row_half_mirror row_mask:0xf bank_mask:0xf bound_ctrl:1
	s_nop 1
	v_add_f32_dpp v88, v88, v88 row_mirror row_mask:0xf bank_mask:0xf bound_ctrl:1
	v_mul_f32_e32 v88, v110, v88
	v_fmac_f32_e32 v88, v8, v111
	v_add_f32_e32 v90, v114, v88
	v_pk_mul_f32 v[88:89], v[104:105], v[110:111] op_sel_hi:[1,0]
	ds_write_b32 v76, v90 offset:38400
	v_pk_fma_f32 v[22:23], v[22:23], v[8:9], v[88:89] op_sel_hi:[1,0,1]
	v_pk_mul_f32 v[88:89], v[106:107], v[110:111] op_sel_hi:[1,0]
	v_pk_fma_f32 v[24:25], v[24:25], v[8:9], v[88:89] op_sel_hi:[1,0,1]
	v_pk_mul_f32 v[88:89], v[108:109], v[110:111] op_sel_hi:[1,0]
	v_pk_fma_f32 v[38:39], v[38:39], v[8:9], v[88:89] op_sel_hi:[1,0,1]
	ds_read_b128 v[88:91], v59 offset:25856
	ds_read_b128 v[96:99], v59 offset:25872
	ds_read_b128 v[104:107], v59 offset:34048
	ds_read_b128 v[108:111], v59 offset:34064
	ds_read_b32 v46, v60 offset:35968
	ds_read_b32 v47, v60 offset:36992
	s_waitcnt lgkmcnt(7)
	v_pk_mul_f32 v[94:95], v[24:25], v[94:95]
	ds_read_b64 v[114:115], v157 offset:37344
	v_pk_fma_f32 v[92:93], v[22:23], v[92:93], v[94:95]
	v_pk_mul_f32 v[94:95], v[40:41], v[102:103]
	v_pk_fma_f32 v[94:95], v[38:39], v[100:101], v[94:95]
	v_pk_mul_f32 v[22:23], v[22:23], v[112:113] op_sel_hi:[1,0]
	v_pk_add_f32 v[92:93], v[92:93], v[94:95]
	v_add_f32_e32 v8, v92, v93
	s_nop 1
	v_add_f32_dpp v8, v8, v8 quad_perm:[1,0,3,2] row_mask:0xf bank_mask:0xf bound_ctrl:1
	s_nop 1
	v_add_f32_dpp v8, v8, v8 quad_perm:[2,3,0,1] row_mask:0xf bank_mask:0xf bound_ctrl:1
	s_nop 1
	v_add_f32_dpp v8, v8, v8 row_half_mirror row_mask:0xf bank_mask:0xf bound_ctrl:1
	s_nop 1
	v_add_f32_dpp v8, v8, v8 row_mirror row_mask:0xf bank_mask:0xf bound_ctrl:1
	v_mul_f32_e32 v8, v112, v8
	v_fmac_f32_e32 v8, v16, v113
	v_add_f32_e32 v8, v116, v8
	v_pk_fma_f32 v[116:117], v[26:27], v[16:17], v[22:23] op_sel_hi:[1,0,1]
	v_pk_mul_f32 v[22:23], v[24:25], v[112:113] op_sel_hi:[1,0]
	ds_write_b32 v77, v8 offset:38400
	v_pk_fma_f32 v[118:119], v[28:29], v[16:17], v[22:23] op_sel_hi:[1,0,1]
	v_pk_mul_f32 v[22:23], v[38:39], v[112:113] op_sel_hi:[1,0]
	ds_read_b128 v[26:29], v59 offset:26368
	v_pk_fma_f32 v[120:121], v[42:43], v[16:17], v[22:23] op_sel_hi:[1,0,1]
	v_pk_mul_f32 v[22:23], v[40:41], v[112:113] op_sel_hi:[1,0]
	v_pk_fma_f32 v[112:113], v[44:45], v[16:17], v[22:23] op_sel_hi:[1,0,1]
	ds_read_b128 v[22:25], v59 offset:26384
	ds_read_b128 v[92:95], v59 offset:34560
	ds_read_b128 v[100:103], v59 offset:34576
	ds_read_b32 v8, v60 offset:36032
	ds_read_b32 v16, v60 offset:37056
	s_waitcnt lgkmcnt(7)
; DI float bf2f(bf16_t h) { return __uint_as_float(((unsigned)h) << 16); }
; DI float siluf(float x) { return x * sigmf(x); }
; DI float row16_sum(float v) { v += dppf(v, 0); v += dppf(v, 1); v += dppf(v, 2); v += dppf(v, 3); return v; }
; DI void mamba_scan(CP p, const Ptrs& w, int l, int item, float* sm) {
;     ...
;   auto stage = [&](const MPre& P, float* bufp) {
; #pragma unroll
;     for (int i = 0; i < 2; ++i) {
;       int idx = tid + 256 * i, j = idx >> 5, q = idx & 31;
;       float f[8];
;       unpack8(P.pbq[i], f);
;       float* d = bufp + (q < 16 ? 0 : 2048) + j * 128 + (q & 15) * 8;
;       *(float4*)d = make_float4(f[0], f[1], f[2], f[3]);
;       *(float4*)(d + 4) = make_float4(f[4], f[5], f[6], f[7]);
;     }
;     {
;       float xs = siluf(wX0 * P.pxm[0] * bf2f(P.px[0]) + wX1 * bf2f(P.px[1]) + wX2 * P.pxm[1] * bf2f(P.px[2]) + bX);
;       bufp[4096 + xj * 16 + xp] = xs * P.pdt[0];
;       bufp[4096 + 256 + xj * 16 + xp] = Dsk * xs;
;       if (xp == 0) *(float4*)(bufp + 4096 + 512 + xj * 4) = make_float4(P.pdt[1], P.pdt[2], 0.f, 0.f);
;     }
;   };
;     ...
;   auto run_chunk = [&](int c, const float* bf, float* sy) {
;     flush(max(c - 1, 0));
;     MStep cur = lds_step(bf, 0);
; #pragma unroll
;     for (int j = 0; j < 16; ++j) {
;       MStep nxt = cur;
;       if (j + 1 < 16) nxt = lds_step(bf, j + 1);
;       f2v ya = M0 * cur.C0.xy + M1 * cur.C0.zw, yb = M2 * cur.C1.xy + M3 * cur.C1.zw;
;       ya += yb;
;       float yp = row16_sum(ya.x + ya.y);
;       float y = cur.sc.x * yp + cur.xq * cur.sc.y + cur.ds;
;       const float dA = cur.sc.x, xq = cur.xq;
;       M0 = M0 * dA + xq * cur.B0.xy; M1 = M1 * dA + xq * cur.B0.zw;
;       M2 = M2 * dA + xq * cur.B1.xy; M3 = M3 * dA + xq * cur.B1.zw;
;       sy[(ng == 0 ? j * 16 : 0) + ysel] = y;
;       cur = nxt;
;     }
	v_pk_mul_f32 v[40:41], v[118:119], v[106:107]
	ds_read_b64 v[38:39], v157 offset:37360
	v_pk_mul_f32 v[42:43], v[112:113], v[110:111]
	v_pk_fma_f32 v[40:41], v[116:117], v[104:105], v[40:41]
	v_pk_fma_f32 v[42:43], v[120:121], v[108:109], v[42:43]
	v_pk_add_f32 v[40:41], v[40:41], v[42:43]
	v_add_f32_e32 v40, v40, v41
	s_nop 1
	v_add_f32_dpp v40, v40, v40 quad_perm:[1,0,3,2] row_mask:0xf bank_mask:0xf bound_ctrl:1
	s_nop 1
	v_add_f32_dpp v40, v40, v40 quad_perm:[2,3,0,1] row_mask:0xf bank_mask:0xf bound_ctrl:1
	s_nop 1
	v_add_f32_dpp v40, v40, v40 row_half_mirror row_mask:0xf bank_mask:0xf bound_ctrl:1
	s_nop 1
	v_add_f32_dpp v40, v40, v40 row_mirror row_mask:0xf bank_mask:0xf bound_ctrl:1
	v_mul_f32_e32 v40, v114, v40
	v_fmac_f32_e32 v40, v46, v115
	v_add_f32_e32 v104, v47, v40
	v_pk_mul_f32 v[40:41], v[116:117], v[114:115] op_sel_hi:[1,0]
	ds_write_b32 v78, v104 offset:38400
	v_pk_fma_f32 v[42:43], v[88:89], v[46:47], v[40:41] op_sel_hi:[1,0,1]
	v_pk_mul_f32 v[40:41], v[118:119], v[114:115] op_sel_hi:[1,0]
	v_pk_mul_f32 v[88:89], v[112:113], v[114:115] op_sel_hi:[1,0]
	v_pk_fma_f32 v[44:45], v[90:91], v[46:47], v[40:41] op_sel_hi:[1,0,1]
	v_pk_mul_f32 v[40:41], v[120:121], v[114:115] op_sel_hi:[1,0]
	v_pk_fma_f32 v[40:41], v[96:97], v[46:47], v[40:41] op_sel_hi:[1,0,1]
	v_pk_fma_f32 v[46:47], v[98:99], v[46:47], v[88:89] op_sel_hi:[1,0,1]
	s_waitcnt lgkmcnt(5)
	v_pk_mul_f32 v[88:89], v[44:45], v[94:95]
	s_waitcnt lgkmcnt(4)
	v_pk_mul_f32 v[90:91], v[46:47], v[102:103]
	v_pk_fma_f32 v[88:89], v[42:43], v[92:93], v[88:89]
	v_pk_fma_f32 v[90:91], v[40:41], v[100:101], v[90:91]
	s_waitcnt vmcnt(8)
	v_lshlrev_b32_e32 v94, 16, v21
	v_pk_add_f32 v[88:89], v[88:89], v[90:91]
	v_and_b32_e32 v95, 0xffff0000, v21
	v_add_f32_e32 v88, v88, v89
	v_lshlrev_b32_e32 v21, 16, v85
	v_lshlrev_b32_e32 v90, 16, v19
	v_add_f32_dpp v88, v88, v88 quad_perm:[1,0,3,2] row_mask:0xf bank_mask:0xf bound_ctrl:1
	v_and_b32_e32 v91, 0xffff0000, v19
	v_lshlrev_b32_e32 v19, 16, v84
	v_add_f32_dpp v88, v88, v88 quad_perm:[2,3,0,1] row_mask:0xf bank_mask:0xf bound_ctrl:1
	v_mul_f32_e32 v21, v50, v21
	v_and_b32_e32 v89, 0xffff0000, v18
	v_add_f32_dpp v88, v88, v88 row_half_mirror row_mask:0xf bank_mask:0xf bound_ctrl:1
	v_lshlrev_b32_e32 v92, 16, v20
	v_and_b32_e32 v93, 0xffff0000, v20
	v_add_f32_dpp v88, v88, v88 row_mirror row_mask:0xf bank_mask:0xf bound_ctrl:1
	s_waitcnt lgkmcnt(1)
	v_mul_f32_e32 v88, v38, v88
	v_fmac_f32_e32 v88, v8, v39
	v_add_f32_e32 v16, v16, v88
	ds_write_b32 v80, v16 offset:38400
	v_mul_f32_e32 v16, v49, v87
	v_fmac_f32_e32 v21, v16, v19
	v_mul_f32_e32 v16, v51, v86
	v_lshlrev_b32_e32 v19, 16, v83
	v_fmac_f32_e32 v21, v16, v19
	v_add_f32_e32 v16, v52, v21
	v_mul_f32_e32 v19, 0xbfb8aa3b, v16
	v_exp_f32_e32 v39, v19
	v_lshlrev_b32_e32 v88, 16, v18
	v_lshlrev_b32_e32 v18, 16, v12
	v_and_b32_e32 v19, 0xffff0000, v12
	v_add_f32_e32 v12, 1.0, v39
	v_rcp_f32_e32 v12, v12
	ds_write_b128 v58, v[92:95] offset:16
	ds_write_b128 v58, v[88:91]
	v_lshlrev_b32_e32 v20, 16, v13
	v_lshlrev_b32_e32 v90, 16, v15
	v_mul_f32_e32 v12, v16, v12
	v_lshlrev_b32_e32 v88, 16, v14
	v_and_b32_e32 v21, 0xffff0000, v13
	v_and_b32_e32 v91, 0xffff0000, v15
	v_and_b32_e32 v89, 0xffff0000, v14
	v_mul_f32_e32 v13, v36, v12
	v_mul_f32_e32 v12, v53, v12
	ds_write_b128 v58, v[88:91] offset:4112
	ds_write_b128 v58, v[18:21] offset:4096
	ds_write2st64_b32 v57, v13, v12 offset0:64 offset1:68
	s_and_saveexec_b64 s[4:5], vcc
	s_cbranch_execz .LBB0_543
	v_mov_b32_e32 v16, v37
	v_mov_b32_e32 v18, v157
	v_mov_b32_e32 v19, v157
	ds_write_b128 v72, v[16:19] offset:18432
	s_branch .LBB0_543

; DI float row16_sum(float v) { v += dppf(v, 0); v += dppf(v, 1); v += dppf(v, 2); v += dppf(v, 3); return v; }
; DI void rwkv_scan(CP p, const Ptrs& w, int l, int item, float* sm) {
;     ...
;   auto load = [&](int c, RPre& P) {
;     int ii = pos2i(c * 16 + sj, dir);
;     size_t tok = (size_t)b * TPB + ii;
;     const bf16_t* prow = w.pB + tok * SPB + sc_;
;     bool hp = (ii != 0) && (ii != CTXL), hn = (ii != CTXL - 1) && (ii != TPB - 1);
;     const int op = hp ? -SPB : 0, on = hn ? SPB : 0;
;     P.pmk[0] = hp ? 0.5f : 0.f; P.pmk[1] = hn ? 0.5f : 0.f;
; #pragma unroll
;     for (int q = 0; q < 3; ++q) {
;       P.pq[q][0] = *(const uint2*)(prow + q * 512);
;       P.pq[q][1] = *(const uint2*)(prow + q * 512 + op);
;       P.pq[q][2] = *(const uint2*)(prow + q * 512 + on);
;     }
;     P.pwd = *(const uint2*)(Wd + tok * 512 + sc_);
;     P.pad_ = *(const uint2*)(Ad + tok * 512 + sc_);
;     const float* sc = w.bonus + (tok * 8 + hd) * 8;
;     P.psc[0] = sc[0]; P.psc[1] = sc[1 + 3 * dir]; P.psc[2] = sc[2 + 3 * dir];
;   };
;     ...
;   auto run_chunk = [&](int c, const float* bf, float* sy) {
;     flush(max(c - 1, 0));
;     RStep cur = lds_step(bf, 0);
; #pragma unroll
;     for (int j = 0; j < 16; ++j) {
;       RStep nxt = cur;
;       if (j + 1 < 16) nxt = lds_step(bf, j + 1);
;       f2v sa2 = SA * cur.a4.xy + SB * cur.a4.zw;
;       f2v yp2 = SA * cur.wr4.xy + SB * cur.wr4.zw;
;       float sa = sa2.x + sa2.y, yp = yp2.x + yp2.y;
;       sa = row16_sum(sa); yp = row16_sum(yp);
;       float y = yp + sa * cur.sc.x + cur.vv * cur.sc.y;
;       SA = SA * cur.w4.xy + (sa * cur.b4.xy + cur.vv * cur.k4.xy);
;       SB = SB * cur.w4.zw + (sa * cur.b4.zw + cur.vv * cur.k4.zw);
;       sy[(kg == 0 ? j * 16 : 0) + ysel - (c & 1) * 0] = y;
;       cur = nxt;
;     }
;   };
.LBB0_554:
	s_waitcnt lgkmcnt(0)
	s_min_u32 s4, s38, 1
	s_lshl_b32 s5, s4, 8
	s_lshl_b32 s46, s4, 4
	s_add_i32 s4, s17, 4
	s_min_u32 s4, s4, 0x20f
	v_lshl_add_u32 v168, s4, 4, v97
	s_sub_i32 s39, s16, s5
	v_add_u32_e64 v146, s21, 0
	v_cmp_lt_i32_e64 s[4:5], s37, v168
	ds_read2st64_b32 v[154:155], v106 offset0:80 offset1:81
	ds_read2_b64 v[24:27], v146 offset1:1
	v_cndmask_b32_e64 v169, v231, v232, s[4:5]
	ds_read_b128 v[28:31], v105
	v_sub_u32_e32 v169, v169, v168
	ds_read_b128 v[98:101], v105 offset:256
	v_cndmask_b32_e32 v168, v169, v168, vcc
	ds_read_b128 v[126:129], v105 offset:4096
	v_ashrrev_i32_e32 v169, 31, v168
	ds_read_b128 v[130:133], v105 offset:4352
	v_lshl_add_u64 v[170:171], s[12:13], 0, v[168:169]
	v_and_b32_e32 v169, 0xfffffeff, v168
	ds_read_b128 v[134:137], v105 offset:8192
	v_mad_u64_u32 v[150:151], s[4:5], v170, s20, v[42:43]
	v_cmp_eq_u32_e64 s[42:43], 0, v169
	ds_read_b128 v[138:141], v105 offset:8448
	v_mov_b32_e32 v152, v151
	v_cndmask_b32_e64 v169, -1, 0, s[42:43]
	ds_read_b128 v[142:145], v105 offset:12288
	v_mad_u64_u32 v[152:153], s[4:5], v171, s20, v[152:153]
	s_and_b32 s4, s39, 0x100
	ds_read_b128 v[146:149], v105 offset:12544
	v_mov_b32_e32 v151, v152
	v_and_b32_e32 v152, 0xffffdfff, v168
	v_cndmask_b32_e64 v168, v236, 0, s[42:43]
	global_load_dwordx2 v[88:89], v[150:151], off
	global_load_dwordx2 v[86:87], v[150:151], off offset:1024
	global_load_dwordx2 v[84:85], v[150:151], off offset:2048
	v_lshl_add_u64 v[168:169], v[150:151], 0, v[168:169]
	v_cmp_eq_u32_e64 s[44:45], s37, v152
	global_load_dwordx2 v[74:75], v[168:169], off
	s_waitcnt lgkmcnt(7)
	v_pk_mul_f32 v[30:31], v[22:23], v[30:31]
	v_cndmask_b32_e64 v156, v237, 0, s[44:45]
	v_pk_fma_f32 v[28:29], v[20:21], v[28:29], v[30:31]
	v_lshl_add_u64 v[152:153], v[150:151], 0, v[156:157]
	v_add_f32_e32 v28, v28, v29
	global_load_dwordx2 v[76:77], v[152:153], off
	global_load_dwordx2 v[78:79], v[168:169], off offset:1024
	global_load_dwordx2 v[70:71], v[168:169], off offset:2048
	global_load_dwordx2 v[80:81], v[152:153], off offset:1024
	global_load_dwordx2 v[72:73], v[152:153], off offset:2048
	v_lshlrev_b64 v[168:169], 10, v[170:171]
	s_waitcnt lgkmcnt(3)
	v_pk_mul_f32 v[30:31], v[22:23], v[128:129]
	v_add_f32_dpp v28, v28, v28 quad_perm:[1,0,3,2] row_mask:0xf bank_mask:0xf bound_ctrl:1
	v_lshl_add_u64 v[150:151], v[34:35], 0, v[168:169]
	v_lshl_add_u64 v[168:169], v[36:37], 0, v[168:169]
	v_pk_fma_f32 v[30:31], v[20:21], v[126:127], v[30:31]
	global_load_dwordx2 v[92:93], v[150:151], off
	global_load_dwordx2 v[90:91], v[168:169], off
	v_lshlrev_b64 v[168:169], 8, v[170:171]
	ds_read_b128 v[150:153], v105 offset:16384
	v_lshl_add_u64 v[168:169], s[6:7], 0, v[168:169]
	v_add_f32_e32 v29, v30, v31
	v_add_f32_dpp v28, v28, v28 quad_perm:[2,3,0,1] row_mask:0xf bank_mask:0xf bound_ctrl:1
	global_load_dword v82, v[168:169], off
	v_lshl_add_u64 v[170:171], v[168:169], 0, s[90:91]
	v_lshl_add_u32 v169, s4, 2, v83
	v_subrev_u32_e32 v168, s46, v125
	global_load_dwordx2 v[68:69], v[170:171], off offset:4
	ds_read_b32 v169, v169 offset:49408
	v_cmp_lt_i32_e64 s[4:5], s37, v168
	v_add_f32_dpp v29, v29, v29 quad_perm:[1,0,3,2] row_mask:0xf bank_mask:0xf bound_ctrl:1
	v_add_f32_dpp v28, v28, v28 row_half_mirror row_mask:0xf bank_mask:0xf bound_ctrl:1
	v_cndmask_b32_e64 v170, v231, v232, s[4:5]
	v_add_f32_dpp v29, v29, v29 quad_perm:[2,3,0,1] row_mask:0xf bank_mask:0xf bound_ctrl:1
	v_add_f32_dpp v28, v28, v28 row_mirror row_mask:0xf bank_mask:0xf bound_ctrl:1
	v_add3_u32 v170, v170, v124, s46
	v_add_f32_dpp v29, v29, v29 row_half_mirror row_mask:0xf bank_mask:0xf bound_ctrl:1
	v_cndmask_b32_e32 v168, v170, v168, vcc
	s_waitcnt lgkmcnt(0)
	v_cvt_pk_bf16_f32 v170, v169, s0
	v_add_f32_dpp v29, v29, v29 row_mirror row_mask:0xf bank_mask:0xf bound_ctrl:1
	v_fmac_f32_e32 v29, v24, v28
	v_fmac_f32_e32 v29, v154, v25
	v_pk_mul_f32 v[24:25], v[142:143], v[28:29] op_sel_hi:[1,0]
	v_pk_fma_f32 v[24:25], v[150:151], v[154:155], v[24:25] op_sel_hi:[1,0,1]
	v_pk_fma_f32 v[24:25], v[20:21], v[134:135], v[24:25]
	v_pk_mul_f32 v[20:21], v[144:145], v[28:29] op_sel_hi:[1,0]
	v_pk_fma_f32 v[20:21], v[152:153], v[154:155], v[20:21] op_sel_hi:[1,0,1]
	v_pk_fma_f32 v[150:151], v[22:23], v[136:137], v[20:21]
	v_pk_mul_f32 v[100:101], v[100:101], v[150:151]
	v_pk_fma_f32 v[98:99], v[98:99], v[24:25], v[100:101]
	v_pk_mul_f32 v[100:101], v[132:133], v[150:151]
	v_add_f32_e32 v98, v98, v99
	v_ashrrev_i32_e32 v169, 31, v168
	v_pk_fma_f32 v[100:101], v[130:131], v[24:25], v[100:101]
	v_add_f32_dpp v98, v98, v98 quad_perm:[1,0,3,2] row_mask:0xf bank_mask:0xf bound_ctrl:1
	v_lshl_add_u64 v[168:169], s[12:13], 0, v[168:169]
	v_add_f32_e32 v99, v100, v101
	v_add_f32_dpp v98, v98, v98 quad_perm:[2,3,0,1] row_mask:0xf bank_mask:0xf bound_ctrl:1
	v_lshlrev_b64 v[168:169], 10, v[168:169]
	v_add_f32_dpp v99, v99, v99 quad_perm:[1,0,3,2] row_mask:0xf bank_mask:0xf bound_ctrl:1
	v_add_f32_dpp v98, v98, v98 row_half_mirror row_mask:0xf bank_mask:0xf bound_ctrl:1
	v_lshl_add_u64 v[168:169], v[38:39], 0, v[168:169]
	v_add_f32_dpp v99, v99, v99 quad_perm:[2,3,0,1] row_mask:0xf bank_mask:0xf bound_ctrl:1
	v_add_f32_dpp v98, v98, v98 row_mirror row_mask:0xf bank_mask:0xf bound_ctrl:1
	global_store_short v[168:169], v170, off
	ds_read_b128 v[168:171], v105 offset:16640
	ds_write_b32 v107, v29 offset:49408
	ds_read_b128 v[20:23], v105 offset:512
	ds_read_b128 v[28:31], v105 offset:4608
	v_add_f32_dpp v99, v99, v99 row_half_mirror row_mask:0xf bank_mask:0xf bound_ctrl:1
	ds_read_b128 v[126:129], v105 offset:8704
	ds_read_b128 v[134:137], v105 offset:12800
	v_add_f32_dpp v99, v99, v99 row_mirror row_mask:0xf bank_mask:0xf bound_ctrl:1
	ds_read_b128 v[142:145], v105 offset:16896
	v_fmac_f32_e32 v99, v98, v26
	v_mov_b32_e32 v100, v155
	ds_read_b32 v96, v106 offset:20992
	v_fmac_f32_e32 v99, v155, v27
	ds_read_b64 v[152:153], v157 offset:24592
	v_pk_mul_f32 v[26:27], v[146:147], v[98:99] op_sel_hi:[1,0]
	ds_write_b32 v108, v99 offset:49408
	s_waitcnt lgkmcnt(9)
; DI float row16_sum(float v) { v += dppf(v, 0); v += dppf(v, 1); v += dppf(v, 2); v += dppf(v, 3); return v; }
; DI void rwkv_scan(CP p, const Ptrs& w, int l, int item, float* sm) {
;     ...
;   auto lds_step = [&](const float* bf, int j) {
;     RStep q;
;     q.a4 = *(const f4v*)(bf + 0 * 1024 + j * 64 + 4 * kg);
;     q.wr4 = *(const f4v*)(bf + 1 * 1024 + j * 64 + 4 * kg);
;     q.w4 = *(const f4v*)(bf + 2 * 1024 + j * 64 + 4 * kg);
;     q.b4 = *(const f4v*)(bf + 3 * 1024 + j * 64 + 4 * kg);
;     q.k4 = *(const f4v*)(bf + 4 * 1024 + j * 64 + 4 * kg);
;     q.vv = bf[5 * 1024 + j * 64 + row];
;     q.sc = *(const float2*)(bf + 6 * 1024 + j * 2);
;     return q;
;   };
;   auto flush = [&](int c) {
;     {
;       int j = tid >> 4, rr = tid & 15;
;       int ii = pos2i(c * 16 + j, dir);
;       yout[((size_t)b * TPB + ii) * 512 + hd * 64 + rq * 16 + rr] = f2bf(sY[(c & 1) * 256 + j * 16 + rr]);
;     }
;   };
;   __syncthreads();
;   load(0, PA);
;   stage(PA, sm);
;   load(1, PB);
;   __syncthreads();
;   const int NCH = TPB / 16;
;   auto run_chunk = [&](int c, const float* bf, float* sy) {
;     flush(max(c - 1, 0));
;     RStep cur = lds_step(bf, 0);
; #pragma unroll
;     for (int j = 0; j < 16; ++j) {
;       RStep nxt = cur;
;       if (j + 1 < 16) nxt = lds_step(bf, j + 1);
;       f2v sa2 = SA * cur.a4.xy + SB * cur.a4.zw;
;       f2v yp2 = SA * cur.wr4.xy + SB * cur.wr4.zw;
;       float sa = sa2.x + sa2.y, yp = yp2.x + yp2.y;
;       sa = row16_sum(sa); yp = row16_sum(yp);
;       float y = yp + sa * cur.sc.x + cur.vv * cur.sc.y;
;       SA = SA * cur.w4.xy + (sa * cur.b4.xy + cur.vv * cur.k4.xy);
;       SB = SB * cur.w4.zw + (sa * cur.b4.zw + cur.vv * cur.k4.zw);
;       sy[(kg == 0 ? j * 16 : 0) + ysel - (c & 1) * 0] = y;
;       cur = nxt;
;     }
	v_pk_fma_f32 v[26:27], v[168:169], v[100:101], v[26:27] op_sel_hi:[1,0,1]
	v_pk_fma_f32 v[154:155], v[138:139], v[24:25], v[26:27]
	v_pk_mul_f32 v[24:25], v[148:149], v[98:99] op_sel_hi:[1,0]
	v_pk_fma_f32 v[24:25], v[170:171], v[100:101], v[24:25] op_sel_hi:[1,0,1]
	v_pk_fma_f32 v[150:151], v[140:141], v[150:151], v[24:25]
	ds_read_b128 v[24:27], v105 offset:768
	ds_read_b128 v[98:101], v105 offset:4864
	ds_read_b128 v[130:133], v105 offset:8960
	ds_read_b128 v[138:141], v105 offset:13056
	ds_read_b128 v[146:149], v105 offset:17152
	s_waitcnt lgkmcnt(12)
	v_pk_mul_f32 v[22:23], v[22:23], v[150:151]
	ds_read_b32 v102, v106 offset:21248
	v_pk_fma_f32 v[20:21], v[20:21], v[154:155], v[22:23]
	s_waitcnt lgkmcnt(12)
	v_pk_mul_f32 v[22:23], v[30:31], v[150:151]
	ds_read_b64 v[168:169], v157 offset:24600
	v_pk_fma_f32 v[22:23], v[28:29], v[154:155], v[22:23]
	v_add_f32_e32 v20, v20, v21
	v_add_f32_e32 v21, v22, v23
	s_nop 0
	v_add_f32_dpp v20, v20, v20 quad_perm:[1,0,3,2] row_mask:0xf bank_mask:0xf bound_ctrl:1
	v_add_f32_dpp v21, v21, v21 quad_perm:[1,0,3,2] row_mask:0xf bank_mask:0xf bound_ctrl:1
	s_nop 0
	v_add_f32_dpp v20, v20, v20 quad_perm:[2,3,0,1] row_mask:0xf bank_mask:0xf bound_ctrl:1
	v_add_f32_dpp v21, v21, v21 quad_perm:[2,3,0,1] row_mask:0xf bank_mask:0xf bound_ctrl:1
	s_nop 0
	v_add_f32_dpp v20, v20, v20 row_half_mirror row_mask:0xf bank_mask:0xf bound_ctrl:1
	v_add_f32_dpp v21, v21, v21 row_half_mirror row_mask:0xf bank_mask:0xf bound_ctrl:1
	s_nop 0
	v_add_f32_dpp v20, v20, v20 row_mirror row_mask:0xf bank_mask:0xf bound_ctrl:1
	v_add_f32_dpp v28, v21, v21 row_mirror row_mask:0xf bank_mask:0xf bound_ctrl:1
	s_waitcnt lgkmcnt(8)
	v_pk_mul_f32 v[22:23], v[134:135], v[20:21] op_sel_hi:[1,0]
	v_fmac_f32_e32 v28, v20, v152
	v_pk_mul_f32 v[20:21], v[136:137], v[20:21] op_sel_hi:[1,0]
	v_pk_fma_f32 v[22:23], v[142:143], v[96:97], v[22:23] op_sel_hi:[1,0,1]
	v_fmac_f32_e32 v28, v96, v153
	v_pk_fma_f32 v[20:21], v[144:145], v[96:97], v[20:21] op_sel_hi:[1,0,1]
	v_pk_fma_f32 v[152:153], v[126:127], v[154:155], v[22:23]
	ds_write_b32 v109, v28 offset:49408
	v_pk_fma_f32 v[150:151], v[128:129], v[150:151], v[20:21]
	ds_read_b128 v[20:23], v105 offset:1024
	ds_read_b128 v[28:31], v105 offset:5120
	ds_read_b128 v[126:129], v105 offset:9216
	ds_read_b128 v[134:137], v105 offset:13312
	ds_read_b128 v[142:145], v105 offset:17408
	ds_read_b32 v96, v106 offset:21504
	s_waitcnt lgkmcnt(14)
	ds_read_b64 v[154:155], v157 offset:24608
	s_waitcnt lgkmcnt(8)
	v_pk_mul_f32 v[26:27], v[26:27], v[150:151]
	v_pk_fma_f32 v[24:25], v[24:25], v[152:153], v[26:27]
	v_pk_mul_f32 v[26:27], v[100:101], v[150:151]
	v_add_f32_e32 v24, v24, v25
	v_pk_fma_f32 v[26:27], v[98:99], v[152:153], v[26:27]
	v_add_f32_e32 v25, v26, v27
	v_add_f32_dpp v24, v24, v24 quad_perm:[1,0,3,2] row_mask:0xf bank_mask:0xf bound_ctrl:1
	s_nop 0
	v_add_f32_dpp v25, v25, v25 quad_perm:[1,0,3,2] row_mask:0xf bank_mask:0xf bound_ctrl:1
	v_add_f32_dpp v24, v24, v24 quad_perm:[2,3,0,1] row_mask:0xf bank_mask:0xf bound_ctrl:1
	s_nop 0
	v_add_f32_dpp v25, v25, v25 quad_perm:[2,3,0,1] row_mask:0xf bank_mask:0xf bound_ctrl:1
	v_add_f32_dpp v24, v24, v24 row_half_mirror row_mask:0xf bank_mask:0xf bound_ctrl:1
	s_nop 0
	v_add_f32_dpp v25, v25, v25 row_half_mirror row_mask:0xf bank_mask:0xf bound_ctrl:1
	v_add_f32_dpp v24, v24, v24 row_mirror row_mask:0xf bank_mask:0xf bound_ctrl:1
	v_pk_mul_f32 v[26:27], v[138:139], v[24:25] op_sel_hi:[1,0]
	v_add_f32_dpp v98, v25, v25 row_mirror row_mask:0xf bank_mask:0xf bound_ctrl:1
	v_pk_fma_f32 v[26:27], v[146:147], v[102:103], v[26:27] op_sel_hi:[1,0,1]
	v_fmac_f32_e32 v98, v24, v168
	v_pk_mul_f32 v[24:25], v[140:141], v[24:25] op_sel_hi:[1,0]
	v_pk_fma_f32 v[152:153], v[130:131], v[152:153], v[26:27]
	v_fmac_f32_e32 v98, v102, v169
	v_pk_fma_f32 v[24:25], v[148:149], v[102:103], v[24:25] op_sel_hi:[1,0,1]
	ds_write_b32 v110, v98 offset:49408
	v_pk_fma_f32 v[150:151], v[132:133], v[150:151], v[24:25]
	ds_read_b128 v[24:27], v105 offset:1280
	ds_read_b128 v[98:101], v105 offset:5376
	ds_read_b128 v[130:133], v105 offset:9472
	ds_read_b128 v[138:141], v105 offset:13568
	ds_read_b128 v[146:149], v105 offset:17664
	s_waitcnt lgkmcnt(6)
	v_pk_mul_f32 v[22:23], v[22:23], v[150:151]
	ds_read_b32 v102, v106 offset:21760
	v_pk_fma_f32 v[20:21], v[20:21], v[152:153], v[22:23]
	v_pk_mul_f32 v[22:23], v[30:31], v[150:151]
	ds_read_b64 v[168:169], v157 offset:24616
	v_pk_fma_f32 v[22:23], v[28:29], v[152:153], v[22:23]
	v_add_f32_e32 v20, v20, v21
	v_add_f32_e32 v21, v22, v23
	s_nop 0
	v_add_f32_dpp v20, v20, v20 quad_perm:[1,0,3,2] row_mask:0xf bank_mask:0xf bound_ctrl:1
	v_add_f32_dpp v21, v21, v21 quad_perm:[1,0,3,2] row_mask:0xf bank_mask:0xf bound_ctrl:1
	s_nop 0
	v_add_f32_dpp v20, v20, v20 quad_perm:[2,3,0,1] row_mask:0xf bank_mask:0xf bound_ctrl:1
	v_add_f32_dpp v21, v21, v21 quad_perm:[2,3,0,1] row_mask:0xf bank_mask:0xf bound_ctrl:1
	s_nop 0
	v_add_f32_dpp v20, v20, v20 row_half_mirror row_mask:0xf bank_mask:0xf bound_ctrl:1
	v_add_f32_dpp v21, v21, v21 row_half_mirror row_mask:0xf bank_mask:0xf bound_ctrl:1
	s_nop 0
	v_add_f32_dpp v20, v20, v20 row_mirror row_mask:0xf bank_mask:0xf bound_ctrl:1
	v_add_f32_dpp v28, v21, v21 row_mirror row_mask:0xf bank_mask:0xf bound_ctrl:1
	v_pk_mul_f32 v[22:23], v[134:135], v[20:21] op_sel_hi:[1,0]
	v_fmac_f32_e32 v28, v20, v154
	v_pk_mul_f32 v[20:21], v[136:137], v[20:21] op_sel_hi:[1,0]
	v_pk_fma_f32 v[22:23], v[142:143], v[96:97], v[22:23] op_sel_hi:[1,0,1]
	v_fmac_f32_e32 v28, v96, v155
	v_pk_fma_f32 v[20:21], v[144:145], v[96:97], v[20:21] op_sel_hi:[1,0,1]
	v_pk_fma_f32 v[152:153], v[126:127], v[152:153], v[22:23]
	ds_write_b32 v111, v28 offset:49408
	v_pk_fma_f32 v[150:151], v[128:129], v[150:151], v[20:21]
	ds_read_b128 v[20:23], v105 offset:1536
	ds_read_b128 v[28:31], v105 offset:5632
	ds_read_b128 v[126:129], v105 offset:9728
	ds_read_b128 v[134:137], v105 offset:13824
	ds_read_b128 v[142:145], v105 offset:17920
	ds_read_b32 v96, v106 offset:22016
	s_waitcnt lgkmcnt(14)
; DI float row16_sum(float v) { v += dppf(v, 0); v += dppf(v, 1); v += dppf(v, 2); v += dppf(v, 3); return v; }
; DI void rwkv_scan(CP p, const Ptrs& w, int l, int item, float* sm) {
;     ...
;   auto lds_step = [&](const float* bf, int j) {
;     RStep q;
;     q.a4 = *(const f4v*)(bf + 0 * 1024 + j * 64 + 4 * kg);
;     q.wr4 = *(const f4v*)(bf + 1 * 1024 + j * 64 + 4 * kg);
;     q.w4 = *(const f4v*)(bf + 2 * 1024 + j * 64 + 4 * kg);
;     q.b4 = *(const f4v*)(bf + 3 * 1024 + j * 64 + 4 * kg);
;     q.k4 = *(const f4v*)(bf + 4 * 1024 + j * 64 + 4 * kg);
;     q.vv = bf[5 * 1024 + j * 64 + row];
;     q.sc = *(const float2*)(bf + 6 * 1024 + j * 2);
;     return q;
;   };
;   auto flush = [&](int c) {
;     {
;       int j = tid >> 4, rr = tid & 15;
;       int ii = pos2i(c * 16 + j, dir);
;       yout[((size_t)b * TPB + ii) * 512 + hd * 64 + rq * 16 + rr] = f2bf(sY[(c & 1) * 256 + j * 16 + rr]);
;     }
;   };
;   __syncthreads();
;   load(0, PA);
;   stage(PA, sm);
;   load(1, PB);
;   __syncthreads();
;   const int NCH = TPB / 16;
;   auto run_chunk = [&](int c, const float* bf, float* sy) {
;     flush(max(c - 1, 0));
;     RStep cur = lds_step(bf, 0);
; #pragma unroll
;     for (int j = 0; j < 16; ++j) {
;       RStep nxt = cur;
;       if (j + 1 < 16) nxt = lds_step(bf, j + 1);
;       f2v sa2 = SA * cur.a4.xy + SB * cur.a4.zw;
;       f2v yp2 = SA * cur.wr4.xy + SB * cur.wr4.zw;
;       float sa = sa2.x + sa2.y, yp = yp2.x + yp2.y;
;       sa = row16_sum(sa); yp = row16_sum(yp);
;       float y = yp + sa * cur.sc.x + cur.vv * cur.sc.y;
;       SA = SA * cur.w4.xy + (sa * cur.b4.xy + cur.vv * cur.k4.xy);
;       SB = SB * cur.w4.zw + (sa * cur.b4.zw + cur.vv * cur.k4.zw);
;       sy[(kg == 0 ? j * 16 : 0) + ysel - (c & 1) * 0] = y;
;       cur = nxt;
;     }
	ds_read_b64 v[154:155], v157 offset:24624
	s_waitcnt lgkmcnt(8)
	v_pk_mul_f32 v[26:27], v[26:27], v[150:151]
	v_pk_fma_f32 v[24:25], v[24:25], v[152:153], v[26:27]
	v_pk_mul_f32 v[26:27], v[100:101], v[150:151]
	v_add_f32_e32 v24, v24, v25
	v_pk_fma_f32 v[26:27], v[98:99], v[152:153], v[26:27]
	v_add_f32_e32 v25, v26, v27
	v_add_f32_dpp v24, v24, v24 quad_perm:[1,0,3,2] row_mask:0xf bank_mask:0xf bound_ctrl:1
	s_nop 0
	v_add_f32_dpp v25, v25, v25 quad_perm:[1,0,3,2] row_mask:0xf bank_mask:0xf bound_ctrl:1
	v_add_f32_dpp v24, v24, v24 quad_perm:[2,3,0,1] row_mask:0xf bank_mask:0xf bound_ctrl:1
	s_nop 0
	v_add_f32_dpp v25, v25, v25 quad_perm:[2,3,0,1] row_mask:0xf bank_mask:0xf bound_ctrl:1
	v_add_f32_dpp v24, v24, v24 row_half_mirror row_mask:0xf bank_mask:0xf bound_ctrl:1
	s_nop 0
	v_add_f32_dpp v25, v25, v25 row_half_mirror row_mask:0xf bank_mask:0xf bound_ctrl:1
	v_add_f32_dpp v24, v24, v24 row_mirror row_mask:0xf bank_mask:0xf bound_ctrl:1
	v_pk_mul_f32 v[26:27], v[138:139], v[24:25] op_sel_hi:[1,0]
	v_add_f32_dpp v98, v25, v25 row_mirror row_mask:0xf bank_mask:0xf bound_ctrl:1
	v_pk_fma_f32 v[26:27], v[146:147], v[102:103], v[26:27] op_sel_hi:[1,0,1]
	v_fmac_f32_e32 v98, v24, v168
	v_pk_mul_f32 v[24:25], v[140:141], v[24:25] op_sel_hi:[1,0]
	v_pk_fma_f32 v[152:153], v[130:131], v[152:153], v[26:27]
	v_fmac_f32_e32 v98, v102, v169
	v_pk_fma_f32 v[24:25], v[148:149], v[102:103], v[24:25] op_sel_hi:[1,0,1]
	ds_write_b32 v112, v98 offset:49408
	v_pk_fma_f32 v[150:151], v[132:133], v[150:151], v[24:25]
	ds_read_b128 v[24:27], v105 offset:1792
	ds_read_b128 v[98:101], v105 offset:5888
	ds_read_b128 v[130:133], v105 offset:9984
	ds_read_b128 v[138:141], v105 offset:14080
	ds_read_b128 v[146:149], v105 offset:18176
	s_waitcnt lgkmcnt(6)
	v_pk_mul_f32 v[22:23], v[22:23], v[150:151]
	ds_read_b32 v102, v106 offset:22272
	v_pk_fma_f32 v[20:21], v[20:21], v[152:153], v[22:23]
	v_pk_mul_f32 v[22:23], v[30:31], v[150:151]
	ds_read_b64 v[168:169], v157 offset:24632
	v_pk_fma_f32 v[22:23], v[28:29], v[152:153], v[22:23]
	v_add_f32_e32 v20, v20, v21
	v_add_f32_e32 v21, v22, v23
	s_nop 0
	v_add_f32_dpp v20, v20, v20 quad_perm:[1,0,3,2] row_mask:0xf bank_mask:0xf bound_ctrl:1
	v_add_f32_dpp v21, v21, v21 quad_perm:[1,0,3,2] row_mask:0xf bank_mask:0xf bound_ctrl:1
	s_nop 0
	v_add_f32_dpp v20, v20, v20 quad_perm:[2,3,0,1] row_mask:0xf bank_mask:0xf bound_ctrl:1
	v_add_f32_dpp v21, v21, v21 quad_perm:[2,3,0,1] row_mask:0xf bank_mask:0xf bound_ctrl:1
	s_nop 0
	v_add_f32_dpp v20, v20, v20 row_half_mirror row_mask:0xf bank_mask:0xf bound_ctrl:1
	v_add_f32_dpp v21, v21, v21 row_half_mirror row_mask:0xf bank_mask:0xf bound_ctrl:1
	s_nop 0
	v_add_f32_dpp v20, v20, v20 row_mirror row_mask:0xf bank_mask:0xf bound_ctrl:1
	v_add_f32_dpp v28, v21, v21 row_mirror row_mask:0xf bank_mask:0xf bound_ctrl:1
	v_pk_mul_f32 v[22:23], v[134:135], v[20:21] op_sel_hi:[1,0]
	v_fmac_f32_e32 v28, v20, v154
	v_pk_mul_f32 v[20:21], v[136:137], v[20:21] op_sel_hi:[1,0]
	v_pk_fma_f32 v[22:23], v[142:143], v[96:97], v[22:23] op_sel_hi:[1,0,1]
	v_fmac_f32_e32 v28, v96, v155
	v_pk_fma_f32 v[20:21], v[144:145], v[96:97], v[20:21] op_sel_hi:[1,0,1]
	v_pk_fma_f32 v[152:153], v[126:127], v[152:153], v[22:23]
	ds_write_b32 v113, v28 offset:49408
	v_pk_fma_f32 v[150:151], v[128:129], v[150:151], v[20:21]
	ds_read_b128 v[20:23], v105 offset:2048
	ds_read_b128 v[28:31], v105 offset:6144
	ds_read_b128 v[126:129], v105 offset:10240
	ds_read_b128 v[134:137], v105 offset:14336
	ds_read_b128 v[142:145], v105 offset:18432
	ds_read_b32 v96, v106 offset:22528
	s_waitcnt lgkmcnt(14)
	ds_read_b64 v[154:155], v157 offset:24640
	s_waitcnt lgkmcnt(8)
	v_pk_mul_f32 v[26:27], v[26:27], v[150:151]
	v_pk_fma_f32 v[24:25], v[24:25], v[152:153], v[26:27]
	v_pk_mul_f32 v[26:27], v[100:101], v[150:151]
	v_add_f32_e32 v24, v24, v25
	v_pk_fma_f32 v[26:27], v[98:99], v[152:153], v[26:27]
	v_add_f32_e32 v25, v26, v27
	v_add_f32_dpp v24, v24, v24 quad_perm:[1,0,3,2] row_mask:0xf bank_mask:0xf bound_ctrl:1
	s_nop 0
	v_add_f32_dpp v25, v25, v25 quad_perm:[1,0,3,2] row_mask:0xf bank_mask:0xf bound_ctrl:1
	v_add_f32_dpp v24, v24, v24 quad_perm:[2,3,0,1] row_mask:0xf bank_mask:0xf bound_ctrl:1
	s_nop 0
	v_add_f32_dpp v25, v25, v25 quad_perm:[2,3,0,1] row_mask:0xf bank_mask:0xf bound_ctrl:1
	v_add_f32_dpp v24, v24, v24 row_half_mirror row_mask:0xf bank_mask:0xf bound_ctrl:1
	s_nop 0
	v_add_f32_dpp v25, v25, v25 row_half_mirror row_mask:0xf bank_mask:0xf bound_ctrl:1
	v_add_f32_dpp v24, v24, v24 row_mirror row_mask:0xf bank_mask:0xf bound_ctrl:1
	v_pk_mul_f32 v[26:27], v[138:139], v[24:25] op_sel_hi:[1,0]
	v_add_f32_dpp v98, v25, v25 row_mirror row_mask:0xf bank_mask:0xf bound_ctrl:1
	v_pk_fma_f32 v[26:27], v[146:147], v[102:103], v[26:27] op_sel_hi:[1,0,1]
	v_fmac_f32_e32 v98, v24, v168
	v_pk_mul_f32 v[24:25], v[140:141], v[24:25] op_sel_hi:[1,0]
	v_pk_fma_f32 v[152:153], v[130:131], v[152:153], v[26:27]
	v_fmac_f32_e32 v98, v102, v169
	v_pk_fma_f32 v[24:25], v[148:149], v[102:103], v[24:25] op_sel_hi:[1,0,1]
	ds_write_b32 v114, v98 offset:49408
	v_pk_fma_f32 v[150:151], v[132:133], v[150:151], v[24:25]
	ds_read_b128 v[24:27], v105 offset:2304
	ds_read_b128 v[98:101], v105 offset:6400
	ds_read_b128 v[130:133], v105 offset:10496
	ds_read_b128 v[138:141], v105 offset:14592
	ds_read_b128 v[146:149], v105 offset:18688
	s_waitcnt lgkmcnt(6)
; DI float row16_sum(float v) { v += dppf(v, 0); v += dppf(v, 1); v += dppf(v, 2); v += dppf(v, 3); return v; }
; DI void rwkv_scan(CP p, const Ptrs& w, int l, int item, float* sm) {
;     ...
;   auto lds_step = [&](const float* bf, int j) {
;     RStep q;
;     q.a4 = *(const f4v*)(bf + 0 * 1024 + j * 64 + 4 * kg);
;     q.wr4 = *(const f4v*)(bf + 1 * 1024 + j * 64 + 4 * kg);
;     q.w4 = *(const f4v*)(bf + 2 * 1024 + j * 64 + 4 * kg);
;     q.b4 = *(const f4v*)(bf + 3 * 1024 + j * 64 + 4 * kg);
;     q.k4 = *(const f4v*)(bf + 4 * 1024 + j * 64 + 4 * kg);
;     q.vv = bf[5 * 1024 + j * 64 + row];
;     q.sc = *(const float2*)(bf + 6 * 1024 + j * 2);
;     return q;
;   };
;     ...
; #pragma unroll
;     for (int j = 0; j < 16; ++j) {
;       RStep nxt = cur;
;       if (j + 1 < 16) nxt = lds_step(bf, j + 1);
;       f2v sa2 = SA * cur.a4.xy + SB * cur.a4.zw;
;       f2v yp2 = SA * cur.wr4.xy + SB * cur.wr4.zw;
;       float sa = sa2.x + sa2.y, yp = yp2.x + yp2.y;
;       sa = row16_sum(sa); yp = row16_sum(yp);
;       float y = yp + sa * cur.sc.x + cur.vv * cur.sc.y;
;       SA = SA * cur.w4.xy + (sa * cur.b4.xy + cur.vv * cur.k4.xy);
;       SB = SB * cur.w4.zw + (sa * cur.b4.zw + cur.vv * cur.k4.zw);
;       sy[(kg == 0 ? j * 16 : 0) + ysel - (c & 1) * 0] = y;
;       cur = nxt;
;     }
	v_pk_mul_f32 v[22:23], v[22:23], v[150:151]
	ds_read_b32 v102, v106 offset:22784
	v_pk_fma_f32 v[20:21], v[20:21], v[152:153], v[22:23]
	v_pk_mul_f32 v[22:23], v[30:31], v[150:151]
	ds_read_b64 v[168:169], v157 offset:24648
	v_pk_fma_f32 v[22:23], v[28:29], v[152:153], v[22:23]
	v_add_f32_e32 v20, v20, v21
	v_add_f32_e32 v21, v22, v23
	s_nop 0
	v_add_f32_dpp v20, v20, v20 quad_perm:[1,0,3,2] row_mask:0xf bank_mask:0xf bound_ctrl:1
	v_add_f32_dpp v21, v21, v21 quad_perm:[1,0,3,2] row_mask:0xf bank_mask:0xf bound_ctrl:1
	s_nop 0
	v_add_f32_dpp v20, v20, v20 quad_perm:[2,3,0,1] row_mask:0xf bank_mask:0xf bound_ctrl:1
	v_add_f32_dpp v21, v21, v21 quad_perm:[2,3,0,1] row_mask:0xf bank_mask:0xf bound_ctrl:1
	s_nop 0
	v_add_f32_dpp v20, v20, v20 row_half_mirror row_mask:0xf bank_mask:0xf bound_ctrl:1
	v_add_f32_dpp v21, v21, v21 row_half_mirror row_mask:0xf bank_mask:0xf bound_ctrl:1
	s_nop 0
	v_add_f32_dpp v20, v20, v20 row_mirror row_mask:0xf bank_mask:0xf bound_ctrl:1
	v_add_f32_dpp v28, v21, v21 row_mirror row_mask:0xf bank_mask:0xf bound_ctrl:1
	v_pk_mul_f32 v[22:23], v[134:135], v[20:21] op_sel_hi:[1,0]
	v_fmac_f32_e32 v28, v20, v154
	v_pk_mul_f32 v[20:21], v[136:137], v[20:21] op_sel_hi:[1,0]
	v_pk_fma_f32 v[22:23], v[142:143], v[96:97], v[22:23] op_sel_hi:[1,0,1]
	v_fmac_f32_e32 v28, v96, v155
	v_pk_fma_f32 v[20:21], v[144:145], v[96:97], v[20:21] op_sel_hi:[1,0,1]
	v_pk_fma_f32 v[152:153], v[126:127], v[152:153], v[22:23]
	ds_write_b32 v115, v28 offset:49408
	v_pk_fma_f32 v[150:151], v[128:129], v[150:151], v[20:21]
	ds_read_b128 v[20:23], v105 offset:2560
	ds_read_b128 v[28:31], v105 offset:6656
	ds_read_b128 v[126:129], v105 offset:10752
	ds_read_b128 v[134:137], v105 offset:14848
	ds_read_b128 v[142:145], v105 offset:18944
	ds_read_b32 v96, v106 offset:23040
	s_waitcnt lgkmcnt(14)
	ds_read_b64 v[154:155], v157 offset:24656
	s_waitcnt lgkmcnt(8)
	v_pk_mul_f32 v[26:27], v[26:27], v[150:151]
	v_pk_fma_f32 v[24:25], v[24:25], v[152:153], v[26:27]
	v_pk_mul_f32 v[26:27], v[100:101], v[150:151]
	v_add_f32_e32 v24, v24, v25
	v_pk_fma_f32 v[26:27], v[98:99], v[152:153], v[26:27]
	v_add_f32_e32 v25, v26, v27
	v_add_f32_dpp v24, v24, v24 quad_perm:[1,0,3,2] row_mask:0xf bank_mask:0xf bound_ctrl:1
	s_nop 0
	v_add_f32_dpp v25, v25, v25 quad_perm:[1,0,3,2] row_mask:0xf bank_mask:0xf bound_ctrl:1
	v_add_f32_dpp v24, v24, v24 quad_perm:[2,3,0,1] row_mask:0xf bank_mask:0xf bound_ctrl:1
	s_nop 0
	v_add_f32_dpp v25, v25, v25 quad_perm:[2,3,0,1] row_mask:0xf bank_mask:0xf bound_ctrl:1
	v_add_f32_dpp v24, v24, v24 row_half_mirror row_mask:0xf bank_mask:0xf bound_ctrl:1
	s_nop 0
	v_add_f32_dpp v25, v25, v25 row_half_mirror row_mask:0xf bank_mask:0xf bound_ctrl:1
	v_add_f32_dpp v24, v24, v24 row_mirror row_mask:0xf bank_mask:0xf bound_ctrl:1
	v_pk_mul_f32 v[26:27], v[138:139], v[24:25] op_sel_hi:[1,0]
	v_add_f32_dpp v98, v25, v25 row_mirror row_mask:0xf bank_mask:0xf bound_ctrl:1
	v_pk_fma_f32 v[26:27], v[146:147], v[102:103], v[26:27] op_sel_hi:[1,0,1]
	v_fmac_f32_e32 v98, v24, v168
	v_pk_mul_f32 v[24:25], v[140:141], v[24:25] op_sel_hi:[1,0]
	v_pk_fma_f32 v[152:153], v[130:131], v[152:153], v[26:27]
	v_fmac_f32_e32 v98, v102, v169
	v_pk_fma_f32 v[24:25], v[148:149], v[102:103], v[24:25] op_sel_hi:[1,0,1]
	ds_write_b32 v116, v98 offset:49408
	v_pk_fma_f32 v[150:151], v[132:133], v[150:151], v[24:25]
	ds_read_b128 v[24:27], v105 offset:2816
	ds_read_b128 v[98:101], v105 offset:6912
	ds_read_b128 v[130:133], v105 offset:11008
	ds_read_b128 v[138:141], v105 offset:15104
	ds_read_b128 v[146:149], v105 offset:19200
	s_waitcnt lgkmcnt(6)
	v_pk_mul_f32 v[22:23], v[22:23], v[150:151]
	ds_read_b32 v102, v106 offset:23296
	v_pk_fma_f32 v[20:21], v[20:21], v[152:153], v[22:23]
	v_pk_mul_f32 v[22:23], v[30:31], v[150:151]
	ds_read_b64 v[168:169], v157 offset:24664
	v_pk_fma_f32 v[22:23], v[28:29], v[152:153], v[22:23]
	v_add_f32_e32 v20, v20, v21
	v_add_f32_e32 v21, v22, v23
	s_nop 0
	v_add_f32_dpp v20, v20, v20 quad_perm:[1,0,3,2] row_mask:0xf bank_mask:0xf bound_ctrl:1
	v_add_f32_dpp v21, v21, v21 quad_perm:[1,0,3,2] row_mask:0xf bank_mask:0xf bound_ctrl:1
	s_nop 0
	v_add_f32_dpp v20, v20, v20 quad_perm:[2,3,0,1] row_mask:0xf bank_mask:0xf bound_ctrl:1
	v_add_f32_dpp v21, v21, v21 quad_perm:[2,3,0,1] row_mask:0xf bank_mask:0xf bound_ctrl:1
	s_nop 0
	v_add_f32_dpp v20, v20, v20 row_half_mirror row_mask:0xf bank_mask:0xf bound_ctrl:1
	v_add_f32_dpp v21, v21, v21 row_half_mirror row_mask:0xf bank_mask:0xf bound_ctrl:1
	s_nop 0
	v_add_f32_dpp v20, v20, v20 row_mirror row_mask:0xf bank_mask:0xf bound_ctrl:1
	v_add_f32_dpp v28, v21, v21 row_mirror row_mask:0xf bank_mask:0xf bound_ctrl:1
	v_pk_mul_f32 v[22:23], v[134:135], v[20:21] op_sel_hi:[1,0]
	v_fmac_f32_e32 v28, v20, v154
	v_pk_mul_f32 v[20:21], v[136:137], v[20:21] op_sel_hi:[1,0]
	v_pk_fma_f32 v[22:23], v[142:143], v[96:97], v[22:23] op_sel_hi:[1,0,1]
	v_fmac_f32_e32 v28, v96, v155
	v_pk_fma_f32 v[20:21], v[144:145], v[96:97], v[20:21] op_sel_hi:[1,0,1]
	v_pk_fma_f32 v[152:153], v[126:127], v[152:153], v[22:23]
	ds_write_b32 v117, v28 offset:49408
	v_pk_fma_f32 v[150:151], v[128:129], v[150:151], v[20:21]
	ds_read_b128 v[20:23], v105 offset:3072
	ds_read_b128 v[28:31], v105 offset:7168
	ds_read_b128 v[126:129], v105 offset:11264
	ds_read_b128 v[134:137], v105 offset:15360
	ds_read_b128 v[142:145], v105 offset:19456
	ds_read_b32 v96, v106 offset:23552
	s_waitcnt lgkmcnt(14)
	ds_read_b64 v[154:155], v157 offset:24672
	s_waitcnt lgkmcnt(8)
; DI float row16_sum(float v) { v += dppf(v, 0); v += dppf(v, 1); v += dppf(v, 2); v += dppf(v, 3); return v; }
; DI void rwkv_scan(CP p, const Ptrs& w, int l, int item, float* sm) {
;     ...
;   auto lds_step = [&](const float* bf, int j) {
;     RStep q;
;     q.a4 = *(const f4v*)(bf + 0 * 1024 + j * 64 + 4 * kg);
;     q.wr4 = *(const f4v*)(bf + 1 * 1024 + j * 64 + 4 * kg);
;     q.w4 = *(const f4v*)(bf + 2 * 1024 + j * 64 + 4 * kg);
;     q.b4 = *(const f4v*)(bf + 3 * 1024 + j * 64 + 4 * kg);
;     q.k4 = *(const f4v*)(bf + 4 * 1024 + j * 64 + 4 * kg);
;     q.vv = bf[5 * 1024 + j * 64 + row];
;     q.sc = *(const float2*)(bf + 6 * 1024 + j * 2);
;     return q;
;   };
;     ...
; #pragma unroll
;     for (int j = 0; j < 16; ++j) {
;       RStep nxt = cur;
;       if (j + 1 < 16) nxt = lds_step(bf, j + 1);
;       f2v sa2 = SA * cur.a4.xy + SB * cur.a4.zw;
;       f2v yp2 = SA * cur.wr4.xy + SB * cur.wr4.zw;
;       float sa = sa2.x + sa2.y, yp = yp2.x + yp2.y;
;       sa = row16_sum(sa); yp = row16_sum(yp);
;       float y = yp + sa * cur.sc.x + cur.vv * cur.sc.y;
;       SA = SA * cur.w4.xy + (sa * cur.b4.xy + cur.vv * cur.k4.xy);
;       SB = SB * cur.w4.zw + (sa * cur.b4.zw + cur.vv * cur.k4.zw);
;       sy[(kg == 0 ? j * 16 : 0) + ysel - (c & 1) * 0] = y;
;       cur = nxt;
;     }
	v_pk_mul_f32 v[26:27], v[26:27], v[150:151]
	v_pk_fma_f32 v[24:25], v[24:25], v[152:153], v[26:27]
	v_pk_mul_f32 v[26:27], v[100:101], v[150:151]
	v_add_f32_e32 v24, v24, v25
	v_pk_fma_f32 v[26:27], v[98:99], v[152:153], v[26:27]
	v_add_f32_e32 v25, v26, v27
	v_add_f32_dpp v24, v24, v24 quad_perm:[1,0,3,2] row_mask:0xf bank_mask:0xf bound_ctrl:1
	s_nop 0
	v_add_f32_dpp v25, v25, v25 quad_perm:[1,0,3,2] row_mask:0xf bank_mask:0xf bound_ctrl:1
	v_add_f32_dpp v24, v24, v24 quad_perm:[2,3,0,1] row_mask:0xf bank_mask:0xf bound_ctrl:1
	s_nop 0
	v_add_f32_dpp v25, v25, v25 quad_perm:[2,3,0,1] row_mask:0xf bank_mask:0xf bound_ctrl:1
	v_add_f32_dpp v24, v24, v24 row_half_mirror row_mask:0xf bank_mask:0xf bound_ctrl:1
	s_nop 0
	v_add_f32_dpp v25, v25, v25 row_half_mirror row_mask:0xf bank_mask:0xf bound_ctrl:1
	v_add_f32_dpp v24, v24, v24 row_mirror row_mask:0xf bank_mask:0xf bound_ctrl:1
	v_pk_mul_f32 v[26:27], v[138:139], v[24:25] op_sel_hi:[1,0]
	v_add_f32_dpp v98, v25, v25 row_mirror row_mask:0xf bank_mask:0xf bound_ctrl:1
	v_pk_fma_f32 v[26:27], v[146:147], v[102:103], v[26:27] op_sel_hi:[1,0,1]
	v_fmac_f32_e32 v98, v24, v168
	v_pk_mul_f32 v[24:25], v[140:141], v[24:25] op_sel_hi:[1,0]
	v_pk_fma_f32 v[152:153], v[130:131], v[152:153], v[26:27]
	v_fmac_f32_e32 v98, v102, v169
	v_pk_fma_f32 v[24:25], v[148:149], v[102:103], v[24:25] op_sel_hi:[1,0,1]
	ds_write_b32 v118, v98 offset:49408
	v_pk_fma_f32 v[150:151], v[132:133], v[150:151], v[24:25]
	ds_read_b128 v[24:27], v105 offset:3328
	ds_read_b128 v[98:101], v105 offset:7424
	ds_read_b128 v[130:133], v105 offset:11520
	ds_read_b128 v[138:141], v105 offset:15616
	ds_read_b128 v[146:149], v105 offset:19712
	s_waitcnt lgkmcnt(6)
	v_pk_mul_f32 v[22:23], v[22:23], v[150:151]
	ds_read_b32 v102, v106 offset:23808
	v_pk_fma_f32 v[20:21], v[20:21], v[152:153], v[22:23]
	v_pk_mul_f32 v[22:23], v[30:31], v[150:151]
	ds_read_b64 v[172:173], v157 offset:24680
	v_pk_fma_f32 v[22:23], v[28:29], v[152:153], v[22:23]
	v_add_f32_e32 v20, v20, v21
	v_add_f32_e32 v21, v22, v23
	s_nop 0
	v_add_f32_dpp v20, v20, v20 quad_perm:[1,0,3,2] row_mask:0xf bank_mask:0xf bound_ctrl:1
	v_add_f32_dpp v21, v21, v21 quad_perm:[1,0,3,2] row_mask:0xf bank_mask:0xf bound_ctrl:1
	s_nop 0
	v_add_f32_dpp v20, v20, v20 quad_perm:[2,3,0,1] row_mask:0xf bank_mask:0xf bound_ctrl:1
	v_add_f32_dpp v21, v21, v21 quad_perm:[2,3,0,1] row_mask:0xf bank_mask:0xf bound_ctrl:1
	s_nop 0
	v_add_f32_dpp v20, v20, v20 row_half_mirror row_mask:0xf bank_mask:0xf bound_ctrl:1
	v_add_f32_dpp v21, v21, v21 row_half_mirror row_mask:0xf bank_mask:0xf bound_ctrl:1
	s_nop 0
	v_add_f32_dpp v20, v20, v20 row_mirror row_mask:0xf bank_mask:0xf bound_ctrl:1
	v_add_f32_dpp v28, v21, v21 row_mirror row_mask:0xf bank_mask:0xf bound_ctrl:1
	v_pk_mul_f32 v[22:23], v[134:135], v[20:21] op_sel_hi:[1,0]
	v_fmac_f32_e32 v28, v20, v154
	v_pk_mul_f32 v[20:21], v[136:137], v[20:21] op_sel_hi:[1,0]
	v_pk_fma_f32 v[22:23], v[142:143], v[96:97], v[22:23] op_sel_hi:[1,0,1]
	v_fmac_f32_e32 v28, v96, v155
	v_pk_fma_f32 v[20:21], v[144:145], v[96:97], v[20:21] op_sel_hi:[1,0,1]
	v_pk_fma_f32 v[22:23], v[126:127], v[152:153], v[22:23]
	ds_write_b32 v119, v28 offset:49408
	v_pk_fma_f32 v[20:21], v[128:129], v[150:151], v[20:21]
	ds_read_b128 v[126:129], v105 offset:3584
	ds_read_b128 v[134:137], v105 offset:7680
	ds_read_b128 v[142:145], v105 offset:11776
	ds_read_b128 v[150:153], v105 offset:15872
	ds_read_b128 v[168:171], v105 offset:19968
	ds_read_b32 v154, v106 offset:24064
	s_waitcnt lgkmcnt(14)
	ds_read_b64 v[174:175], v157 offset:24688
	s_waitcnt lgkmcnt(8)
	v_pk_mul_f32 v[26:27], v[26:27], v[20:21]
	v_pk_fma_f32 v[24:25], v[24:25], v[22:23], v[26:27]
	v_pk_mul_f32 v[26:27], v[100:101], v[20:21]
	v_add_f32_e32 v24, v24, v25
	v_pk_fma_f32 v[26:27], v[98:99], v[22:23], v[26:27]
	v_add_f32_e32 v25, v26, v27
	v_add_f32_dpp v24, v24, v24 quad_perm:[1,0,3,2] row_mask:0xf bank_mask:0xf bound_ctrl:1
	s_nop 0
	v_add_f32_dpp v25, v25, v25 quad_perm:[1,0,3,2] row_mask:0xf bank_mask:0xf bound_ctrl:1
	v_add_f32_dpp v24, v24, v24 quad_perm:[2,3,0,1] row_mask:0xf bank_mask:0xf bound_ctrl:1
	s_nop 0
	v_add_f32_dpp v25, v25, v25 quad_perm:[2,3,0,1] row_mask:0xf bank_mask:0xf bound_ctrl:1
	v_add_f32_dpp v24, v24, v24 row_half_mirror row_mask:0xf bank_mask:0xf bound_ctrl:1
	s_nop 0
	v_add_f32_dpp v25, v25, v25 row_half_mirror row_mask:0xf bank_mask:0xf bound_ctrl:1
	v_add_f32_dpp v24, v24, v24 row_mirror row_mask:0xf bank_mask:0xf bound_ctrl:1
	s_nop 0
	v_add_f32_dpp v25, v25, v25 row_mirror row_mask:0xf bank_mask:0xf bound_ctrl:1
	v_fmac_f32_e32 v25, v24, v172
	v_fmac_f32_e32 v25, v102, v173
	v_pk_mul_f32 v[26:27], v[138:139], v[24:25] op_sel_hi:[1,0]
	ds_write_b32 v120, v25 offset:49408
	v_pk_fma_f32 v[26:27], v[146:147], v[102:103], v[26:27] op_sel_hi:[1,0,1]
	v_pk_fma_f32 v[98:99], v[130:131], v[22:23], v[26:27]
	v_pk_mul_f32 v[22:23], v[140:141], v[24:25] op_sel_hi:[1,0]
	v_pk_fma_f32 v[22:23], v[148:149], v[102:103], v[22:23] op_sel_hi:[1,0,1]
	v_pk_fma_f32 v[100:101], v[132:133], v[20:21], v[22:23]
	ds_read_b128 v[130:133], v105 offset:3840
	ds_read_b128 v[138:141], v105 offset:7936
	ds_read_b128 v[20:23], v105 offset:12032
	ds_read_b128 v[28:31], v105 offset:16128
	s_waitcnt lgkmcnt(5)
	v_pk_mul_f32 v[128:129], v[128:129], v[100:101]
	ds_read_b128 v[24:27], v105 offset:20224
	v_pk_fma_f32 v[126:127], v[126:127], v[98:99], v[128:129]
	v_pk_mul_f32 v[128:129], v[136:137], v[100:101]
	ds_read_b32 v96, v106 offset:24320
	ds_read_b64 v[146:147], v157 offset:24696
	v_add_f32_e32 v102, v126, v127
	v_pk_fma_f32 v[128:129], v[134:135], v[98:99], v[128:129]
	s_waitcnt vmcnt(21)
; DI float row16_sum(float v) { v += dppf(v, 0); v += dppf(v, 1); v += dppf(v, 2); v += dppf(v, 3); return v; }
; DI void rwkv_scan(CP p, const Ptrs& w, int l, int item, float* sm) {
;     ...
;   auto stage = [&](const RPre& P, float* bufp) {
;     float rc[4], rp[4], rn[4], kc[4], kp[4], kn[4], vc[4], vp[4], vn[4], wd4[4], ad4[4];
;     up4(P.pq[0][0], rc); up4(P.pq[0][1], rp); up4(P.pq[0][2], rn);
;     up4(P.pq[1][0], kc); up4(P.pq[1][1], kp); up4(P.pq[1][2], kn);
;     up4(P.pq[2][0], vc); up4(P.pq[2][1], vp); up4(P.pq[2][2], vn);
;     up4(P.pwd, wd4); up4(P.pad_, ad4);
;     float o0[4], o1[4], o2[4], o3[4], o4[4], o5[4];
; #pragma unroll
;     for (int j = 0; j < 4; ++j) {
;       float r_s = rc[j] + ((P.pmk[0] * rp[j] + P.pmk[1] * rn[j]) - rc[j]) * mu_r[j];
;       float k_s = kc[j] + ((P.pmk[0] * kp[j] + P.pmk[1] * kn[j]) - kc[j]) * mu_k[j];
;       float v_s = vc[j] + ((P.pmk[0] * vp[j] + P.pmk[1] * vn[j]) - vc[j]) * mu_v[j];
;       float kk = k_s * kk_c[j] * P.psc[0];
;       float a = ad4[j], wv = 1.f - wd4[j];
;       o0[j] = -kk; o1[j] = wv * r_s; o2[j] = wv; o3[j] = kk * a; o4[j] = k_s * (1.f + (a - 1.f) * ka_c[j]); o5[j] = v_s;
;     }
;     float* d = bufp + sj * 64 + skq;
;     *(float4*)(d + 0 * 1024) = make_float4(o0[0], o0[1], o0[2], o0[3]);
;     *(float4*)(d + 1 * 1024) = make_float4(o1[0], o1[1], o1[2], o1[3]);
;     *(float4*)(d + 2 * 1024) = make_float4(o2[0], o2[1], o2[2], o2[3]);
;     *(float4*)(d + 3 * 1024) = make_float4(o3[0], o3[1], o3[2], o3[3]);
;     *(float4*)(d + 4 * 1024) = make_float4(o4[0], o4[1], o4[2], o4[3]);
;     *(float4*)(d + 5 * 1024) = make_float4(o5[0], o5[1], o5[2], o5[3]);
;     ...
;       f2v sa2 = SA * cur.a4.xy + SB * cur.a4.zw;
;       f2v yp2 = SA * cur.wr4.xy + SB * cur.wr4.zw;
;       float sa = sa2.x + sa2.y, yp = yp2.x + yp2.y;
;       sa = row16_sum(sa); yp = row16_sum(yp);
;       float y = yp + sa * cur.sc.x + cur.vv * cur.sc.y;
;       SA = SA * cur.w4.xy + (sa * cur.b4.xy + cur.vv * cur.k4.xy);
;       SB = SB * cur.w4.zw + (sa * cur.b4.zw + cur.vv * cur.k4.zw);
;       sy[(kg == 0 ? j * 16 : 0) + ysel - (c & 1) * 0] = y;
;       cur = nxt;
;     }
	v_and_b32_e32 v137, 0xffff0000, v52
	v_add_f32_e32 v126, v128, v129
	v_add_f32_dpp v102, v102, v102 quad_perm:[1,0,3,2] row_mask:0xf bank_mask:0xf bound_ctrl:1
	s_waitcnt vmcnt(20)
	v_lshlrev_b32_e32 v136, 16, v54
	v_add_f32_dpp v126, v126, v126 quad_perm:[1,0,3,2] row_mask:0xf bank_mask:0xf bound_ctrl:1
	v_add_f32_dpp v102, v102, v102 quad_perm:[2,3,0,1] row_mask:0xf bank_mask:0xf bound_ctrl:1
	s_waitcnt vmcnt(16)
	v_lshlrev_b32_e32 v134, 16, v64
	v_add_f32_dpp v126, v126, v126 quad_perm:[2,3,0,1] row_mask:0xf bank_mask:0xf bound_ctrl:1
	v_add_f32_dpp v102, v102, v102 row_half_mirror row_mask:0xf bank_mask:0xf bound_ctrl:1
	v_and_b32_e32 v135, 0xffff0000, v64
	v_add_f32_dpp v126, v126, v126 row_half_mirror row_mask:0xf bank_mask:0xf bound_ctrl:1
	v_add_f32_dpp v102, v102, v102 row_mirror row_mask:0xf bank_mask:0xf bound_ctrl:1
	v_lshlrev_b32_e32 v64, 16, v65
	v_add_f32_dpp v128, v126, v126 row_mirror row_mask:0xf bank_mask:0xf bound_ctrl:1
	s_waitcnt lgkmcnt(11)
	v_pk_mul_f32 v[126:127], v[150:151], v[102:103] op_sel_hi:[1,0]
	s_waitcnt lgkmcnt(8)
	v_fmac_f32_e32 v128, v102, v174
	v_pk_fma_f32 v[126:127], v[168:169], v[154:155], v[126:127] op_sel_hi:[1,0,1]
	v_fmac_f32_e32 v128, v154, v175
	v_pk_fma_f32 v[98:99], v[142:143], v[98:99], v[126:127]
	v_pk_mul_f32 v[126:127], v[152:153], v[102:103] op_sel_hi:[1,0]
	ds_write_b32 v121, v128 offset:49408
	v_pk_fma_f32 v[126:127], v[170:171], v[154:155], v[126:127] op_sel_hi:[1,0,1]
	v_and_b32_e32 v65, 0xffff0000, v65
	v_pk_fma_f32 v[100:101], v[144:145], v[100:101], v[126:127]
	s_waitcnt lgkmcnt(7)
	v_pk_mul_f32 v[126:127], v[132:133], v[100:101]
	s_waitcnt lgkmcnt(6)
	v_pk_mul_f32 v[128:129], v[140:141], v[100:101]
	v_pk_fma_f32 v[126:127], v[130:131], v[98:99], v[126:127]
	v_pk_fma_f32 v[128:129], v[138:139], v[98:99], v[128:129]
	v_add_f32_e32 v102, v126, v127
	v_add_f32_e32 v126, v128, v129
	v_lshlrev_b32_e32 v138, 16, v52
	v_add_f32_dpp v102, v102, v102 quad_perm:[1,0,3,2] row_mask:0xf bank_mask:0xf bound_ctrl:1
	v_add_f32_dpp v126, v126, v126 quad_perm:[1,0,3,2] row_mask:0xf bank_mask:0xf bound_ctrl:1
	v_and_b32_e32 v139, 0xffff0000, v54
	v_add_f32_dpp v102, v102, v102 quad_perm:[2,3,0,1] row_mask:0xf bank_mask:0xf bound_ctrl:1
	v_add_f32_dpp v126, v126, v126 quad_perm:[2,3,0,1] row_mask:0xf bank_mask:0xf bound_ctrl:1
	v_and_b32_e32 v141, 0xffff0000, v53
	v_add_f32_dpp v102, v102, v102 row_half_mirror row_mask:0xf bank_mask:0xf bound_ctrl:1
	v_add_f32_dpp v126, v126, v126 row_half_mirror row_mask:0xf bank_mask:0xf bound_ctrl:1
	v_lshlrev_b32_e32 v52, 16, v53
	v_add_f32_dpp v102, v102, v102 row_mirror row_mask:0xf bank_mask:0xf bound_ctrl:1
	v_add_f32_dpp v126, v126, v126 row_mirror row_mask:0xf bank_mask:0xf bound_ctrl:1
	s_waitcnt lgkmcnt(1)
	v_fmac_f32_e32 v126, v102, v146
	v_and_b32_e32 v53, 0xffff0000, v55
	v_fmac_f32_e32 v126, v96, v147
	v_pk_mul_f32 v[138:139], v[94:95], v[138:139] op_sel:[1,0] op_sel_hi:[0,1]
	v_lshlrev_b32_e32 v140, 16, v55
	v_pk_mul_f32 v[52:53], v[94:95], v[52:53] op_sel:[1,0] op_sel_hi:[0,1]
	ds_write_b32 v122, v126 offset:49408
	v_lshlrev_b32_e32 v126, 16, v58
	v_and_b32_e32 v127, 0xffff0000, v58
	v_lshlrev_b32_e32 v128, 16, v59
	v_and_b32_e32 v129, 0xffff0000, v59
	v_lshlrev_b32_e32 v58, 16, v60
	v_and_b32_e32 v59, 0xffff0000, v60
	v_lshlrev_b32_e32 v60, 16, v61
	v_and_b32_e32 v61, 0xffff0000, v61
	v_pk_fma_f32 v[136:137], v[94:95], v[136:137], v[138:139]
	v_pk_fma_f32 v[52:53], v[94:95], v[140:141], v[52:53]
	v_pk_add_f32 v[136:137], v[136:137], v[58:59] neg_lo:[0,1] neg_hi:[0,1]
	v_pk_add_f32 v[52:53], v[52:53], v[60:61] neg_lo:[0,1] neg_hi:[0,1]
	v_pk_fma_f32 v[136:137], v[8:9], v[136:137], v[58:59]
	v_pk_fma_f32 v[140:141], v[10:11], v[52:53], v[60:61]
	v_pk_mul_f32 v[58:59], v[12:13], v[136:137]
	v_pk_mul_f32 v[52:53], v[14:15], v[140:141]
	s_waitcnt vmcnt(15)
	v_pk_mul_f32 v[138:139], v[56:57], v[58:59] op_sel_hi:[0,1]
	v_pk_mul_f32 v[142:143], v[56:57], v[52:53] op_sel_hi:[0,1]
	v_xor_b32_e32 v59, 0x80000000, v139
	v_xor_b32_e32 v58, 0x80000000, v138
	v_xor_b32_e32 v61, 0x80000000, v143
	v_xor_b32_e32 v60, 0x80000000, v142
	ds_write_b128 v103, v[58:61] offset:24704
	v_lshlrev_b32_e32 v59, 16, v48
	v_and_b32_e32 v61, s0, v48
	v_and_b32_e32 v60, 0xffff0000, v50
	v_pk_mov_b32 v[58:59], v[58:59], v[60:61] op_sel:[1,0]
	v_lshlrev_b32_e32 v54, 16, v50
	v_and_b32_e32 v55, 0xffff0000, v48
	v_pk_mul_f32 v[58:59], v[94:95], v[58:59] op_sel:[1,0] op_sel_hi:[0,1]
	v_pk_fma_f32 v[54:55], v[94:95], v[54:55], v[58:59]
	v_lshlrev_b32_e32 v132, 16, v66
	v_and_b32_e32 v133, 0xffff0000, v66
	v_pk_add_f32 v[54:55], v[54:55], v[126:127] neg_lo:[0,1] neg_hi:[0,1]
	v_lshlrev_b32_e32 v66, 16, v67
	v_and_b32_e32 v67, 0xffff0000, v67
	v_pk_add_f32 v[52:53], v[132:133], 1.0 op_sel_hi:[1,0] neg_lo:[1,0] neg_hi:[1,0]
	v_pk_fma_f32 v[54:55], v[0:1], v[54:55], v[126:127]
	v_and_b32_e32 v61, 0xffff0000, v49
	v_pk_mul_f32 v[58:59], v[54:55], v[52:53]
	v_pk_add_f32 v[54:55], v[66:67], 1.0 op_sel_hi:[1,0] neg_lo:[1,0] neg_hi:[1,0]
	v_lshlrev_b32_e32 v67, 16, v49
	v_and_b32_e32 v49, s0, v49
	v_and_b32_e32 v48, 0xffff0000, v51
	v_pk_mov_b32 v[48:49], v[66:67], v[48:49] op_sel:[1,0]
	v_lshlrev_b32_e32 v60, 16, v51
	v_pk_mul_f32 v[48:49], v[94:95], v[48:49] op_sel:[1,0] op_sel_hi:[0,1]
	v_pk_fma_f32 v[48:49], v[94:95], v[60:61], v[48:49]
	v_pk_mul_f32 v[50:51], v[142:143], v[64:65]
	v_pk_add_f32 v[48:49], v[48:49], v[128:129] neg_lo:[0,1] neg_hi:[0,1]
	v_lshlrev_b32_e32 v130, 16, v62
	v_pk_fma_f32 v[48:49], v[2:3], v[48:49], v[128:129]
	v_and_b32_e32 v131, 0xffff0000, v62
	v_pk_mul_f32 v[60:61], v[48:49], v[54:55]
	v_pk_mul_f32 v[48:49], v[138:139], v[134:135]
	ds_write_b128 v103, v[58:61] offset:28800
; DI void rwkv_scan(CP p, const Ptrs& w, int l, int item, float* sm) {
;     ...
;   auto load = [&](int c, RPre& P) {
;     int ii = pos2i(c * 16 + sj, dir);
;     size_t tok = (size_t)b * TPB + ii;
;     const bf16_t* prow = w.pB + tok * SPB + sc_;
;     bool hp = (ii != 0) && (ii != CTXL), hn = (ii != CTXL - 1) && (ii != TPB - 1);
;     const int op = hp ? -SPB : 0, on = hn ? SPB : 0;
;     P.pmk[0] = hp ? 0.5f : 0.f; P.pmk[1] = hn ? 0.5f : 0.f;
; #pragma unroll
;     for (int q = 0; q < 3; ++q) {
;       P.pq[q][0] = *(const uint2*)(prow + q * 512);
;       P.pq[q][1] = *(const uint2*)(prow + q * 512 + op);
;       P.pq[q][2] = *(const uint2*)(prow + q * 512 + on);
;     }
;     P.pwd = *(const uint2*)(Wd + tok * 512 + sc_);
;     P.pad_ = *(const uint2*)(Ad + tok * 512 + sc_);
;     const float* sc = w.bonus + (tok * 8 + hd) * 8;
;     P.psc[0] = sc[0]; P.psc[1] = sc[1 + 3 * dir]; P.psc[2] = sc[2 + 3 * dir];
;   };
;     ...
;   auto lds_step = [&](const float* bf, int j) {
;     RStep q;
;     q.a4 = *(const f4v*)(bf + 0 * 1024 + j * 64 + 4 * kg);
;     q.wr4 = *(const f4v*)(bf + 1 * 1024 + j * 64 + 4 * kg);
;     q.w4 = *(const f4v*)(bf + 2 * 1024 + j * 64 + 4 * kg);
;     q.b4 = *(const f4v*)(bf + 3 * 1024 + j * 64 + 4 * kg);
;     q.k4 = *(const f4v*)(bf + 4 * 1024 + j * 64 + 4 * kg);
;     q.vv = bf[5 * 1024 + j * 64 + row];
;     q.sc = *(const float2*)(bf + 6 * 1024 + j * 2);
;     return q;
;   };
;   auto flush = [&](int c) {
;     {
;       int j = tid >> 4, rr = tid & 15;
;       int ii = pos2i(c * 16 + j, dir);
;       yout[((size_t)b * TPB + ii) * 512 + hd * 64 + rq * 16 + rr] = f2bf(sY[(c & 1) * 256 + j * 16 + rr]);
;     }
;   };
	ds_write_b128 v103, v[52:55] offset:32896
	ds_write_b128 v103, v[48:51] offset:36992
	v_pk_add_f32 v[48:49], v[134:135], -1.0 op_sel_hi:[1,0]
	v_pk_add_f32 v[50:51], v[64:65], -1.0 op_sel_hi:[1,0]
	v_pk_fma_f32 v[48:49], v[16:17], v[48:49], 1.0 op_sel_hi:[1,1,0]
	v_pk_fma_f32 v[50:51], v[18:19], v[50:51], 1.0 op_sel_hi:[1,1,0]
	v_pk_mul_f32 v[48:49], v[48:49], v[136:137]
	v_pk_mul_f32 v[50:51], v[50:51], v[140:141]
	ds_write_b128 v103, v[48:51] offset:41088
	v_lshlrev_b32_e32 v51, 16, v40
	v_and_b32_e32 v53, s0, v40
	v_and_b32_e32 v52, 0xffff0000, v46
	v_pk_mov_b32 v[50:51], v[50:51], v[52:53] op_sel:[1,0]
	v_lshlrev_b32_e32 v48, 16, v46
	v_and_b32_e32 v49, 0xffff0000, v40
	v_pk_mul_f32 v[50:51], v[94:95], v[50:51] op_sel:[1,0] op_sel_hi:[0,1]
	v_pk_fma_f32 v[48:49], v[94:95], v[48:49], v[50:51]
	v_and_b32_e32 v51, 0xffff0000, v41
	v_lshlrev_b32_e32 v53, 16, v41
	v_and_b32_e32 v41, s0, v41
	v_and_b32_e32 v40, 0xffff0000, v47
	v_pk_mov_b32 v[40:41], v[52:53], v[40:41] op_sel:[1,0]
	v_lshlrev_b32_e32 v50, 16, v47
	v_pk_mul_f32 v[40:41], v[94:95], v[40:41] op_sel:[1,0] op_sel_hi:[0,1]
	v_lshlrev_b32_e32 v62, 16, v63
	v_and_b32_e32 v63, 0xffff0000, v63
	v_pk_fma_f32 v[40:41], v[94:95], v[50:51], v[40:41]
	v_pk_add_f32 v[48:49], v[48:49], v[130:131] neg_lo:[0,1] neg_hi:[0,1]
	v_pk_add_f32 v[40:41], v[40:41], v[62:63] neg_lo:[0,1] neg_hi:[0,1]
	v_pk_fma_f32 v[48:49], v[4:5], v[48:49], v[130:131]
	v_pk_fma_f32 v[50:51], v[6:7], v[40:41], v[62:63]
	ds_write_b128 v103, v[48:51] offset:45184
	s_and_saveexec_b64 s[4:5], s[40:41]
	s_cbranch_execz .LBB0_556
	s_waitcnt vmcnt(14)
	ds_write_b64 v104, v[44:45] offset:49280
.LBB0_556:
	s_or_b64 exec, exec, s[4:5]
	v_pk_mul_f32 v[28:29], v[28:29], v[102:103] op_sel_hi:[1,0]
	s_add_i32 s17, s17, 2
	v_pk_fma_f32 v[24:25], v[24:25], v[96:97], v[28:29] op_sel_hi:[1,0,1]
	s_min_u32 s4, s17, 0x20c
	v_pk_fma_f32 v[154:155], v[20:21], v[98:99], v[24:25]
	v_pk_mul_f32 v[20:21], v[30:31], v[102:103] op_sel_hi:[1,0]
	v_cndmask_b32_e64 v95, 0.5, 0, s[42:43]
	v_pk_fma_f32 v[20:21], v[26:27], v[96:97], v[20:21] op_sel_hi:[1,0,1]
	v_cndmask_b32_e64 v94, 0.5, 0, s[44:45]
	v_pk_fma_f32 v[168:169], v[22:23], v[100:101], v[20:21]
	v_lshl_add_u32 v20, s4, 4, v123
	v_cmp_lt_i32_e64 s[4:5], s37, v20
	s_waitcnt lgkmcnt(0)
	s_barrier
	s_waitcnt lgkmcnt(0)
	v_mov_b32_e32 v146, v20
	v_cndmask_b32_e64 v147, v231, v232, s[4:5]
	v_add_u32_e32 v142, 0x80, v106
	v_add_u32_e64 v143, s22, 0
	v_sub_u32_e32 v147, v147, v146
	ds_read2st64_b32 v[170:171], v142 offset0:176 offset1:177
	v_cndmask_b32_e32 v146, v147, v146, vcc
	ds_read2_b64 v[20:23], v143 offset0:16 offset1:17
	v_ashrrev_i32_e32 v147, 31, v146
	ds_read_b128 v[24:27], v105 offset:24704
	v_lshl_add_u64 v[148:149], s[12:13], 0, v[146:147]
	v_and_b32_e32 v147, 0xfffffeff, v146
	ds_read_b128 v[28:31], v105 offset:24960
	v_mad_u64_u32 v[150:151], s[4:5], v148, s20, v[42:43]
	v_cmp_eq_u32_e64 s[42:43], 0, v147
	ds_read_b128 v[98:101], v105 offset:28800
	v_mov_b32_e32 v152, v151
	v_cndmask_b32_e64 v147, -1, 0, s[42:43]
	ds_read_b128 v[126:129], v105 offset:29056
	v_mad_u64_u32 v[152:153], s[4:5], v149, s20, v[152:153]
	v_cmp_lt_i32_e64 s[4:5], s37, v125
	ds_read_b128 v[130:133], v105 offset:32896
	v_mov_b32_e32 v151, v152
	v_and_b32_e32 v152, 0xffffdfff, v146
	v_cndmask_b32_e64 v146, v236, 0, s[42:43]
	global_load_dwordx2 v[58:59], v[150:151], off
	global_load_dwordx2 v[60:61], v[150:151], off offset:1024
	global_load_dwordx2 v[62:63], v[150:151], off offset:2048
	v_lshl_add_u64 v[146:147], v[150:151], 0, v[146:147]
	v_cmp_eq_u32_e64 s[44:45], s37, v152
	ds_read_b128 v[134:137], v105 offset:33152
	global_load_dwordx2 v[48:49], v[146:147], off
	v_cndmask_b32_e64 v156, v237, 0, s[44:45]
	ds_read_b128 v[138:141], v105 offset:36992
	v_lshl_add_u64 v[152:153], v[150:151], 0, v[156:157]
	ds_read_b128 v[142:145], v105 offset:37248
	global_load_dwordx2 v[50:51], v[152:153], off
	global_load_dwordx2 v[52:53], v[146:147], off offset:1024
	global_load_dwordx2 v[40:41], v[146:147], off offset:2048
	global_load_dwordx2 v[54:55], v[152:153], off offset:1024
	global_load_dwordx2 v[46:47], v[152:153], off offset:2048
	v_lshlrev_b64 v[146:147], 10, v[148:149]
	v_lshl_add_u64 v[150:151], v[34:35], 0, v[146:147]
	v_lshl_add_u64 v[146:147], v[36:37], 0, v[146:147]
	global_load_dwordx2 v[66:67], v[150:151], off
	global_load_dwordx2 v[64:65], v[146:147], off
	v_lshlrev_b64 v[146:147], 8, v[148:149]
	v_lshl_add_u64 v[146:147], s[6:7], 0, v[146:147]
	s_waitcnt lgkmcnt(4)
	v_pk_mul_f32 v[26:27], v[168:169], v[26:27]
	global_load_dword v56, v[146:147], off
	v_lshl_add_u64 v[148:149], v[146:147], 0, s[90:91]
	ds_read_b32 v147, v83 offset:49408
	global_load_dwordx2 v[44:45], v[148:149], off offset:4
	v_cndmask_b32_e64 v146, v231, v232, s[4:5]
	v_pk_fma_f32 v[24:25], v[154:155], v[24:25], v[26:27]
	v_pk_mul_f32 v[26:27], v[168:169], v[100:101]
	v_add_u32_e32 v146, v146, v124
	v_add_f32_e32 v24, v24, v25
	v_pk_fma_f32 v[26:27], v[154:155], v[98:99], v[26:27]
	v_cndmask_b32_e32 v146, v146, v125, vcc
	v_add_f32_dpp v24, v24, v24 quad_perm:[1,0,3,2] row_mask:0xf bank_mask:0xf bound_ctrl:1
	v_add_f32_e32 v25, v26, v27
	s_waitcnt lgkmcnt(0)
; DI float row16_sum(float v) { v += dppf(v, 0); v += dppf(v, 1); v += dppf(v, 2); v += dppf(v, 3); return v; }
; DI void rwkv_scan(CP p, const Ptrs& w, int l, int item, float* sm) {
;     ...
;   auto flush = [&](int c) {
;     {
;       int j = tid >> 4, rr = tid & 15;
;       int ii = pos2i(c * 16 + j, dir);
;       yout[((size_t)b * TPB + ii) * 512 + hd * 64 + rq * 16 + rr] = f2bf(sY[(c & 1) * 256 + j * 16 + rr]);
;     }
;   };
;   __syncthreads();
;   load(0, PA);
;   stage(PA, sm);
;   load(1, PB);
;   __syncthreads();
;   const int NCH = TPB / 16;
;   auto run_chunk = [&](int c, const float* bf, float* sy) {
;     flush(max(c - 1, 0));
;     RStep cur = lds_step(bf, 0);
; #pragma unroll
;     for (int j = 0; j < 16; ++j) {
;       RStep nxt = cur;
;       if (j + 1 < 16) nxt = lds_step(bf, j + 1);
;       f2v sa2 = SA * cur.a4.xy + SB * cur.a4.zw;
;       f2v yp2 = SA * cur.wr4.xy + SB * cur.wr4.zw;
;       float sa = sa2.x + sa2.y, yp = yp2.x + yp2.y;
;       sa = row16_sum(sa); yp = row16_sum(yp);
;       float y = yp + sa * cur.sc.x + cur.vv * cur.sc.y;
;       SA = SA * cur.w4.xy + (sa * cur.b4.xy + cur.vv * cur.k4.xy);
;       SB = SB * cur.w4.zw + (sa * cur.b4.zw + cur.vv * cur.k4.zw);
;       sy[(kg == 0 ? j * 16 : 0) + ysel - (c & 1) * 0] = y;
;       cur = nxt;
;     }
	v_cvt_pk_bf16_f32 v148, v147, s0
	v_add_f32_dpp v24, v24, v24 quad_perm:[2,3,0,1] row_mask:0xf bank_mask:0xf bound_ctrl:1
	v_add_f32_dpp v25, v25, v25 quad_perm:[1,0,3,2] row_mask:0xf bank_mask:0xf bound_ctrl:1
	v_ashrrev_i32_e32 v147, 31, v146
	v_add_f32_dpp v24, v24, v24 row_half_mirror row_mask:0xf bank_mask:0xf bound_ctrl:1
	v_add_f32_dpp v25, v25, v25 quad_perm:[2,3,0,1] row_mask:0xf bank_mask:0xf bound_ctrl:1
	v_lshl_add_u64 v[146:147], s[12:13], 0, v[146:147]
	v_add_f32_dpp v24, v24, v24 row_mirror row_mask:0xf bank_mask:0xf bound_ctrl:1
	v_add_f32_dpp v25, v25, v25 row_half_mirror row_mask:0xf bank_mask:0xf bound_ctrl:1
	v_lshlrev_b64 v[146:147], 10, v[146:147]
	v_lshl_add_u64 v[146:147], v[38:39], 0, v[146:147]
	v_add_f32_dpp v26, v25, v25 row_mirror row_mask:0xf bank_mask:0xf bound_ctrl:1
	global_store_short v[146:147], v148, off
	ds_read_b128 v[146:149], v105 offset:41088
	v_fmac_f32_e32 v26, v20, v24
	ds_read_b128 v[150:153], v105 offset:41344
	v_fmac_f32_e32 v26, v170, v21
	v_pk_mul_f32 v[20:21], v[138:139], v[24:25] op_sel_hi:[1,0]
	v_pk_mul_f32 v[24:25], v[140:141], v[24:25] op_sel_hi:[1,0]
	ds_write_b32 v107, v26 offset:50432
	s_waitcnt lgkmcnt(2)
	v_pk_fma_f32 v[20:21], v[146:147], v[170:171], v[20:21] op_sel_hi:[1,0,1]
	v_pk_fma_f32 v[20:21], v[154:155], v[130:131], v[20:21]
	v_pk_fma_f32 v[24:25], v[148:149], v[170:171], v[24:25] op_sel_hi:[1,0,1]
	v_pk_fma_f32 v[154:155], v[168:169], v[132:133], v[24:25]
	ds_read_b128 v[24:27], v105 offset:33408
	ds_read_b128 v[98:101], v105 offset:37504
	ds_read_b128 v[130:133], v105 offset:25216
	ds_read_b128 v[138:141], v105 offset:41600
	ds_read_b128 v[146:149], v105 offset:29312
	v_pk_mul_f32 v[30:31], v[30:31], v[154:155]
	ds_read_b32 v96, v106 offset:45696
	v_pk_fma_f32 v[28:29], v[28:29], v[20:21], v[30:31]
	v_pk_mul_f32 v[30:31], v[128:129], v[154:155]
	ds_read_b64 v[168:169], v157 offset:49296
	v_pk_fma_f32 v[30:31], v[126:127], v[20:21], v[30:31]
	v_add_f32_e32 v28, v28, v29
	v_add_f32_e32 v29, v30, v31
	v_mov_b32_e32 v30, v171
	v_add_f32_dpp v28, v28, v28 quad_perm:[1,0,3,2] row_mask:0xf bank_mask:0xf bound_ctrl:1
	v_add_f32_dpp v29, v29, v29 quad_perm:[1,0,3,2] row_mask:0xf bank_mask:0xf bound_ctrl:1
	s_nop 0
	v_add_f32_dpp v28, v28, v28 quad_perm:[2,3,0,1] row_mask:0xf bank_mask:0xf bound_ctrl:1
	v_add_f32_dpp v29, v29, v29 quad_perm:[2,3,0,1] row_mask:0xf bank_mask:0xf bound_ctrl:1
	s_nop 0
	v_add_f32_dpp v28, v28, v28 row_half_mirror row_mask:0xf bank_mask:0xf bound_ctrl:1
	v_add_f32_dpp v29, v29, v29 row_half_mirror row_mask:0xf bank_mask:0xf bound_ctrl:1
	s_nop 0
	v_add_f32_dpp v28, v28, v28 row_mirror row_mask:0xf bank_mask:0xf bound_ctrl:1
	v_add_f32_dpp v29, v29, v29 row_mirror row_mask:0xf bank_mask:0xf bound_ctrl:1
	v_fmac_f32_e32 v29, v28, v22
	v_fmac_f32_e32 v29, v171, v23
	v_pk_mul_f32 v[22:23], v[142:143], v[28:29] op_sel_hi:[1,0]
	ds_write_b32 v108, v29 offset:50432
	s_waitcnt lgkmcnt(8)
	v_pk_fma_f32 v[22:23], v[150:151], v[30:31], v[22:23] op_sel_hi:[1,0,1]
	v_pk_fma_f32 v[150:151], v[134:135], v[20:21], v[22:23]
	v_pk_mul_f32 v[20:21], v[144:145], v[28:29] op_sel_hi:[1,0]
	v_pk_fma_f32 v[20:21], v[152:153], v[30:31], v[20:21] op_sel_hi:[1,0,1]
	v_pk_fma_f32 v[152:153], v[136:137], v[154:155], v[20:21]
	ds_read_b128 v[20:23], v105 offset:33664
	ds_read_b128 v[28:31], v105 offset:37760
	ds_read_b128 v[126:129], v105 offset:25472
	ds_read_b128 v[134:137], v105 offset:41856
	ds_read_b128 v[142:145], v105 offset:29568
	ds_read_b32 v102, v106 offset:45952
	ds_read_b64 v[154:155], v157 offset:49304
	s_waitcnt lgkmcnt(8)
	v_pk_mul_f32 v[132:133], v[132:133], v[152:153]
	v_pk_fma_f32 v[130:131], v[130:131], v[150:151], v[132:133]
	v_pk_mul_f32 v[132:133], v[148:149], v[152:153]
	v_add_f32_e32 v130, v130, v131
	v_pk_fma_f32 v[132:133], v[146:147], v[150:151], v[132:133]
	v_add_f32_e32 v131, v132, v133
	v_add_f32_dpp v130, v130, v130 quad_perm:[1,0,3,2] row_mask:0xf bank_mask:0xf bound_ctrl:1
	s_nop 0
	v_add_f32_dpp v131, v131, v131 quad_perm:[1,0,3,2] row_mask:0xf bank_mask:0xf bound_ctrl:1
	v_add_f32_dpp v130, v130, v130 quad_perm:[2,3,0,1] row_mask:0xf bank_mask:0xf bound_ctrl:1
	s_nop 0
	v_add_f32_dpp v131, v131, v131 quad_perm:[2,3,0,1] row_mask:0xf bank_mask:0xf bound_ctrl:1
	v_add_f32_dpp v130, v130, v130 row_half_mirror row_mask:0xf bank_mask:0xf bound_ctrl:1
	s_nop 0
	v_add_f32_dpp v131, v131, v131 row_half_mirror row_mask:0xf bank_mask:0xf bound_ctrl:1
	v_add_f32_dpp v130, v130, v130 row_mirror row_mask:0xf bank_mask:0xf bound_ctrl:1
	s_nop 0
	v_add_f32_dpp v131, v131, v131 row_mirror row_mask:0xf bank_mask:0xf bound_ctrl:1
	v_fmac_f32_e32 v131, v130, v168
	v_fmac_f32_e32 v131, v96, v169
	v_pk_mul_f32 v[98:99], v[98:99], v[130:131] op_sel_hi:[1,0]
	ds_write_b32 v109, v131 offset:50432
	v_pk_fma_f32 v[98:99], v[138:139], v[96:97], v[98:99] op_sel_hi:[1,0,1]
	v_pk_fma_f32 v[150:151], v[24:25], v[150:151], v[98:99]
	v_pk_mul_f32 v[24:25], v[100:101], v[130:131] op_sel_hi:[1,0]
	v_pk_fma_f32 v[24:25], v[140:141], v[96:97], v[24:25] op_sel_hi:[1,0,1]
	v_pk_fma_f32 v[152:153], v[26:27], v[152:153], v[24:25]
	ds_read_b128 v[24:27], v105 offset:33920
	ds_read_b128 v[98:101], v105 offset:38016
	ds_read_b128 v[130:133], v105 offset:25728
	ds_read_b128 v[138:141], v105 offset:42112
	ds_read_b128 v[146:149], v105 offset:29824
	ds_read_b32 v96, v106 offset:46208
	s_waitcnt lgkmcnt(7)
; DI float row16_sum(float v) { v += dppf(v, 0); v += dppf(v, 1); v += dppf(v, 2); v += dppf(v, 3); return v; }
; DI void rwkv_scan(CP p, const Ptrs& w, int l, int item, float* sm) {
;     ...
;   auto lds_step = [&](const float* bf, int j) {
;     RStep q;
;     q.a4 = *(const f4v*)(bf + 0 * 1024 + j * 64 + 4 * kg);
;     q.wr4 = *(const f4v*)(bf + 1 * 1024 + j * 64 + 4 * kg);
;     q.w4 = *(const f4v*)(bf + 2 * 1024 + j * 64 + 4 * kg);
;     q.b4 = *(const f4v*)(bf + 3 * 1024 + j * 64 + 4 * kg);
;     q.k4 = *(const f4v*)(bf + 4 * 1024 + j * 64 + 4 * kg);
;     q.vv = bf[5 * 1024 + j * 64 + row];
;     q.sc = *(const float2*)(bf + 6 * 1024 + j * 2);
;     return q;
;   };
;     ...
; #pragma unroll
;     for (int j = 0; j < 16; ++j) {
;       RStep nxt = cur;
;       if (j + 1 < 16) nxt = lds_step(bf, j + 1);
;       f2v sa2 = SA * cur.a4.xy + SB * cur.a4.zw;
;       f2v yp2 = SA * cur.wr4.xy + SB * cur.wr4.zw;
;       float sa = sa2.x + sa2.y, yp = yp2.x + yp2.y;
;       sa = row16_sum(sa); yp = row16_sum(yp);
;       float y = yp + sa * cur.sc.x + cur.vv * cur.sc.y;
;       SA = SA * cur.w4.xy + (sa * cur.b4.xy + cur.vv * cur.k4.xy);
;       SB = SB * cur.w4.zw + (sa * cur.b4.zw + cur.vv * cur.k4.zw);
;       sy[(kg == 0 ? j * 16 : 0) + ysel - (c & 1) * 0] = y;
;       cur = nxt;
;     }
	v_pk_mul_f32 v[128:129], v[128:129], v[152:153]
	ds_read_b64 v[168:169], v157 offset:49312
	v_pk_fma_f32 v[126:127], v[126:127], v[150:151], v[128:129]
	v_pk_mul_f32 v[128:129], v[144:145], v[152:153]
	v_add_f32_e32 v126, v126, v127
	v_pk_fma_f32 v[128:129], v[142:143], v[150:151], v[128:129]
	v_add_f32_e32 v127, v128, v129
	v_add_f32_dpp v126, v126, v126 quad_perm:[1,0,3,2] row_mask:0xf bank_mask:0xf bound_ctrl:1
	s_nop 0
	v_add_f32_dpp v127, v127, v127 quad_perm:[1,0,3,2] row_mask:0xf bank_mask:0xf bound_ctrl:1
	v_add_f32_dpp v126, v126, v126 quad_perm:[2,3,0,1] row_mask:0xf bank_mask:0xf bound_ctrl:1
	s_nop 0
	v_add_f32_dpp v127, v127, v127 quad_perm:[2,3,0,1] row_mask:0xf bank_mask:0xf bound_ctrl:1
	v_add_f32_dpp v126, v126, v126 row_half_mirror row_mask:0xf bank_mask:0xf bound_ctrl:1
	s_nop 0
	v_add_f32_dpp v127, v127, v127 row_half_mirror row_mask:0xf bank_mask:0xf bound_ctrl:1
	v_add_f32_dpp v126, v126, v126 row_mirror row_mask:0xf bank_mask:0xf bound_ctrl:1
	s_nop 0
	v_add_f32_dpp v127, v127, v127 row_mirror row_mask:0xf bank_mask:0xf bound_ctrl:1
	v_fmac_f32_e32 v127, v126, v154
	v_fmac_f32_e32 v127, v102, v155
	v_pk_mul_f32 v[28:29], v[28:29], v[126:127] op_sel_hi:[1,0]
	ds_write_b32 v110, v127 offset:50432
	v_pk_fma_f32 v[28:29], v[134:135], v[102:103], v[28:29] op_sel_hi:[1,0,1]
	v_pk_fma_f32 v[150:151], v[20:21], v[150:151], v[28:29]
	v_pk_mul_f32 v[20:21], v[30:31], v[126:127] op_sel_hi:[1,0]
	v_pk_fma_f32 v[20:21], v[136:137], v[102:103], v[20:21] op_sel_hi:[1,0,1]
	v_pk_fma_f32 v[152:153], v[22:23], v[152:153], v[20:21]
	ds_read_b128 v[20:23], v105 offset:34176
	ds_read_b128 v[28:31], v105 offset:38272
	ds_read_b128 v[126:129], v105 offset:25984
	ds_read_b128 v[134:137], v105 offset:42368
	ds_read_b128 v[142:145], v105 offset:30080
	ds_read_b32 v102, v106 offset:46464
	s_waitcnt lgkmcnt(14)
	ds_read_b64 v[154:155], v157 offset:49320
	s_waitcnt lgkmcnt(8)
	v_pk_mul_f32 v[132:133], v[132:133], v[152:153]
	v_pk_fma_f32 v[130:131], v[130:131], v[150:151], v[132:133]
	v_pk_mul_f32 v[132:133], v[148:149], v[152:153]
	v_add_f32_e32 v130, v130, v131
	v_pk_fma_f32 v[132:133], v[146:147], v[150:151], v[132:133]
	v_add_f32_e32 v131, v132, v133
	v_add_f32_dpp v130, v130, v130 quad_perm:[1,0,3,2] row_mask:0xf bank_mask:0xf bound_ctrl:1
	s_nop 0
	v_add_f32_dpp v131, v131, v131 quad_perm:[1,0,3,2] row_mask:0xf bank_mask:0xf bound_ctrl:1
	v_add_f32_dpp v130, v130, v130 quad_perm:[2,3,0,1] row_mask:0xf bank_mask:0xf bound_ctrl:1
	s_nop 0
	v_add_f32_dpp v131, v131, v131 quad_perm:[2,3,0,1] row_mask:0xf bank_mask:0xf bound_ctrl:1
	v_add_f32_dpp v130, v130, v130 row_half_mirror row_mask:0xf bank_mask:0xf bound_ctrl:1
	s_nop 0
	v_add_f32_dpp v131, v131, v131 row_half_mirror row_mask:0xf bank_mask:0xf bound_ctrl:1
	v_add_f32_dpp v130, v130, v130 row_mirror row_mask:0xf bank_mask:0xf bound_ctrl:1
	s_nop 0
	v_add_f32_dpp v131, v131, v131 row_mirror row_mask:0xf bank_mask:0xf bound_ctrl:1
	v_fmac_f32_e32 v131, v130, v168
	v_fmac_f32_e32 v131, v96, v169
	v_pk_mul_f32 v[98:99], v[98:99], v[130:131] op_sel_hi:[1,0]
	ds_write_b32 v111, v131 offset:50432
	v_pk_fma_f32 v[98:99], v[138:139], v[96:97], v[98:99] op_sel_hi:[1,0,1]
	v_pk_fma_f32 v[150:151], v[24:25], v[150:151], v[98:99]
	v_pk_mul_f32 v[24:25], v[100:101], v[130:131] op_sel_hi:[1,0]
	v_pk_fma_f32 v[24:25], v[140:141], v[96:97], v[24:25] op_sel_hi:[1,0,1]
	v_pk_fma_f32 v[152:153], v[26:27], v[152:153], v[24:25]
	ds_read_b128 v[24:27], v105 offset:34432
	ds_read_b128 v[98:101], v105 offset:38528
	ds_read_b128 v[130:133], v105 offset:26240
	ds_read_b128 v[138:141], v105 offset:42624
	ds_read_b128 v[146:149], v105 offset:30336
	ds_read_b32 v96, v106 offset:46720
	s_waitcnt lgkmcnt(7)
	v_pk_mul_f32 v[128:129], v[128:129], v[152:153]
	ds_read_b64 v[168:169], v157 offset:49328
	v_pk_fma_f32 v[126:127], v[126:127], v[150:151], v[128:129]
	v_pk_mul_f32 v[128:129], v[144:145], v[152:153]
	v_add_f32_e32 v126, v126, v127
	v_pk_fma_f32 v[128:129], v[142:143], v[150:151], v[128:129]
	v_add_f32_e32 v127, v128, v129
	v_add_f32_dpp v126, v126, v126 quad_perm:[1,0,3,2] row_mask:0xf bank_mask:0xf bound_ctrl:1
	s_nop 0
	v_add_f32_dpp v127, v127, v127 quad_perm:[1,0,3,2] row_mask:0xf bank_mask:0xf bound_ctrl:1
	v_add_f32_dpp v126, v126, v126 quad_perm:[2,3,0,1] row_mask:0xf bank_mask:0xf bound_ctrl:1
	s_nop 0
	v_add_f32_dpp v127, v127, v127 quad_perm:[2,3,0,1] row_mask:0xf bank_mask:0xf bound_ctrl:1
	v_add_f32_dpp v126, v126, v126 row_half_mirror row_mask:0xf bank_mask:0xf bound_ctrl:1
	s_nop 0
	v_add_f32_dpp v127, v127, v127 row_half_mirror row_mask:0xf bank_mask:0xf bound_ctrl:1
	v_add_f32_dpp v126, v126, v126 row_mirror row_mask:0xf bank_mask:0xf bound_ctrl:1
	s_nop 0
	v_add_f32_dpp v127, v127, v127 row_mirror row_mask:0xf bank_mask:0xf bound_ctrl:1
	v_fmac_f32_e32 v127, v126, v154
	v_fmac_f32_e32 v127, v102, v155
	v_pk_mul_f32 v[28:29], v[28:29], v[126:127] op_sel_hi:[1,0]
	ds_write_b32 v112, v127 offset:50432
	v_pk_fma_f32 v[28:29], v[134:135], v[102:103], v[28:29] op_sel_hi:[1,0,1]
	v_pk_fma_f32 v[150:151], v[20:21], v[150:151], v[28:29]
	v_pk_mul_f32 v[20:21], v[30:31], v[126:127] op_sel_hi:[1,0]
	v_pk_fma_f32 v[20:21], v[136:137], v[102:103], v[20:21] op_sel_hi:[1,0,1]
	v_pk_fma_f32 v[152:153], v[22:23], v[152:153], v[20:21]
	ds_read_b128 v[20:23], v105 offset:34688
	ds_read_b128 v[28:31], v105 offset:38784
	ds_read_b128 v[126:129], v105 offset:26496
	ds_read_b128 v[134:137], v105 offset:42880
	ds_read_b128 v[142:145], v105 offset:30592
	ds_read_b32 v102, v106 offset:46976
	s_waitcnt lgkmcnt(14)
	ds_read_b64 v[154:155], v157 offset:49336
	s_waitcnt lgkmcnt(8)
; DI float row16_sum(float v) { v += dppf(v, 0); v += dppf(v, 1); v += dppf(v, 2); v += dppf(v, 3); return v; }
; DI void rwkv_scan(CP p, const Ptrs& w, int l, int item, float* sm) {
;     ...
;   auto lds_step = [&](const float* bf, int j) {
;     RStep q;
;     q.a4 = *(const f4v*)(bf + 0 * 1024 + j * 64 + 4 * kg);
;     q.wr4 = *(const f4v*)(bf + 1 * 1024 + j * 64 + 4 * kg);
;     q.w4 = *(const f4v*)(bf + 2 * 1024 + j * 64 + 4 * kg);
;     q.b4 = *(const f4v*)(bf + 3 * 1024 + j * 64 + 4 * kg);
;     q.k4 = *(const f4v*)(bf + 4 * 1024 + j * 64 + 4 * kg);
;     q.vv = bf[5 * 1024 + j * 64 + row];
;     q.sc = *(const float2*)(bf + 6 * 1024 + j * 2);
;     return q;
;   };
;     ...
; #pragma unroll
;     for (int j = 0; j < 16; ++j) {
;       RStep nxt = cur;
;       if (j + 1 < 16) nxt = lds_step(bf, j + 1);
;       f2v sa2 = SA * cur.a4.xy + SB * cur.a4.zw;
;       f2v yp2 = SA * cur.wr4.xy + SB * cur.wr4.zw;
;       float sa = sa2.x + sa2.y, yp = yp2.x + yp2.y;
;       sa = row16_sum(sa); yp = row16_sum(yp);
;       float y = yp + sa * cur.sc.x + cur.vv * cur.sc.y;
;       SA = SA * cur.w4.xy + (sa * cur.b4.xy + cur.vv * cur.k4.xy);
;       SB = SB * cur.w4.zw + (sa * cur.b4.zw + cur.vv * cur.k4.zw);
;       sy[(kg == 0 ? j * 16 : 0) + ysel - (c & 1) * 0] = y;
;       cur = nxt;
;     }
	v_pk_mul_f32 v[132:133], v[132:133], v[152:153]
	v_pk_fma_f32 v[130:131], v[130:131], v[150:151], v[132:133]
	v_pk_mul_f32 v[132:133], v[148:149], v[152:153]
	v_add_f32_e32 v130, v130, v131
	v_pk_fma_f32 v[132:133], v[146:147], v[150:151], v[132:133]
	v_add_f32_e32 v131, v132, v133
	v_add_f32_dpp v130, v130, v130 quad_perm:[1,0,3,2] row_mask:0xf bank_mask:0xf bound_ctrl:1
	s_nop 0
	v_add_f32_dpp v131, v131, v131 quad_perm:[1,0,3,2] row_mask:0xf bank_mask:0xf bound_ctrl:1
	v_add_f32_dpp v130, v130, v130 quad_perm:[2,3,0,1] row_mask:0xf bank_mask:0xf bound_ctrl:1
	s_nop 0
	v_add_f32_dpp v131, v131, v131 quad_perm:[2,3,0,1] row_mask:0xf bank_mask:0xf bound_ctrl:1
	v_add_f32_dpp v130, v130, v130 row_half_mirror row_mask:0xf bank_mask:0xf bound_ctrl:1
	s_nop 0
	v_add_f32_dpp v131, v131, v131 row_half_mirror row_mask:0xf bank_mask:0xf bound_ctrl:1
	v_add_f32_dpp v130, v130, v130 row_mirror row_mask:0xf bank_mask:0xf bound_ctrl:1
	s_nop 0
	v_add_f32_dpp v131, v131, v131 row_mirror row_mask:0xf bank_mask:0xf bound_ctrl:1
	v_fmac_f32_e32 v131, v130, v168
	v_fmac_f32_e32 v131, v96, v169
	v_pk_mul_f32 v[98:99], v[98:99], v[130:131] op_sel_hi:[1,0]
	ds_write_b32 v113, v131 offset:50432
	v_pk_fma_f32 v[98:99], v[138:139], v[96:97], v[98:99] op_sel_hi:[1,0,1]
	v_pk_fma_f32 v[150:151], v[24:25], v[150:151], v[98:99]
	v_pk_mul_f32 v[24:25], v[100:101], v[130:131] op_sel_hi:[1,0]
	v_pk_fma_f32 v[24:25], v[140:141], v[96:97], v[24:25] op_sel_hi:[1,0,1]
	v_pk_fma_f32 v[152:153], v[26:27], v[152:153], v[24:25]
	ds_read_b128 v[24:27], v105 offset:34944
	ds_read_b128 v[98:101], v105 offset:39040
	ds_read_b128 v[130:133], v105 offset:26752
	ds_read_b128 v[138:141], v105 offset:43136
	ds_read_b128 v[146:149], v105 offset:30848
	ds_read_b32 v96, v106 offset:47232
	s_waitcnt lgkmcnt(7)
	v_pk_mul_f32 v[128:129], v[128:129], v[152:153]
	ds_read_b64 v[168:169], v157 offset:49344
	v_pk_fma_f32 v[126:127], v[126:127], v[150:151], v[128:129]
	v_pk_mul_f32 v[128:129], v[144:145], v[152:153]
	v_add_f32_e32 v126, v126, v127
	v_pk_fma_f32 v[128:129], v[142:143], v[150:151], v[128:129]
	v_add_f32_e32 v127, v128, v129
	v_add_f32_dpp v126, v126, v126 quad_perm:[1,0,3,2] row_mask:0xf bank_mask:0xf bound_ctrl:1
	s_nop 0
	v_add_f32_dpp v127, v127, v127 quad_perm:[1,0,3,2] row_mask:0xf bank_mask:0xf bound_ctrl:1
	v_add_f32_dpp v126, v126, v126 quad_perm:[2,3,0,1] row_mask:0xf bank_mask:0xf bound_ctrl:1
	s_nop 0
	v_add_f32_dpp v127, v127, v127 quad_perm:[2,3,0,1] row_mask:0xf bank_mask:0xf bound_ctrl:1
	v_add_f32_dpp v126, v126, v126 row_half_mirror row_mask:0xf bank_mask:0xf bound_ctrl:1
	s_nop 0
	v_add_f32_dpp v127, v127, v127 row_half_mirror row_mask:0xf bank_mask:0xf bound_ctrl:1
	v_add_f32_dpp v126, v126, v126 row_mirror row_mask:0xf bank_mask:0xf bound_ctrl:1
	s_nop 0
	v_add_f32_dpp v127, v127, v127 row_mirror row_mask:0xf bank_mask:0xf bound_ctrl:1
	v_fmac_f32_e32 v127, v126, v154
	v_fmac_f32_e32 v127, v102, v155
	v_pk_mul_f32 v[28:29], v[28:29], v[126:127] op_sel_hi:[1,0]
	ds_write_b32 v114, v127 offset:50432
	v_pk_fma_f32 v[28:29], v[134:135], v[102:103], v[28:29] op_sel_hi:[1,0,1]
	v_pk_fma_f32 v[150:151], v[20:21], v[150:151], v[28:29]
	v_pk_mul_f32 v[20:21], v[30:31], v[126:127] op_sel_hi:[1,0]
	v_pk_fma_f32 v[20:21], v[136:137], v[102:103], v[20:21] op_sel_hi:[1,0,1]
	v_pk_fma_f32 v[152:153], v[22:23], v[152:153], v[20:21]
	ds_read_b128 v[20:23], v105 offset:35200
	ds_read_b128 v[28:31], v105 offset:39296
	ds_read_b128 v[126:129], v105 offset:27008
	ds_read_b128 v[134:137], v105 offset:43392
	ds_read_b128 v[142:145], v105 offset:31104
	ds_read_b32 v102, v106 offset:47488
	s_waitcnt lgkmcnt(14)
	ds_read_b64 v[154:155], v157 offset:49352
	s_waitcnt lgkmcnt(8)
	v_pk_mul_f32 v[132:133], v[132:133], v[152:153]
	v_pk_fma_f32 v[130:131], v[130:131], v[150:151], v[132:133]
	v_pk_mul_f32 v[132:133], v[148:149], v[152:153]
	v_add_f32_e32 v130, v130, v131
	v_pk_fma_f32 v[132:133], v[146:147], v[150:151], v[132:133]
	v_add_f32_e32 v131, v132, v133
	v_add_f32_dpp v130, v130, v130 quad_perm:[1,0,3,2] row_mask:0xf bank_mask:0xf bound_ctrl:1
	s_nop 0
	v_add_f32_dpp v131, v131, v131 quad_perm:[1,0,3,2] row_mask:0xf bank_mask:0xf bound_ctrl:1
	v_add_f32_dpp v130, v130, v130 quad_perm:[2,3,0,1] row_mask:0xf bank_mask:0xf bound_ctrl:1
	s_nop 0
	v_add_f32_dpp v131, v131, v131 quad_perm:[2,3,0,1] row_mask:0xf bank_mask:0xf bound_ctrl:1
	v_add_f32_dpp v130, v130, v130 row_half_mirror row_mask:0xf bank_mask:0xf bound_ctrl:1
	s_nop 0
	v_add_f32_dpp v131, v131, v131 row_half_mirror row_mask:0xf bank_mask:0xf bound_ctrl:1
	v_add_f32_dpp v130, v130, v130 row_mirror row_mask:0xf bank_mask:0xf bound_ctrl:1
	s_nop 0
	v_add_f32_dpp v131, v131, v131 row_mirror row_mask:0xf bank_mask:0xf bound_ctrl:1
	v_fmac_f32_e32 v131, v130, v168
	v_fmac_f32_e32 v131, v96, v169
	v_pk_mul_f32 v[98:99], v[98:99], v[130:131] op_sel_hi:[1,0]
	ds_write_b32 v115, v131 offset:50432
	v_pk_fma_f32 v[98:99], v[138:139], v[96:97], v[98:99] op_sel_hi:[1,0,1]
	v_pk_fma_f32 v[150:151], v[24:25], v[150:151], v[98:99]
	v_pk_mul_f32 v[24:25], v[100:101], v[130:131] op_sel_hi:[1,0]
	v_pk_fma_f32 v[24:25], v[140:141], v[96:97], v[24:25] op_sel_hi:[1,0,1]
	v_pk_fma_f32 v[152:153], v[26:27], v[152:153], v[24:25]
	ds_read_b128 v[24:27], v105 offset:35456
	ds_read_b128 v[98:101], v105 offset:39552
	ds_read_b128 v[130:133], v105 offset:27264
	ds_read_b128 v[138:141], v105 offset:43648
	ds_read_b128 v[146:149], v105 offset:31360
	ds_read_b32 v96, v106 offset:47744
	s_waitcnt lgkmcnt(7)
; DI float row16_sum(float v) { v += dppf(v, 0); v += dppf(v, 1); v += dppf(v, 2); v += dppf(v, 3); return v; }
; DI void rwkv_scan(CP p, const Ptrs& w, int l, int item, float* sm) {
;     ...
;   auto lds_step = [&](const float* bf, int j) {
;     RStep q;
;     q.a4 = *(const f4v*)(bf + 0 * 1024 + j * 64 + 4 * kg);
;     q.wr4 = *(const f4v*)(bf + 1 * 1024 + j * 64 + 4 * kg);
;     q.w4 = *(const f4v*)(bf + 2 * 1024 + j * 64 + 4 * kg);
;     q.b4 = *(const f4v*)(bf + 3 * 1024 + j * 64 + 4 * kg);
;     q.k4 = *(const f4v*)(bf + 4 * 1024 + j * 64 + 4 * kg);
;     q.vv = bf[5 * 1024 + j * 64 + row];
;     q.sc = *(const float2*)(bf + 6 * 1024 + j * 2);
;     return q;
;   };
;     ...
; #pragma unroll
;     for (int j = 0; j < 16; ++j) {
;       RStep nxt = cur;
;       if (j + 1 < 16) nxt = lds_step(bf, j + 1);
;       f2v sa2 = SA * cur.a4.xy + SB * cur.a4.zw;
;       f2v yp2 = SA * cur.wr4.xy + SB * cur.wr4.zw;
;       float sa = sa2.x + sa2.y, yp = yp2.x + yp2.y;
;       sa = row16_sum(sa); yp = row16_sum(yp);
;       float y = yp + sa * cur.sc.x + cur.vv * cur.sc.y;
;       SA = SA * cur.w4.xy + (sa * cur.b4.xy + cur.vv * cur.k4.xy);
;       SB = SB * cur.w4.zw + (sa * cur.b4.zw + cur.vv * cur.k4.zw);
;       sy[(kg == 0 ? j * 16 : 0) + ysel - (c & 1) * 0] = y;
;       cur = nxt;
;     }
	v_pk_mul_f32 v[128:129], v[128:129], v[152:153]
	ds_read_b64 v[168:169], v157 offset:49360
	v_pk_fma_f32 v[126:127], v[126:127], v[150:151], v[128:129]
	v_pk_mul_f32 v[128:129], v[144:145], v[152:153]
	v_add_f32_e32 v126, v126, v127
	v_pk_fma_f32 v[128:129], v[142:143], v[150:151], v[128:129]
	v_add_f32_e32 v127, v128, v129
	v_add_f32_dpp v126, v126, v126 quad_perm:[1,0,3,2] row_mask:0xf bank_mask:0xf bound_ctrl:1
	s_nop 0
	v_add_f32_dpp v127, v127, v127 quad_perm:[1,0,3,2] row_mask:0xf bank_mask:0xf bound_ctrl:1
	v_add_f32_dpp v126, v126, v126 quad_perm:[2,3,0,1] row_mask:0xf bank_mask:0xf bound_ctrl:1
	s_nop 0
	v_add_f32_dpp v127, v127, v127 quad_perm:[2,3,0,1] row_mask:0xf bank_mask:0xf bound_ctrl:1
	v_add_f32_dpp v126, v126, v126 row_half_mirror row_mask:0xf bank_mask:0xf bound_ctrl:1
	s_nop 0
	v_add_f32_dpp v127, v127, v127 row_half_mirror row_mask:0xf bank_mask:0xf bound_ctrl:1
	v_add_f32_dpp v126, v126, v126 row_mirror row_mask:0xf bank_mask:0xf bound_ctrl:1
	s_nop 0
	v_add_f32_dpp v127, v127, v127 row_mirror row_mask:0xf bank_mask:0xf bound_ctrl:1
	v_fmac_f32_e32 v127, v126, v154
	v_fmac_f32_e32 v127, v102, v155
	v_pk_mul_f32 v[28:29], v[28:29], v[126:127] op_sel_hi:[1,0]
	ds_write_b32 v116, v127 offset:50432
	v_pk_fma_f32 v[28:29], v[134:135], v[102:103], v[28:29] op_sel_hi:[1,0,1]
	v_pk_fma_f32 v[150:151], v[20:21], v[150:151], v[28:29]
	v_pk_mul_f32 v[20:21], v[30:31], v[126:127] op_sel_hi:[1,0]
	v_pk_fma_f32 v[20:21], v[136:137], v[102:103], v[20:21] op_sel_hi:[1,0,1]
	v_pk_fma_f32 v[152:153], v[22:23], v[152:153], v[20:21]
	ds_read_b128 v[20:23], v105 offset:35712
	ds_read_b128 v[28:31], v105 offset:39808
	ds_read_b128 v[126:129], v105 offset:27520
	ds_read_b128 v[134:137], v105 offset:43904
	ds_read_b128 v[142:145], v105 offset:31616
	ds_read_b32 v102, v106 offset:48000
	s_waitcnt lgkmcnt(14)
	ds_read_b64 v[154:155], v157 offset:49368
	s_waitcnt lgkmcnt(8)
	v_pk_mul_f32 v[132:133], v[132:133], v[152:153]
	v_pk_fma_f32 v[130:131], v[130:131], v[150:151], v[132:133]
	v_pk_mul_f32 v[132:133], v[148:149], v[152:153]
	v_add_f32_e32 v130, v130, v131
	v_pk_fma_f32 v[132:133], v[146:147], v[150:151], v[132:133]
	v_add_f32_e32 v131, v132, v133
	v_add_f32_dpp v130, v130, v130 quad_perm:[1,0,3,2] row_mask:0xf bank_mask:0xf bound_ctrl:1
	s_nop 0
	v_add_f32_dpp v131, v131, v131 quad_perm:[1,0,3,2] row_mask:0xf bank_mask:0xf bound_ctrl:1
	v_add_f32_dpp v130, v130, v130 quad_perm:[2,3,0,1] row_mask:0xf bank_mask:0xf bound_ctrl:1
	s_nop 0
	v_add_f32_dpp v131, v131, v131 quad_perm:[2,3,0,1] row_mask:0xf bank_mask:0xf bound_ctrl:1
	v_add_f32_dpp v130, v130, v130 row_half_mirror row_mask:0xf bank_mask:0xf bound_ctrl:1
	s_nop 0
	v_add_f32_dpp v131, v131, v131 row_half_mirror row_mask:0xf bank_mask:0xf bound_ctrl:1
	v_add_f32_dpp v130, v130, v130 row_mirror row_mask:0xf bank_mask:0xf bound_ctrl:1
	s_nop 0
	v_add_f32_dpp v131, v131, v131 row_mirror row_mask:0xf bank_mask:0xf bound_ctrl:1
	v_fmac_f32_e32 v131, v130, v168
	v_fmac_f32_e32 v131, v96, v169
	v_pk_mul_f32 v[98:99], v[98:99], v[130:131] op_sel_hi:[1,0]
	ds_write_b32 v117, v131 offset:50432
	v_pk_fma_f32 v[98:99], v[138:139], v[96:97], v[98:99] op_sel_hi:[1,0,1]
	v_pk_fma_f32 v[150:151], v[24:25], v[150:151], v[98:99]
	v_pk_mul_f32 v[24:25], v[100:101], v[130:131] op_sel_hi:[1,0]
	v_pk_fma_f32 v[24:25], v[140:141], v[96:97], v[24:25] op_sel_hi:[1,0,1]
	v_pk_fma_f32 v[152:153], v[26:27], v[152:153], v[24:25]
	ds_read_b128 v[24:27], v105 offset:35968
	ds_read_b128 v[98:101], v105 offset:40064
	ds_read_b128 v[130:133], v105 offset:27776
	ds_read_b128 v[138:141], v105 offset:44160
	ds_read_b128 v[146:149], v105 offset:31872
	ds_read_b32 v96, v106 offset:48256
	s_waitcnt lgkmcnt(7)
	v_pk_mul_f32 v[128:129], v[128:129], v[152:153]
	ds_read_b64 v[168:169], v157 offset:49376
	v_pk_fma_f32 v[126:127], v[126:127], v[150:151], v[128:129]
	v_pk_mul_f32 v[128:129], v[144:145], v[152:153]
	v_add_f32_e32 v126, v126, v127
	v_pk_fma_f32 v[128:129], v[142:143], v[150:151], v[128:129]
	v_add_f32_e32 v127, v128, v129
	v_add_f32_dpp v126, v126, v126 quad_perm:[1,0,3,2] row_mask:0xf bank_mask:0xf bound_ctrl:1
	s_nop 0
	v_add_f32_dpp v127, v127, v127 quad_perm:[1,0,3,2] row_mask:0xf bank_mask:0xf bound_ctrl:1
	v_add_f32_dpp v126, v126, v126 quad_perm:[2,3,0,1] row_mask:0xf bank_mask:0xf bound_ctrl:1
	s_nop 0
	v_add_f32_dpp v127, v127, v127 quad_perm:[2,3,0,1] row_mask:0xf bank_mask:0xf bound_ctrl:1
	v_add_f32_dpp v126, v126, v126 row_half_mirror row_mask:0xf bank_mask:0xf bound_ctrl:1
	s_nop 0
	v_add_f32_dpp v127, v127, v127 row_half_mirror row_mask:0xf bank_mask:0xf bound_ctrl:1
	v_add_f32_dpp v126, v126, v126 row_mirror row_mask:0xf bank_mask:0xf bound_ctrl:1
	s_nop 0
	v_add_f32_dpp v127, v127, v127 row_mirror row_mask:0xf bank_mask:0xf bound_ctrl:1
	v_fmac_f32_e32 v127, v126, v154
	v_fmac_f32_e32 v127, v102, v155
	v_pk_mul_f32 v[28:29], v[28:29], v[126:127] op_sel_hi:[1,0]
	ds_write_b32 v118, v127 offset:50432
	v_pk_fma_f32 v[28:29], v[134:135], v[102:103], v[28:29] op_sel_hi:[1,0,1]
	v_pk_fma_f32 v[150:151], v[20:21], v[150:151], v[28:29]
	v_pk_mul_f32 v[20:21], v[30:31], v[126:127] op_sel_hi:[1,0]
	v_pk_fma_f32 v[20:21], v[136:137], v[102:103], v[20:21] op_sel_hi:[1,0,1]
	v_pk_fma_f32 v[152:153], v[22:23], v[152:153], v[20:21]
	ds_read_b128 v[20:23], v105 offset:36224
	ds_read_b128 v[28:31], v105 offset:40320
	ds_read_b128 v[126:129], v105 offset:28032
	ds_read_b128 v[134:137], v105 offset:44416
	ds_read_b128 v[142:145], v105 offset:32128
	ds_read_b32 v102, v106 offset:48512
	s_waitcnt lgkmcnt(14)
	ds_read_b64 v[154:155], v157 offset:49384
	s_waitcnt lgkmcnt(8)
; DI float row16_sum(float v) { v += dppf(v, 0); v += dppf(v, 1); v += dppf(v, 2); v += dppf(v, 3); return v; }
; DI void rwkv_scan(CP p, const Ptrs& w, int l, int item, float* sm) {
;     ...
;   auto lds_step = [&](const float* bf, int j) {
;     RStep q;
;     q.a4 = *(const f4v*)(bf + 0 * 1024 + j * 64 + 4 * kg);
;     q.wr4 = *(const f4v*)(bf + 1 * 1024 + j * 64 + 4 * kg);
;     q.w4 = *(const f4v*)(bf + 2 * 1024 + j * 64 + 4 * kg);
;     q.b4 = *(const f4v*)(bf + 3 * 1024 + j * 64 + 4 * kg);
;     q.k4 = *(const f4v*)(bf + 4 * 1024 + j * 64 + 4 * kg);
;     q.vv = bf[5 * 1024 + j * 64 + row];
;     q.sc = *(const float2*)(bf + 6 * 1024 + j * 2);
;     return q;
;   };
;     ...
; #pragma unroll
;     for (int j = 0; j < 16; ++j) {
;       RStep nxt = cur;
;       if (j + 1 < 16) nxt = lds_step(bf, j + 1);
;       f2v sa2 = SA * cur.a4.xy + SB * cur.a4.zw;
;       f2v yp2 = SA * cur.wr4.xy + SB * cur.wr4.zw;
;       float sa = sa2.x + sa2.y, yp = yp2.x + yp2.y;
;       sa = row16_sum(sa); yp = row16_sum(yp);
;       float y = yp + sa * cur.sc.x + cur.vv * cur.sc.y;
;       SA = SA * cur.w4.xy + (sa * cur.b4.xy + cur.vv * cur.k4.xy);
;       SB = SB * cur.w4.zw + (sa * cur.b4.zw + cur.vv * cur.k4.zw);
;       sy[(kg == 0 ? j * 16 : 0) + ysel - (c & 1) * 0] = y;
;       cur = nxt;
;     }
	v_pk_mul_f32 v[132:133], v[132:133], v[152:153]
	v_pk_fma_f32 v[130:131], v[130:131], v[150:151], v[132:133]
	v_pk_mul_f32 v[132:133], v[148:149], v[152:153]
	v_add_f32_e32 v130, v130, v131
	v_pk_fma_f32 v[132:133], v[146:147], v[150:151], v[132:133]
	v_add_f32_e32 v131, v132, v133
	v_add_f32_dpp v130, v130, v130 quad_perm:[1,0,3,2] row_mask:0xf bank_mask:0xf bound_ctrl:1
	s_nop 0
	v_add_f32_dpp v131, v131, v131 quad_perm:[1,0,3,2] row_mask:0xf bank_mask:0xf bound_ctrl:1
	v_add_f32_dpp v130, v130, v130 quad_perm:[2,3,0,1] row_mask:0xf bank_mask:0xf bound_ctrl:1
	s_nop 0
	v_add_f32_dpp v131, v131, v131 quad_perm:[2,3,0,1] row_mask:0xf bank_mask:0xf bound_ctrl:1
	v_add_f32_dpp v130, v130, v130 row_half_mirror row_mask:0xf bank_mask:0xf bound_ctrl:1
	s_nop 0
	v_add_f32_dpp v131, v131, v131 row_half_mirror row_mask:0xf bank_mask:0xf bound_ctrl:1
	v_add_f32_dpp v130, v130, v130 row_mirror row_mask:0xf bank_mask:0xf bound_ctrl:1
	s_nop 0
	v_add_f32_dpp v131, v131, v131 row_mirror row_mask:0xf bank_mask:0xf bound_ctrl:1
	v_fmac_f32_e32 v131, v130, v168
	v_fmac_f32_e32 v131, v96, v169
	v_pk_mul_f32 v[98:99], v[98:99], v[130:131] op_sel_hi:[1,0]
	ds_write_b32 v119, v131 offset:50432
	v_pk_fma_f32 v[98:99], v[138:139], v[96:97], v[98:99] op_sel_hi:[1,0,1]
	v_pk_fma_f32 v[24:25], v[24:25], v[150:151], v[98:99]
	v_pk_mul_f32 v[98:99], v[100:101], v[130:131] op_sel_hi:[1,0]
	v_pk_fma_f32 v[98:99], v[140:141], v[96:97], v[98:99] op_sel_hi:[1,0,1]
	v_pk_fma_f32 v[26:27], v[26:27], v[152:153], v[98:99]
	ds_read_b128 v[98:101], v105 offset:36480
	ds_read_b128 v[130:133], v105 offset:40576
	ds_read_b128 v[138:141], v105 offset:28288
	ds_read_b128 v[146:149], v105 offset:44672
	ds_read_b128 v[150:153], v105 offset:32384
	ds_read_b32 v156, v106 offset:48768
	s_waitcnt lgkmcnt(7)
	v_pk_mul_f32 v[128:129], v[128:129], v[26:27]
	ds_read_b64 v[168:169], v157 offset:49392
	v_pk_fma_f32 v[126:127], v[126:127], v[24:25], v[128:129]
	v_pk_mul_f32 v[128:129], v[144:145], v[26:27]
	v_add_f32_e32 v96, v126, v127
	v_pk_fma_f32 v[128:129], v[142:143], v[24:25], v[128:129]
	v_add_f32_e32 v126, v128, v129
	v_add_f32_dpp v96, v96, v96 quad_perm:[1,0,3,2] row_mask:0xf bank_mask:0xf bound_ctrl:1
	s_nop 0
	v_add_f32_dpp v126, v126, v126 quad_perm:[1,0,3,2] row_mask:0xf bank_mask:0xf bound_ctrl:1
	v_add_f32_dpp v96, v96, v96 quad_perm:[2,3,0,1] row_mask:0xf bank_mask:0xf bound_ctrl:1
	s_nop 0
	v_add_f32_dpp v126, v126, v126 quad_perm:[2,3,0,1] row_mask:0xf bank_mask:0xf bound_ctrl:1
	v_add_f32_dpp v96, v96, v96 row_half_mirror row_mask:0xf bank_mask:0xf bound_ctrl:1
	s_nop 0
	v_add_f32_dpp v126, v126, v126 row_half_mirror row_mask:0xf bank_mask:0xf bound_ctrl:1
	v_add_f32_dpp v96, v96, v96 row_mirror row_mask:0xf bank_mask:0xf bound_ctrl:1
	v_pk_mul_f32 v[28:29], v[28:29], v[96:97] op_sel_hi:[1,0]
	v_add_f32_dpp v126, v126, v126 row_mirror row_mask:0xf bank_mask:0xf bound_ctrl:1
	v_pk_fma_f32 v[28:29], v[134:135], v[102:103], v[28:29] op_sel_hi:[1,0,1]
	v_fmac_f32_e32 v126, v96, v154
	v_pk_fma_f32 v[142:143], v[20:21], v[24:25], v[28:29]
	v_pk_mul_f32 v[20:21], v[30:31], v[96:97] op_sel_hi:[1,0]
	v_fmac_f32_e32 v126, v102, v155
	v_pk_fma_f32 v[20:21], v[136:137], v[102:103], v[20:21] op_sel_hi:[1,0,1]
	ds_write_b32 v120, v126 offset:50432
	v_pk_fma_f32 v[144:145], v[22:23], v[26:27], v[20:21]
	ds_read_b128 v[20:23], v105 offset:36736
	ds_read_b128 v[28:31], v105 offset:40832
	ds_read_b128 v[126:129], v105 offset:28544
	ds_read_b128 v[24:27], v105 offset:44928
	ds_read_b128 v[134:137], v105 offset:32640
	ds_read_b32 v96, v106 offset:49024
	s_waitcnt lgkmcnt(14)
	ds_read_b64 v[154:155], v157 offset:49400
	s_waitcnt lgkmcnt(8)
	v_pk_mul_f32 v[140:141], v[140:141], v[144:145]
	v_pk_fma_f32 v[138:139], v[138:139], v[142:143], v[140:141]
	v_pk_mul_f32 v[140:141], v[152:153], v[144:145]
	v_add_f32_e32 v102, v138, v139
	v_pk_fma_f32 v[140:141], v[150:151], v[142:143], v[140:141]
	v_add_f32_e32 v138, v140, v141
	v_add_f32_dpp v102, v102, v102 quad_perm:[1,0,3,2] row_mask:0xf bank_mask:0xf bound_ctrl:1
	s_waitcnt vmcnt(20)
	v_and_b32_e32 v139, 0xffff0000, v80
	v_add_f32_dpp v102, v102, v102 quad_perm:[2,3,0,1] row_mask:0xf bank_mask:0xf bound_ctrl:1
	v_add_f32_dpp v138, v138, v138 quad_perm:[1,0,3,2] row_mask:0xf bank_mask:0xf bound_ctrl:1
	v_and_b32_e32 v141, 0xffff0000, v79
	v_add_f32_dpp v102, v102, v102 row_half_mirror row_mask:0xf bank_mask:0xf bound_ctrl:1
	v_add_f32_dpp v138, v138, v138 quad_perm:[2,3,0,1] row_mask:0xf bank_mask:0xf bound_ctrl:1
	v_lshlrev_b32_e32 v140, 16, v81
	v_add_f32_dpp v102, v102, v102 row_mirror row_mask:0xf bank_mask:0xf bound_ctrl:1
	v_pk_mul_f32 v[130:131], v[130:131], v[102:103] op_sel_hi:[1,0]
	v_add_f32_dpp v138, v138, v138 row_half_mirror row_mask:0xf bank_mask:0xf bound_ctrl:1
	s_waitcnt lgkmcnt(9)
	v_pk_fma_f32 v[130:131], v[146:147], v[156:157], v[130:131] op_sel_hi:[1,0,1]
	s_nop 0
	v_pk_fma_f32 v[98:99], v[98:99], v[142:143], v[130:131]
	v_pk_mul_f32 v[130:131], v[132:133], v[102:103] op_sel_hi:[1,0]
	v_add_f32_dpp v138, v138, v138 row_mirror row_mask:0xf bank_mask:0xf bound_ctrl:1
	v_pk_fma_f32 v[130:131], v[148:149], v[156:157], v[130:131] op_sel_hi:[1,0,1]
	s_waitcnt lgkmcnt(8)
	v_fmac_f32_e32 v138, v102, v168
	v_pk_fma_f32 v[100:101], v[100:101], v[144:145], v[130:131]
	v_fmac_f32_e32 v138, v156, v169
	s_waitcnt lgkmcnt(4)
	v_pk_mul_f32 v[128:129], v[128:129], v[100:101]
	ds_write_b32 v121, v138 offset:50432
	v_pk_fma_f32 v[126:127], v[126:127], v[98:99], v[128:129]
	s_waitcnt lgkmcnt(3)
; DI float row16_sum(float v) { v += dppf(v, 0); v += dppf(v, 1); v += dppf(v, 2); v += dppf(v, 3); return v; }
; DI void rwkv_scan(CP p, const Ptrs& w, int l, int item, float* sm) {
;     ...
;   auto stage = [&](const RPre& P, float* bufp) {
;     float rc[4], rp[4], rn[4], kc[4], kp[4], kn[4], vc[4], vp[4], vn[4], wd4[4], ad4[4];
;     up4(P.pq[0][0], rc); up4(P.pq[0][1], rp); up4(P.pq[0][2], rn);
;     up4(P.pq[1][0], kc); up4(P.pq[1][1], kp); up4(P.pq[1][2], kn);
;     up4(P.pq[2][0], vc); up4(P.pq[2][1], vp); up4(P.pq[2][2], vn);
;     up4(P.pwd, wd4); up4(P.pad_, ad4);
;     float o0[4], o1[4], o2[4], o3[4], o4[4], o5[4];
; #pragma unroll
;     for (int j = 0; j < 4; ++j) {
;       float r_s = rc[j] + ((P.pmk[0] * rp[j] + P.pmk[1] * rn[j]) - rc[j]) * mu_r[j];
;       float k_s = kc[j] + ((P.pmk[0] * kp[j] + P.pmk[1] * kn[j]) - kc[j]) * mu_k[j];
;       float v_s = vc[j] + ((P.pmk[0] * vp[j] + P.pmk[1] * vn[j]) - vc[j]) * mu_v[j];
;       float kk = k_s * kk_c[j] * P.psc[0];
;       float a = ad4[j], wv = 1.f - wd4[j];
;       o0[j] = -kk; o1[j] = wv * r_s; o2[j] = wv; o3[j] = kk * a; o4[j] = k_s * (1.f + (a - 1.f) * ka_c[j]); o5[j] = v_s;
;     }
;     float* d = bufp + sj * 64 + skq;
;     *(float4*)(d + 0 * 1024) = make_float4(o0[0], o0[1], o0[2], o0[3]);
;     *(float4*)(d + 1 * 1024) = make_float4(o1[0], o1[1], o1[2], o1[3]);
;     *(float4*)(d + 2 * 1024) = make_float4(o2[0], o2[1], o2[2], o2[3]);
;     *(float4*)(d + 3 * 1024) = make_float4(o3[0], o3[1], o3[2], o3[3]);
;     *(float4*)(d + 4 * 1024) = make_float4(o4[0], o4[1], o4[2], o4[3]);
;     *(float4*)(d + 5 * 1024) = make_float4(o5[0], o5[1], o5[2], o5[3]);
;     if (skq == 0) *(float2*)(bufp + 6 * 1024 + sj * 2) = make_float2(P.psc[1], P.psc[2]);
;     ...
;       f2v sa2 = SA * cur.a4.xy + SB * cur.a4.zw;
;       f2v yp2 = SA * cur.wr4.xy + SB * cur.wr4.zw;
;       float sa = sa2.x + sa2.y, yp = yp2.x + yp2.y;
;       sa = row16_sum(sa); yp = row16_sum(yp);
;       float y = yp + sa * cur.sc.x + cur.vv * cur.sc.y;
;       SA = SA * cur.w4.xy + (sa * cur.b4.xy + cur.vv * cur.k4.xy);
;       SB = SB * cur.w4.zw + (sa * cur.b4.zw + cur.vv * cur.k4.zw);
;       sy[(kg == 0 ? j * 16 : 0) + ysel - (c & 1) * 0] = y;
;       cur = nxt;
;     }
	v_pk_mul_f32 v[128:129], v[136:137], v[100:101]
	v_lshlrev_b32_e32 v132, 16, v85
	v_pk_fma_f32 v[128:129], v[134:135], v[98:99], v[128:129]
	v_and_b32_e32 v133, 0xffff0000, v85
	v_and_b32_e32 v85, 0xffff0000, v78
	v_lshlrev_b32_e32 v138, 16, v78
	v_lshlrev_b32_e32 v78, 16, v79
	v_and_b32_e32 v79, 0xffff0000, v81
	v_add_f32_e32 v102, v126, v127
	v_add_f32_e32 v126, v128, v129
	v_lshlrev_b32_e32 v130, 16, v84
	v_and_b32_e32 v131, 0xffff0000, v84
	v_lshlrev_b32_e32 v84, 16, v80
	v_pk_mul_f32 v[138:139], v[94:95], v[138:139] op_sel:[1,0] op_sel_hi:[0,1]
	v_pk_mul_f32 v[78:79], v[94:95], v[78:79] op_sel:[1,0] op_sel_hi:[0,1]
	v_add_f32_dpp v102, v102, v102 quad_perm:[1,0,3,2] row_mask:0xf bank_mask:0xf bound_ctrl:1
	v_add_f32_dpp v126, v126, v126 quad_perm:[1,0,3,2] row_mask:0xf bank_mask:0xf bound_ctrl:1
	v_lshlrev_b32_e32 v128, 16, v86
	v_and_b32_e32 v129, 0xffff0000, v86
	v_lshlrev_b32_e32 v86, 16, v87
	v_and_b32_e32 v87, 0xffff0000, v87
	v_pk_fma_f32 v[84:85], v[94:95], v[84:85], v[138:139]
	v_pk_fma_f32 v[78:79], v[94:95], v[140:141], v[78:79]
	v_add_f32_dpp v102, v102, v102 quad_perm:[2,3,0,1] row_mask:0xf bank_mask:0xf bound_ctrl:1
	v_add_f32_dpp v126, v126, v126 quad_perm:[2,3,0,1] row_mask:0xf bank_mask:0xf bound_ctrl:1
	v_pk_add_f32 v[84:85], v[84:85], v[128:129] neg_lo:[0,1] neg_hi:[0,1]
	v_pk_add_f32 v[78:79], v[78:79], v[86:87] neg_lo:[0,1] neg_hi:[0,1]
	v_add_f32_dpp v102, v102, v102 row_half_mirror row_mask:0xf bank_mask:0xf bound_ctrl:1
	v_add_f32_dpp v126, v126, v126 row_half_mirror row_mask:0xf bank_mask:0xf bound_ctrl:1
	v_pk_fma_f32 v[128:129], v[8:9], v[84:85], v[128:129]
	v_pk_fma_f32 v[140:141], v[10:11], v[78:79], v[86:87]
	v_add_f32_dpp v102, v102, v102 row_mirror row_mask:0xf bank_mask:0xf bound_ctrl:1
	v_add_f32_dpp v126, v126, v126 row_mirror row_mask:0xf bank_mask:0xf bound_ctrl:1
	v_pk_mul_f32 v[84:85], v[12:13], v[128:129]
	v_pk_mul_f32 v[78:79], v[14:15], v[140:141]
	s_waitcnt lgkmcnt(1)
	v_fmac_f32_e32 v126, v102, v154
	s_waitcnt vmcnt(16)
	v_pk_mul_f32 v[138:139], v[82:83], v[84:85] op_sel_hi:[0,1]
	v_pk_mul_f32 v[142:143], v[82:83], v[78:79] op_sel_hi:[0,1]
	v_fmac_f32_e32 v126, v96, v155
	v_xor_b32_e32 v85, 0x80000000, v139
	v_xor_b32_e32 v84, 0x80000000, v138
	v_xor_b32_e32 v87, 0x80000000, v143
	v_xor_b32_e32 v86, 0x80000000, v142
	ds_write_b32 v122, v126 offset:50432
	ds_write_b128 v103, v[84:87]
	v_lshlrev_b32_e32 v84, 16, v74
	v_and_b32_e32 v85, 0xffff0000, v76
	v_lshlrev_b32_e32 v80, 16, v76
	v_and_b32_e32 v81, 0xffff0000, v74
	v_pk_mul_f32 v[84:85], v[94:95], v[84:85] op_sel:[1,0] op_sel_hi:[0,1]
	v_lshlrev_b32_e32 v126, 16, v88
	v_and_b32_e32 v127, 0xffff0000, v88
	v_pk_fma_f32 v[80:81], v[94:95], v[80:81], v[84:85]
	v_lshlrev_b32_e32 v134, 16, v92
	v_and_b32_e32 v135, 0xffff0000, v92
	v_pk_add_f32 v[80:81], v[80:81], v[126:127] neg_lo:[0,1] neg_hi:[0,1]
	v_lshlrev_b32_e32 v92, 16, v93
	v_and_b32_e32 v93, 0xffff0000, v93
	v_pk_add_f32 v[78:79], v[134:135], 1.0 op_sel_hi:[1,0] neg_lo:[1,0] neg_hi:[1,0]
	v_pk_fma_f32 v[80:81], v[0:1], v[80:81], v[126:127]
	v_and_b32_e32 v87, 0xffff0000, v75
	v_pk_mul_f32 v[84:85], v[80:81], v[78:79]
	v_pk_add_f32 v[80:81], v[92:93], 1.0 op_sel_hi:[1,0] neg_lo:[1,0] neg_hi:[1,0]
	v_lshlrev_b32_e32 v93, 16, v75
	v_and_b32_e32 v75, s0, v75
	v_and_b32_e32 v74, 0xffff0000, v77
	v_pk_mov_b32 v[74:75], v[92:93], v[74:75] op_sel:[1,0]
	v_lshlrev_b32_e32 v86, 16, v77
	v_pk_mul_f32 v[74:75], v[94:95], v[74:75] op_sel:[1,0] op_sel_hi:[0,1]
	v_lshlrev_b32_e32 v88, 16, v89
	v_and_b32_e32 v89, 0xffff0000, v89
	v_pk_fma_f32 v[74:75], v[94:95], v[86:87], v[74:75]
	v_lshlrev_b32_e32 v136, 16, v90
	v_pk_add_f32 v[74:75], v[74:75], v[88:89] neg_lo:[0,1] neg_hi:[0,1]
	v_and_b32_e32 v137, 0xffff0000, v90
	v_lshlrev_b32_e32 v90, 16, v91
	v_and_b32_e32 v91, 0xffff0000, v91
	v_pk_fma_f32 v[74:75], v[2:3], v[74:75], v[88:89]
	v_pk_mul_f32 v[76:77], v[142:143], v[90:91]
	v_pk_mul_f32 v[86:87], v[74:75], v[80:81]
	v_pk_mul_f32 v[74:75], v[138:139], v[136:137]
	ds_write_b128 v103, v[84:87] offset:4096
	ds_write_b128 v103, v[78:81] offset:8192
	ds_write_b128 v103, v[74:77] offset:12288
	v_pk_add_f32 v[74:75], v[136:137], -1.0 op_sel_hi:[1,0]
	v_pk_add_f32 v[76:77], v[90:91], -1.0 op_sel_hi:[1,0]
	v_pk_fma_f32 v[74:75], v[16:17], v[74:75], 1.0 op_sel_hi:[1,1,0]
	v_pk_fma_f32 v[76:77], v[18:19], v[76:77], 1.0 op_sel_hi:[1,1,0]
	v_pk_mul_f32 v[74:75], v[128:129], v[74:75]
	v_pk_mul_f32 v[76:77], v[140:141], v[76:77]
	ds_write_b128 v103, v[74:77] offset:16384
	v_lshlrev_b32_e32 v76, 16, v70
	v_and_b32_e32 v77, 0xffff0000, v72
	v_lshlrev_b32_e32 v74, 16, v72
	v_and_b32_e32 v75, 0xffff0000, v70
	v_pk_mul_f32 v[76:77], v[94:95], v[76:77] op_sel:[1,0] op_sel_hi:[0,1]
	v_pk_fma_f32 v[74:75], v[94:95], v[74:75], v[76:77]
	v_and_b32_e32 v77, 0xffff0000, v71
	v_lshlrev_b32_e32 v79, 16, v71
	v_and_b32_e32 v71, s0, v71
	v_and_b32_e32 v70, 0xffff0000, v73
	v_pk_mov_b32 v[70:71], v[78:79], v[70:71] op_sel:[1,0]
	v_lshlrev_b32_e32 v76, 16, v73
	v_pk_mul_f32 v[70:71], v[94:95], v[70:71] op_sel:[1,0] op_sel_hi:[0,1]
	v_pk_fma_f32 v[70:71], v[94:95], v[76:77], v[70:71]
	v_pk_add_f32 v[74:75], v[74:75], v[130:131] neg_lo:[0,1] neg_hi:[0,1]
	v_pk_add_f32 v[70:71], v[70:71], v[132:133] neg_lo:[0,1] neg_hi:[0,1]
	v_pk_fma_f32 v[74:75], v[4:5], v[74:75], v[130:131]
	v_pk_fma_f32 v[76:77], v[6:7], v[70:71], v[132:133]
	ds_write_b128 v103, v[74:77] offset:20480
	s_and_saveexec_b64 s[4:5], s[40:41]
	s_cbranch_execz .LBB0_553
	s_waitcnt vmcnt(15)
	ds_write_b64 v104, v[68:69] offset:24576
	s_branch .LBB0_553

; __global__ void __launch_bounds__(256, 2) fwd_kernel(Params p) {
;   __shared__ __attribute__((aligned(16))) char smem_raw[SMEM_BYTES];
	.amdhsa_kernel _Z10fwd_kernel6Params
		.amdhsa_group_segment_fixed_size 73764
		.amdhsa_private_segment_fixed_size 0
		.amdhsa_kernarg_size 576
		.amdhsa_user_sgpr_count 2
		.amdhsa_user_sgpr_dispatch_ptr 0
		.amdhsa_user_sgpr_queue_ptr 0
		.amdhsa_user_sgpr_kernarg_segment_ptr 1
		.amdhsa_user_sgpr_dispatch_id 0
		.amdhsa_user_sgpr_kernarg_preload_length 0
		.amdhsa_user_sgpr_kernarg_preload_offset 0
		.amdhsa_user_sgpr_private_segment_size 0
		.amdhsa_uses_dynamic_stack 0
		.amdhsa_enable_private_segment 0
		.amdhsa_system_sgpr_workgroup_id_x 1
		.amdhsa_system_sgpr_workgroup_id_y 0
		.amdhsa_system_sgpr_workgroup_id_z 0
		.amdhsa_system_sgpr_workgroup_info 0
		.amdhsa_system_vgpr_workitem_id 2
		.amdhsa_next_free_vgpr 256
		.amdhsa_next_free_sgpr 102
		.amdhsa_accum_offset 256
		.amdhsa_reserve_vcc 1
		.amdhsa_float_round_mode_32 0
		.amdhsa_float_round_mode_16_64 0
		.amdhsa_float_denorm_mode_32 3
		.amdhsa_float_denorm_mode_16_64 3
		.amdhsa_dx10_clamp 1
		.amdhsa_ieee_mode 1
		.amdhsa_fp16_overflow 0
		.amdhsa_tg_split 0
		.amdhsa_exception_fp_ieee_invalid_op 0
		.amdhsa_exception_fp_denorm_src 0
		.amdhsa_exception_fp_ieee_div_zero 0
		.amdhsa_exception_fp_ieee_overflow 0
		.amdhsa_exception_fp_ieee_underflow 0
		.amdhsa_exception_fp_ieee_inexact 0
		.amdhsa_exception_int_div_zero 0
	.end_amdhsa_kernel

; __global__ void __launch_bounds__(256, 2) fwd_kernel(Params p) {
;   __shared__ __attribute__((aligned(16))) char smem_raw[SMEM_BYTES];
amdhsa.kernels:
  - .agpr_count:     0
    .args:
      - .offset:         0
        .size:           320
        .value_kind:     by_value
      - .offset:         320
        .size:           4
        .value_kind:     hidden_block_count_x
      - .offset:         324
        .size:           4
        .value_kind:     hidden_block_count_y
      - .offset:         328
        .size:           4
        .value_kind:     hidden_block_count_z
      - .offset:         332
        .size:           2
        .value_kind:     hidden_group_size_x
      - .offset:         334
        .size:           2
        .value_kind:     hidden_group_size_y
      - .offset:         336
        .size:           2
        .value_kind:     hidden_group_size_z
      - .offset:         338
        .size:           2
        .value_kind:     hidden_remainder_x
      - .offset:         340
        .size:           2
        .value_kind:     hidden_remainder_y
      - .offset:         342
        .size:           2
        .value_kind:     hidden_remainder_z
      - .offset:         360
        .size:           8
        .value_kind:     hidden_global_offset_x
      - .offset:         368
        .size:           8
        .value_kind:     hidden_global_offset_y
      - .offset:         376
        .size:           8
        .value_kind:     hidden_global_offset_z
      - .offset:         384
        .size:           2
        .value_kind:     hidden_grid_dims
      - .offset:         408
        .size:           8
        .value_kind:     hidden_multigrid_sync_arg
    .group_segment_fixed_size: 73764
    .kernarg_segment_align: 8
    .kernarg_segment_size: 576
    .language:       OpenCL C
    .language_version:
      - 2
      - 0
    .max_flat_workgroup_size: 256
    .name:           _Z10fwd_kernel6Params
    .private_segment_fixed_size: 0
    .sgpr_count:     108
    .sgpr_spill_count: 189
    .symbol:         _Z10fwd_kernel6Params.kd
    .uniform_work_group_size: 1
    .uses_dynamic_stack: false
    .vgpr_count:     256
    .vgpr_spill_count: 0
    .wavefront_size: 64
